# counted lgkmcnt waits inside MFMA bursts of all five GEMM K-loops (replaces full lgkmcnt(0) drain before each burst)
# baseline (speedup 1.0000x reference)
.LBB0_181:
	ds_read_b128 v[144:147], v157
	ds_read_b128 v[148:151], v157 offset:1024
	ds_read_b128 v[162:165], v157 offset:2048
	ds_read_b128 v[166:169], v157 offset:3072
	s_add_u32 s30, s28, 0xfff80080
	s_addc_u32 s31, s29, -1
	s_cmp_eq_u32 s54, 28
	s_cselect_b32 s35, s2, s31
	s_cselect_b32 s34, s3, s30
	s_cselect_b32 s31, s7, s27
	s_cselect_b32 s30, s9, s11
	s_add_i32 m0, s39, 0xc000
	ds_read_b128 v[170:173], v158
	ds_read_b128 v[174:177], v158 offset:1024
	ds_read_b128 v[178:181], v158 offset:2048
	ds_read_b128 v[186:189], v158 offset:3072
	ds_read_b128 v[194:197], v158 offset:4096
	ds_read_b128 v[198:201], v158 offset:5120
	ds_read_b128 v[202:205], v158 offset:6144
	ds_read_b128 v[206:209], v158 offset:7168
	global_load_lds_dwordx4 v136, s[28:29]
	s_add_i32 m0, s39, 0xe000
	s_nop 0
	global_load_lds_dwordx4 v138, s[28:29]
	s_waitcnt lgkmcnt(8)
	s_barrier
	s_setprio 1
	s_waitcnt lgkmcnt(7)
	v_mfma_f32_16x16x32_bf16 v[124:127], v[144:147], v[170:173], v[124:127]
	v_mfma_f32_16x16x32_bf16 v[120:123], v[162:165], v[170:173], v[120:123]
	s_waitcnt lgkmcnt(5)
	v_mfma_f32_16x16x32_bf16 v[108:111], v[144:147], v[178:181], v[108:111]
	v_mfma_f32_16x16x32_bf16 v[104:107], v[162:165], v[178:181], v[104:107]
	s_waitcnt lgkmcnt(3)
	v_mfma_f32_16x16x32_bf16 v[92:95], v[144:147], v[194:197], v[92:95]
	v_mfma_f32_16x16x32_bf16 v[88:91], v[162:165], v[194:197], v[88:91]
	s_waitcnt lgkmcnt(1)
	v_mfma_f32_16x16x32_bf16 v[76:79], v[144:147], v[202:205], v[76:79]
	v_mfma_f32_16x16x32_bf16 v[72:75], v[162:165], v[202:205], v[72:75]
	v_mfma_f32_16x16x32_bf16 v[124:127], v[148:151], v[174:177], v[124:127]
	v_mfma_f32_16x16x32_bf16 v[120:123], v[166:169], v[174:177], v[120:123]
	v_mfma_f32_16x16x32_bf16 v[108:111], v[148:151], v[186:189], v[108:111]
	v_mfma_f32_16x16x32_bf16 v[104:107], v[166:169], v[186:189], v[104:107]
	v_mfma_f32_16x16x32_bf16 v[92:95], v[148:151], v[198:201], v[92:95]
	v_mfma_f32_16x16x32_bf16 v[88:91], v[166:169], v[198:201], v[88:91]
	s_waitcnt lgkmcnt(0)
	v_mfma_f32_16x16x32_bf16 v[76:79], v[148:151], v[206:209], v[76:79]
	v_mfma_f32_16x16x32_bf16 v[72:75], v[166:169], v[206:209], v[72:75]
	s_setprio 0
	s_barrier
	s_add_i32 s55, s48, s38
	s_add_u32 s58, s30, s0
	s_addc_u32 s59, s31, s1
	s_mov_b32 m0, s55
	ds_read_b128 v[210:213], v159
	ds_read_b128 v[214:217], v159 offset:1024
	ds_read_b128 v[218:221], v159 offset:2048
	ds_read_b128 v[222:225], v159 offset:3072
	global_load_lds_dwordx4 v130, s[30:31]
	s_add_i32 m0, s55, 0x2000
	s_nop 0
	global_load_lds_dwordx4 v134, s[30:31]
	s_barrier
	s_setprio 1
	s_waitcnt lgkmcnt(3)
	v_mfma_f32_16x16x32_bf16 v[116:119], v[210:213], v[170:173], v[116:119]
	s_waitcnt lgkmcnt(1)
	v_mfma_f32_16x16x32_bf16 v[112:115], v[218:221], v[170:173], v[112:115]
	v_mfma_f32_16x16x32_bf16 v[100:103], v[210:213], v[178:181], v[100:103]
	v_mfma_f32_16x16x32_bf16 v[96:99], v[218:221], v[178:181], v[96:99]
	v_mfma_f32_16x16x32_bf16 v[84:87], v[210:213], v[194:197], v[84:87]
	v_mfma_f32_16x16x32_bf16 v[80:83], v[218:221], v[194:197], v[80:83]
	v_mfma_f32_16x16x32_bf16 v[68:71], v[210:213], v[202:205], v[68:71]
	v_mfma_f32_16x16x32_bf16 v[64:67], v[218:221], v[202:205], v[64:67]
	v_mfma_f32_16x16x32_bf16 v[116:119], v[214:217], v[174:177], v[116:119]
	s_waitcnt lgkmcnt(0)
	v_mfma_f32_16x16x32_bf16 v[112:115], v[222:225], v[174:177], v[112:115]
	v_mfma_f32_16x16x32_bf16 v[100:103], v[214:217], v[186:189], v[100:103]
	v_mfma_f32_16x16x32_bf16 v[96:99], v[222:225], v[186:189], v[96:99]
	v_mfma_f32_16x16x32_bf16 v[84:87], v[214:217], v[198:201], v[84:87]
	v_mfma_f32_16x16x32_bf16 v[80:83], v[222:225], v[198:201], v[80:83]
	v_mfma_f32_16x16x32_bf16 v[68:71], v[214:217], v[206:209], v[68:71]
	v_mfma_f32_16x16x32_bf16 v[64:67], v[222:225], v[206:209], v[64:67]
	s_setprio 0
	s_mov_b32 m0, s39
	s_add_u32 s60, s34, s0
	s_addc_u32 s61, s35, s1
	s_barrier
	ds_read_b128 v[170:173], v158 offset:16384
	ds_read_b128 v[174:177], v158 offset:17408
	ds_read_b128 v[178:181], v158 offset:18432
	ds_read_b128 v[186:189], v158 offset:19456
	ds_read_b128 v[194:197], v158 offset:20480
	ds_read_b128 v[198:201], v158 offset:21504
	ds_read_b128 v[202:205], v158 offset:22528
	ds_read_b128 v[206:209], v158 offset:23552
	global_load_lds_dwordx4 v128, s[34:35]
	s_mov_b32 m0, s40
	s_nop 0
	global_load_lds_dwordx4 v132, s[34:35]
	s_barrier
	s_setprio 1
	s_waitcnt lgkmcnt(7)
	v_mfma_f32_16x16x32_bf16 v[60:63], v[144:147], v[170:173], v[60:63]
	v_mfma_f32_16x16x32_bf16 v[56:59], v[162:165], v[170:173], v[56:59]
	s_waitcnt lgkmcnt(5)
	v_mfma_f32_16x16x32_bf16 v[44:47], v[144:147], v[178:181], v[44:47]
	v_mfma_f32_16x16x32_bf16 v[40:43], v[162:165], v[178:181], v[40:43]
	s_waitcnt lgkmcnt(3)
	v_mfma_f32_16x16x32_bf16 v[28:31], v[144:147], v[194:197], v[28:31]
	v_mfma_f32_16x16x32_bf16 v[24:27], v[162:165], v[194:197], v[24:27]
	s_waitcnt lgkmcnt(1)
	v_mfma_f32_16x16x32_bf16 v[12:15], v[144:147], v[202:205], v[12:15]
	v_mfma_f32_16x16x32_bf16 v[8:11], v[162:165], v[202:205], v[8:11]
	v_mfma_f32_16x16x32_bf16 v[60:63], v[148:151], v[174:177], v[60:63]
	v_mfma_f32_16x16x32_bf16 v[56:59], v[166:169], v[174:177], v[56:59]
	v_mfma_f32_16x16x32_bf16 v[44:47], v[148:151], v[186:189], v[44:47]
	v_mfma_f32_16x16x32_bf16 v[40:43], v[166:169], v[186:189], v[40:43]
	v_mfma_f32_16x16x32_bf16 v[28:31], v[148:151], v[198:201], v[28:31]
	v_mfma_f32_16x16x32_bf16 v[24:27], v[166:169], v[198:201], v[24:27]
	s_waitcnt lgkmcnt(0)
	v_mfma_f32_16x16x32_bf16 v[12:15], v[148:151], v[206:209], v[12:15]
	v_mfma_f32_16x16x32_bf16 v[8:11], v[166:169], v[206:209], v[8:11]
	s_setprio 0
	s_barrier
	s_add_u32 s56, s30, 0x80000
	s_addc_u32 s57, s31, 0
	s_add_i32 s55, s49, s38
	s_mov_b32 m0, s55
	s_nop 0
	global_load_lds_dwordx4 v130, s[56:57]
	s_add_i32 m0, s55, 0x2000
	s_nop 0
	global_load_lds_dwordx4 v134, s[56:57]
	s_waitcnt vmcnt(6)
	s_barrier
	s_setprio 1
	v_mfma_f32_16x16x32_bf16 v[52:55], v[210:213], v[170:173], v[52:55]
	v_mfma_f32_16x16x32_bf16 v[48:51], v[218:221], v[170:173], v[48:51]
	v_mfma_f32_16x16x32_bf16 v[36:39], v[210:213], v[178:181], v[36:39]
	v_mfma_f32_16x16x32_bf16 v[32:35], v[218:221], v[178:181], v[32:35]
	v_mfma_f32_16x16x32_bf16 v[20:23], v[210:213], v[194:197], v[20:23]
	v_mfma_f32_16x16x32_bf16 v[16:19], v[218:221], v[194:197], v[16:19]
	v_mfma_f32_16x16x32_bf16 v[4:7], v[210:213], v[202:205], v[4:7]
	v_mfma_f32_16x16x32_bf16 v[0:3], v[218:221], v[202:205], v[0:3]
	v_mfma_f32_16x16x32_bf16 v[52:55], v[214:217], v[174:177], v[52:55]
	v_mfma_f32_16x16x32_bf16 v[48:51], v[222:225], v[174:177], v[48:51]
	v_mfma_f32_16x16x32_bf16 v[36:39], v[214:217], v[186:189], v[36:39]
	v_mfma_f32_16x16x32_bf16 v[32:35], v[222:225], v[186:189], v[32:35]
	v_mfma_f32_16x16x32_bf16 v[20:23], v[214:217], v[198:201], v[20:23]
	v_mfma_f32_16x16x32_bf16 v[16:19], v[222:225], v[198:201], v[16:19]
	v_mfma_f32_16x16x32_bf16 v[4:7], v[214:217], v[206:209], v[4:7]
	v_mfma_f32_16x16x32_bf16 v[0:3], v[222:225], v[206:209], v[0:3]
	s_setprio 0
	s_add_i32 s55, 0, 0x18000
	v_add_u32_e32 v161, s55, v155
	s_barrier
	ds_read_b128 v[144:147], v161
	ds_read_b128 v[148:151], v161 offset:1024
	ds_read_b128 v[162:165], v161 offset:2048
	ds_read_b128 v[166:169], v161 offset:3072
	s_add_u32 s34, s34, 0x80000
	s_addc_u32 s35, s35, 0
	s_mov_b32 m0, s41
	ds_read_b128 v[170:173], v158 offset:32768
	ds_read_b128 v[174:177], v158 offset:33792
	ds_read_b128 v[178:181], v158 offset:34816
	ds_read_b128 v[186:189], v158 offset:35840
	ds_read_b128 v[194:197], v158 offset:36864
	ds_read_b128 v[198:201], v158 offset:37888
	ds_read_b128 v[202:205], v158 offset:38912
	ds_read_b128 v[206:209], v158 offset:39936
	global_load_lds_dwordx4 v128, s[34:35]
	s_mov_b32 m0, s42
	s_nop 0
	global_load_lds_dwordx4 v132, s[34:35]
	s_waitcnt lgkmcnt(8)
	s_barrier
	s_setprio 1
	s_waitcnt lgkmcnt(7)
	v_mfma_f32_16x16x32_bf16 v[124:127], v[144:147], v[170:173], v[124:127]
	v_mfma_f32_16x16x32_bf16 v[120:123], v[162:165], v[170:173], v[120:123]
	s_waitcnt lgkmcnt(5)
	v_mfma_f32_16x16x32_bf16 v[108:111], v[144:147], v[178:181], v[108:111]
	v_mfma_f32_16x16x32_bf16 v[104:107], v[162:165], v[178:181], v[104:107]
	s_waitcnt lgkmcnt(3)
	v_mfma_f32_16x16x32_bf16 v[92:95], v[144:147], v[194:197], v[92:95]
	v_mfma_f32_16x16x32_bf16 v[88:91], v[162:165], v[194:197], v[88:91]
	s_waitcnt lgkmcnt(1)
	v_mfma_f32_16x16x32_bf16 v[76:79], v[144:147], v[202:205], v[76:79]
	v_mfma_f32_16x16x32_bf16 v[72:75], v[162:165], v[202:205], v[72:75]
	v_mfma_f32_16x16x32_bf16 v[124:127], v[148:151], v[174:177], v[124:127]
	v_mfma_f32_16x16x32_bf16 v[120:123], v[166:169], v[174:177], v[120:123]
	v_mfma_f32_16x16x32_bf16 v[108:111], v[148:151], v[186:189], v[108:111]
	v_mfma_f32_16x16x32_bf16 v[104:107], v[166:169], v[186:189], v[104:107]
	v_mfma_f32_16x16x32_bf16 v[92:95], v[148:151], v[198:201], v[92:95]
	v_mfma_f32_16x16x32_bf16 v[88:91], v[166:169], v[198:201], v[88:91]
	s_waitcnt lgkmcnt(0)
	v_mfma_f32_16x16x32_bf16 v[76:79], v[148:151], v[206:209], v[76:79]
	v_mfma_f32_16x16x32_bf16 v[72:75], v[166:169], v[206:209], v[72:75]
	s_setprio 0
	s_barrier
	s_add_i32 s34, 0, 0x1c000
	s_add_i32 s35, s55, s38
	v_add_u32_e32 v161, s34, v155
	s_mov_b32 m0, s35
	ds_read_b128 v[210:213], v161
	ds_read_b128 v[214:217], v161 offset:1024
	ds_read_b128 v[218:221], v161 offset:2048
	ds_read_b128 v[222:225], v161 offset:3072
	global_load_lds_dwordx4 v130, s[58:59]
	s_add_i32 m0, s35, 0x2000
	s_nop 0
	global_load_lds_dwordx4 v134, s[58:59]
	s_barrier
	s_setprio 1
	s_waitcnt lgkmcnt(3)
	v_mfma_f32_16x16x32_bf16 v[116:119], v[210:213], v[170:173], v[116:119]
	s_waitcnt lgkmcnt(1)
	v_mfma_f32_16x16x32_bf16 v[112:115], v[218:221], v[170:173], v[112:115]
	v_mfma_f32_16x16x32_bf16 v[100:103], v[210:213], v[178:181], v[100:103]
	v_mfma_f32_16x16x32_bf16 v[96:99], v[218:221], v[178:181], v[96:99]
	v_mfma_f32_16x16x32_bf16 v[84:87], v[210:213], v[194:197], v[84:87]
	v_mfma_f32_16x16x32_bf16 v[80:83], v[218:221], v[194:197], v[80:83]
	v_mfma_f32_16x16x32_bf16 v[68:71], v[210:213], v[202:205], v[68:71]
	v_mfma_f32_16x16x32_bf16 v[64:67], v[218:221], v[202:205], v[64:67]
	v_mfma_f32_16x16x32_bf16 v[116:119], v[214:217], v[174:177], v[116:119]
	s_waitcnt lgkmcnt(0)
	v_mfma_f32_16x16x32_bf16 v[112:115], v[222:225], v[174:177], v[112:115]
	v_mfma_f32_16x16x32_bf16 v[100:103], v[214:217], v[186:189], v[100:103]
	v_mfma_f32_16x16x32_bf16 v[96:99], v[222:225], v[186:189], v[96:99]
	v_mfma_f32_16x16x32_bf16 v[84:87], v[214:217], v[198:201], v[84:87]
	v_mfma_f32_16x16x32_bf16 v[80:83], v[222:225], v[198:201], v[80:83]
	v_mfma_f32_16x16x32_bf16 v[68:71], v[214:217], v[206:209], v[68:71]
	v_mfma_f32_16x16x32_bf16 v[64:67], v[222:225], v[206:209], v[64:67]
	s_setprio 0
	s_mov_b32 m0, s44
	s_barrier
; __device__ __forceinline__ unsigned pk2(float lo, float hi) { unsigned r; asm("v_cvt_pk_bf16_f32 %0, %1, %2" : "=v"(r) : "v"(lo), "v"(hi)); return r; }
; template <class Epi>
; __device__ __forceinline__ void gemm_phase(LAS unsigned char* lds, const GemmD g, const Epi& E) {
;     ...
;         for (int t = 0; t < nt; t += 2) PG8_KITER(t);
;     __device__ __forceinline__ void operator()(const f32x4 (&acc)[2][2][4][2], const Unit& u, int wr, int wc, int fr, int fq) const {
;         const int row0 = u.pm * BM + wr * 64 + fr, col0 = u.pn * BM + wc * 32 + 8 * fq;
;         const bool sig = (u.pn >= 36 && u.pn < 52), isdt = (u.pn == 52);
; #pragma unroll
;         for (int ai = 0; ai < 2; ++ai)
; #pragma unroll
;             for (int m = 0; m < 4; ++m) { const int row = row0 + ai * HALF + m * 16;
; #pragma unroll
;                 for (int bj = 0; bj < 2; ++bj) { const f32x4 v0 = acc[ai][bj][m][0], v1 = acc[ai][bj][m][1]; const int col = col0 + bj * HALF;
;                     if (sig) {
;                         const int c = (col - C_GS) >> 1;
;                         float ra[4], gp[4];
; #pragma unroll
;                         for (int j = 0; j < 4; ++j) { const float ea = __expf(-fminf(fmaxf(v0[j], -30.f), 30.f)), eb = __expf(-fminf(fmaxf(v1[j], -30.f), 30.f)); gp[j] = __builtin_amdgcn_rcpf(1.0f + eb); ra[j] = (1.0f + eb) * __builtin_amdgcn_rcpf(1.0f + ea); }
;                         u32x2 wr_, wg; wr_.x = pk2(ra[0], ra[1]); wr_.y = pk2(ra[2], ra[3]); wg.x = pk2(gp[0], gp[1]); wg.y = pk2(gp[2], gp[3]);
;                         *(u32x2*)(proj + (size_t)row * NPROJ + C_GS + c) = wr_;
;                         *(u32x2*)(proj + (size_t)row * NPROJ + C_GP + c) = wg;
;                     } else {
;                         u32x4 w; w.x = pk2(v0[0], v0[1]); w.y = pk2(v0[2], v0[3]); w.z = pk2(v1[0], v1[1]); w.w = pk2(v1[2], v1[3]);
;                         *(u32x4*)(proj + (size_t)row * NPROJ + col) = w;
;                         if (isdt && col < C_DT + 32) { float* d = dtraw + (size_t)row * 32 + (col - C_DT); *(f32x4*)d = v0; *(f32x4*)(d + 4) = v1; } } } }
	ds_read_b128 v[170:173], v158 offset:49152
	ds_read_b128 v[174:177], v158 offset:50176
	ds_read_b128 v[178:181], v158 offset:51200
	ds_read_b128 v[186:189], v158 offset:52224
	ds_read_b128 v[194:197], v158 offset:53248
	ds_read_b128 v[198:201], v158 offset:54272
	ds_read_b128 v[202:205], v158 offset:55296
	ds_read_b128 v[206:209], v158 offset:56320
	global_load_lds_dwordx4 v128, s[60:61]
	s_mov_b32 m0, s45
	s_nop 0
	global_load_lds_dwordx4 v132, s[60:61]
	s_barrier
	s_setprio 1
	s_waitcnt lgkmcnt(7)
	v_mfma_f32_16x16x32_bf16 v[60:63], v[144:147], v[170:173], v[60:63]
	v_mfma_f32_16x16x32_bf16 v[56:59], v[162:165], v[170:173], v[56:59]
	s_waitcnt lgkmcnt(5)
	v_mfma_f32_16x16x32_bf16 v[44:47], v[144:147], v[178:181], v[44:47]
	v_mfma_f32_16x16x32_bf16 v[40:43], v[162:165], v[178:181], v[40:43]
	s_waitcnt lgkmcnt(3)
	v_mfma_f32_16x16x32_bf16 v[28:31], v[144:147], v[194:197], v[28:31]
	v_mfma_f32_16x16x32_bf16 v[24:27], v[162:165], v[194:197], v[24:27]
	s_waitcnt lgkmcnt(1)
	v_mfma_f32_16x16x32_bf16 v[12:15], v[144:147], v[202:205], v[12:15]
	v_mfma_f32_16x16x32_bf16 v[8:11], v[162:165], v[202:205], v[8:11]
	v_mfma_f32_16x16x32_bf16 v[60:63], v[148:151], v[174:177], v[60:63]
	v_mfma_f32_16x16x32_bf16 v[56:59], v[166:169], v[174:177], v[56:59]
	v_mfma_f32_16x16x32_bf16 v[44:47], v[148:151], v[186:189], v[44:47]
	v_mfma_f32_16x16x32_bf16 v[40:43], v[166:169], v[186:189], v[40:43]
	v_mfma_f32_16x16x32_bf16 v[28:31], v[148:151], v[198:201], v[28:31]
	v_mfma_f32_16x16x32_bf16 v[24:27], v[166:169], v[198:201], v[24:27]
	s_waitcnt lgkmcnt(0)
	v_mfma_f32_16x16x32_bf16 v[12:15], v[148:151], v[206:209], v[12:15]
	v_mfma_f32_16x16x32_bf16 v[8:11], v[166:169], v[206:209], v[8:11]
	s_setprio 0
	s_barrier
	s_add_u32 s30, s30, 0x80080
	s_addc_u32 s31, s31, 0
	s_add_i32 s34, s34, s38
	s_mov_b32 m0, s34
	s_nop 0
	global_load_lds_dwordx4 v130, s[30:31]
	s_add_i32 m0, s34, 0x2000
	s_nop 0
	global_load_lds_dwordx4 v134, s[30:31]
	s_waitcnt vmcnt(6)
	s_barrier
	s_setprio 1
	v_mfma_f32_16x16x32_bf16 v[52:55], v[210:213], v[170:173], v[52:55]
	v_mfma_f32_16x16x32_bf16 v[48:51], v[218:221], v[170:173], v[48:51]
	v_mfma_f32_16x16x32_bf16 v[36:39], v[210:213], v[178:181], v[36:39]
	v_mfma_f32_16x16x32_bf16 v[32:35], v[218:221], v[178:181], v[32:35]
	v_mfma_f32_16x16x32_bf16 v[20:23], v[210:213], v[194:197], v[20:23]
	v_mfma_f32_16x16x32_bf16 v[16:19], v[218:221], v[194:197], v[16:19]
	v_mfma_f32_16x16x32_bf16 v[4:7], v[210:213], v[202:205], v[4:7]
	v_mfma_f32_16x16x32_bf16 v[0:3], v[218:221], v[202:205], v[0:3]
	v_mfma_f32_16x16x32_bf16 v[52:55], v[214:217], v[174:177], v[52:55]
	v_mfma_f32_16x16x32_bf16 v[48:51], v[222:225], v[174:177], v[48:51]
	v_mfma_f32_16x16x32_bf16 v[36:39], v[214:217], v[186:189], v[36:39]
	v_mfma_f32_16x16x32_bf16 v[32:35], v[222:225], v[186:189], v[32:35]
	v_mfma_f32_16x16x32_bf16 v[20:23], v[214:217], v[198:201], v[20:23]
	v_mfma_f32_16x16x32_bf16 v[16:19], v[222:225], v[198:201], v[16:19]
	v_mfma_f32_16x16x32_bf16 v[4:7], v[214:217], v[206:209], v[4:7]
	v_mfma_f32_16x16x32_bf16 v[0:3], v[222:225], v[206:209], v[0:3]
	s_setprio 0
	s_add_i32 s54, s54, 2
	s_add_u32 s28, s28, 0x100
	s_addc_u32 s29, s29, 0
	s_add_u32 s11, s11, 0x100
	s_addc_u32 s27, s27, 0
	s_cmp_gt_u32 s54, 29
	s_barrier
	s_cbranch_scc0 .LBB0_181
	s_sub_i32 s2, s6, 36
	v_lshl_add_u32 v146, s26, 8, v154
	s_cmp_gt_u32 s2, 15
	s_cselect_b64 s[28:29], -1, 0
	s_cmp_eq_u32 s6, 52
	v_ashrrev_i32_e32 v147, 31, v146
	v_mad_i64_i32 v[152:153], s[2:3], v146, s50, 0
	v_lshl_or_b32 v144, s6, 8, v156
	s_cselect_b64 s[26:27], -1, 0
	v_lshlrev_b64 v[150:151], 7, v[146:147]
	s_mov_b64 s[2:3], -1
	s_and_b64 vcc, exec, s[28:29]
	s_cbranch_vccz .LBB0_186
	v_lshl_add_u64 v[148:149], s[92:93], 0, v[152:153]
	v_ashrrev_i32_e32 v145, 31, v144
	v_cmp_gt_i32_e32 vcc, s52, v144
	v_lshl_add_u64 v[148:149], v[144:145], 1, v[148:149]
	s_and_b64 s[2:3], s[26:27], vcc
	v_cvt_pk_bf16_f32 v162, v124, v125
	v_cvt_pk_bf16_f32 v163, v126, v127
	v_cvt_pk_bf16_f32 v164, v120, v121
	v_cvt_pk_bf16_f32 v165, v122, v123
	global_store_dwordx4 v[148:149], v[162:165], off
	s_and_saveexec_b64 s[6:7], s[2:3]
	s_cbranch_execz .LBB0_185
	v_lshl_add_u64 v[148:149], s[14:15], 0, v[150:151]
	v_lshl_add_u64 v[148:149], v[144:145], 2, v[148:149]
	v_add_co_u32_e32 v162, vcc, 0xffff3000, v148
	s_nop 1
	v_addc_co_u32_e32 v163, vcc, -1, v149, vcc
	v_add_co_u32_e32 v148, vcc, 0xffff4000, v148
	global_store_dwordx4 v[162:163], v[124:127], off
	s_nop 0
	v_addc_co_u32_e32 v149, vcc, -1, v149, vcc
	global_store_dwordx4 v[148:149], v[120:123], off offset:-4080

.LBB0_600:
	ds_read_b128 v[128:131], v188
	ds_read_b128 v[132:135], v188 offset:1024
	ds_read_b128 v[136:139], v188 offset:2048
	ds_read_b128 v[140:143], v188 offset:3072
	s_add_u32 s30, s6, 0xfff80080
	s_addc_u32 s31, s7, -1
	s_cmp_eq_u32 s51, 4
	s_cselect_b32 s35, s25, s31
	s_cselect_b32 s34, s24, s30
	s_cselect_b32 s31, s2, s15
	s_cselect_b32 s30, s3, s13
	v_lshl_add_u64 v[202:203], s[6:7], 0, v[160:161]
	s_add_i32 m0, s29, 0xc000
	ds_read_b128 v[144:147], v189
	ds_read_b128 v[148:151], v189 offset:1024
	ds_read_b128 v[168:171], v189 offset:2048
	ds_read_b128 v[172:175], v189 offset:3072
	ds_read_b128 v[176:179], v189 offset:4096
	ds_read_b128 v[180:183], v189 offset:5120
	ds_read_b128 v[194:197], v189 offset:6144
	ds_read_b128 v[198:201], v189 offset:7168
	global_load_lds_dwordx4 v[202:203], off
	v_lshl_add_u64 v[202:203], s[6:7], 0, v[162:163]
	s_add_i32 m0, s29, 0xe000
	s_nop 0
	global_load_lds_dwordx4 v[202:203], off
	s_waitcnt lgkmcnt(8)
	s_barrier
	s_setprio 1
	s_waitcnt lgkmcnt(7)
	v_mfma_f32_16x16x32_bf16 v[124:127], v[128:131], v[144:147], v[124:127]
	v_mfma_f32_16x16x32_bf16 v[120:123], v[136:139], v[144:147], v[120:123]
	s_waitcnt lgkmcnt(5)
	v_mfma_f32_16x16x32_bf16 v[116:119], v[128:131], v[168:171], v[116:119]
	v_mfma_f32_16x16x32_bf16 v[112:115], v[136:139], v[168:171], v[112:115]
	s_waitcnt lgkmcnt(3)
	v_mfma_f32_16x16x32_bf16 v[108:111], v[128:131], v[176:179], v[108:111]
	v_mfma_f32_16x16x32_bf16 v[104:107], v[136:139], v[176:179], v[104:107]
	s_waitcnt lgkmcnt(1)
	v_mfma_f32_16x16x32_bf16 v[100:103], v[128:131], v[194:197], v[100:103]
	v_mfma_f32_16x16x32_bf16 v[96:99], v[136:139], v[194:197], v[96:99]
	v_mfma_f32_16x16x32_bf16 v[124:127], v[132:135], v[148:151], v[124:127]
	v_mfma_f32_16x16x32_bf16 v[120:123], v[140:143], v[148:151], v[120:123]
	v_mfma_f32_16x16x32_bf16 v[116:119], v[132:135], v[172:175], v[116:119]
	v_mfma_f32_16x16x32_bf16 v[112:115], v[140:143], v[172:175], v[112:115]
	v_mfma_f32_16x16x32_bf16 v[108:111], v[132:135], v[180:183], v[108:111]
	v_mfma_f32_16x16x32_bf16 v[104:107], v[140:143], v[180:183], v[104:107]
	s_waitcnt lgkmcnt(0)
	v_mfma_f32_16x16x32_bf16 v[100:103], v[132:135], v[198:201], v[100:103]
	v_mfma_f32_16x16x32_bf16 v[96:99], v[140:143], v[198:201], v[96:99]
	s_setprio 0
	s_barrier
	s_add_i32 s52, s47, s38
	v_lshl_add_u64 v[218:219], s[30:31], 0, v[156:157]
	s_mov_b32 m0, s52
	ds_read_b128 v[202:205], v190
	ds_read_b128 v[206:209], v190 offset:1024
	ds_read_b128 v[210:213], v190 offset:2048
	ds_read_b128 v[214:217], v190 offset:3072
	global_load_lds_dwordx4 v[218:219], off
	v_lshl_add_u64 v[220:221], s[30:31], 0, v[152:153]
	s_add_i32 m0, s52, 0x2000
	s_nop 0
	global_load_lds_dwordx4 v[220:221], off
	s_barrier
	s_setprio 1
	s_waitcnt lgkmcnt(3)
	v_mfma_f32_16x16x32_bf16 v[60:63], v[202:205], v[144:147], v[60:63]
	s_waitcnt lgkmcnt(1)
	v_mfma_f32_16x16x32_bf16 v[56:59], v[210:213], v[144:147], v[56:59]
	v_mfma_f32_16x16x32_bf16 v[52:55], v[202:205], v[168:171], v[52:55]
	v_mfma_f32_16x16x32_bf16 v[48:51], v[210:213], v[168:171], v[48:51]
	v_mfma_f32_16x16x32_bf16 v[44:47], v[202:205], v[176:179], v[44:47]
	v_mfma_f32_16x16x32_bf16 v[40:43], v[210:213], v[176:179], v[40:43]
	v_mfma_f32_16x16x32_bf16 v[36:39], v[202:205], v[194:197], v[36:39]
	v_mfma_f32_16x16x32_bf16 v[32:35], v[210:213], v[194:197], v[32:35]
	v_mfma_f32_16x16x32_bf16 v[60:63], v[206:209], v[148:151], v[60:63]
	s_waitcnt lgkmcnt(0)
	v_mfma_f32_16x16x32_bf16 v[56:59], v[214:217], v[148:151], v[56:59]
	v_mfma_f32_16x16x32_bf16 v[52:55], v[206:209], v[172:175], v[52:55]
	v_mfma_f32_16x16x32_bf16 v[48:51], v[214:217], v[172:175], v[48:51]
	v_mfma_f32_16x16x32_bf16 v[44:47], v[206:209], v[180:183], v[44:47]
	v_mfma_f32_16x16x32_bf16 v[40:43], v[214:217], v[180:183], v[40:43]
	v_mfma_f32_16x16x32_bf16 v[36:39], v[206:209], v[198:201], v[36:39]
	v_mfma_f32_16x16x32_bf16 v[32:35], v[214:217], v[198:201], v[32:35]
	s_setprio 0
	s_mov_b32 m0, s29
	v_lshl_add_u64 v[222:223], s[34:35], 0, v[158:159]
	s_barrier
	ds_read_b128 v[144:147], v189 offset:16384
	ds_read_b128 v[148:151], v189 offset:17408
	ds_read_b128 v[168:171], v189 offset:18432
	ds_read_b128 v[172:175], v189 offset:19456
	ds_read_b128 v[176:179], v189 offset:20480
	ds_read_b128 v[180:183], v189 offset:21504
	ds_read_b128 v[194:197], v189 offset:22528
	ds_read_b128 v[198:201], v189 offset:23552
	global_load_lds_dwordx4 v[222:223], off
	v_lshl_add_u64 v[224:225], s[34:35], 0, v[154:155]
	s_mov_b32 m0, s39
	s_nop 0
	global_load_lds_dwordx4 v[224:225], off
	s_barrier
	s_setprio 1
	s_waitcnt lgkmcnt(7)
	v_mfma_f32_16x16x32_bf16 v[92:95], v[128:131], v[144:147], v[92:95]
	v_mfma_f32_16x16x32_bf16 v[88:91], v[136:139], v[144:147], v[88:91]
	s_waitcnt lgkmcnt(5)
	v_mfma_f32_16x16x32_bf16 v[84:87], v[128:131], v[168:171], v[84:87]
	v_mfma_f32_16x16x32_bf16 v[80:83], v[136:139], v[168:171], v[80:83]
	s_waitcnt lgkmcnt(3)
	v_mfma_f32_16x16x32_bf16 v[76:79], v[128:131], v[176:179], v[76:79]
	v_mfma_f32_16x16x32_bf16 v[72:75], v[136:139], v[176:179], v[72:75]
	s_waitcnt lgkmcnt(1)
	v_mfma_f32_16x16x32_bf16 v[68:71], v[128:131], v[194:197], v[68:71]
	v_mfma_f32_16x16x32_bf16 v[64:67], v[136:139], v[194:197], v[64:67]
	v_mfma_f32_16x16x32_bf16 v[92:95], v[132:135], v[148:151], v[92:95]
	v_mfma_f32_16x16x32_bf16 v[88:91], v[140:143], v[148:151], v[88:91]
	v_mfma_f32_16x16x32_bf16 v[84:87], v[132:135], v[172:175], v[84:87]
	v_mfma_f32_16x16x32_bf16 v[80:83], v[140:143], v[172:175], v[80:83]
	v_mfma_f32_16x16x32_bf16 v[76:79], v[132:135], v[180:183], v[76:79]
	v_mfma_f32_16x16x32_bf16 v[72:75], v[140:143], v[180:183], v[72:75]
	s_waitcnt lgkmcnt(0)
	v_mfma_f32_16x16x32_bf16 v[68:71], v[132:135], v[198:201], v[68:71]
	v_mfma_f32_16x16x32_bf16 v[64:67], v[140:143], v[198:201], v[64:67]
	s_setprio 0
	s_barrier
	s_add_u32 s52, s30, 0x20000
	s_addc_u32 s53, s31, 0
	s_add_i32 s54, s48, s38
	v_lshl_add_u64 v[128:129], s[52:53], 0, v[156:157]
	s_mov_b32 m0, s54
	s_nop 0
	global_load_lds_dwordx4 v[128:129], off
	v_lshl_add_u64 v[128:129], s[52:53], 0, v[152:153]
	s_add_i32 m0, s54, 0x2000
	s_nop 0
	global_load_lds_dwordx4 v[128:129], off
	s_waitcnt vmcnt(6)
	s_barrier
	s_setprio 1
	v_mfma_f32_16x16x32_bf16 v[28:31], v[202:205], v[144:147], v[28:31]
	v_mfma_f32_16x16x32_bf16 v[24:27], v[210:213], v[144:147], v[24:27]
	v_mfma_f32_16x16x32_bf16 v[20:23], v[202:205], v[168:171], v[20:23]
	v_mfma_f32_16x16x32_bf16 v[16:19], v[210:213], v[168:171], v[16:19]
	v_mfma_f32_16x16x32_bf16 v[12:15], v[202:205], v[176:179], v[12:15]
	v_mfma_f32_16x16x32_bf16 v[8:11], v[210:213], v[176:179], v[8:11]
	v_mfma_f32_16x16x32_bf16 v[4:7], v[202:205], v[194:197], v[4:7]
	v_mfma_f32_16x16x32_bf16 v[0:3], v[210:213], v[194:197], v[0:3]
	v_mfma_f32_16x16x32_bf16 v[28:31], v[206:209], v[148:151], v[28:31]
	v_mfma_f32_16x16x32_bf16 v[24:27], v[214:217], v[148:151], v[24:27]
	v_mfma_f32_16x16x32_bf16 v[20:23], v[206:209], v[172:175], v[20:23]
	v_mfma_f32_16x16x32_bf16 v[16:19], v[214:217], v[172:175], v[16:19]
	v_mfma_f32_16x16x32_bf16 v[12:15], v[206:209], v[180:183], v[12:15]
	v_mfma_f32_16x16x32_bf16 v[8:11], v[214:217], v[180:183], v[8:11]
	v_mfma_f32_16x16x32_bf16 v[4:7], v[206:209], v[198:201], v[4:7]
	v_mfma_f32_16x16x32_bf16 v[0:3], v[214:217], v[198:201], v[0:3]
	s_setprio 0
	s_add_i32 s52, 0, 0x18000
	v_add_u32_e32 v140, s52, v186
	s_barrier
	ds_read_b128 v[128:131], v140
	ds_read_b128 v[132:135], v140 offset:1024
	ds_read_b128 v[136:139], v140 offset:2048
	ds_read_b128 v[140:143], v140 offset:3072
	s_add_u32 s34, s34, 0x80000
	s_addc_u32 s35, s35, 0
	s_mov_b32 m0, s40
	v_lshl_add_u64 v[202:203], s[34:35], 0, v[158:159]
	ds_read_b128 v[144:147], v189 offset:32768
	ds_read_b128 v[148:151], v189 offset:33792
	ds_read_b128 v[168:171], v189 offset:34816
	ds_read_b128 v[172:175], v189 offset:35840
	ds_read_b128 v[176:179], v189 offset:36864
	ds_read_b128 v[180:183], v189 offset:37888
	ds_read_b128 v[194:197], v189 offset:38912
	ds_read_b128 v[198:201], v189 offset:39936
	global_load_lds_dwordx4 v[202:203], off
	v_lshl_add_u64 v[202:203], s[34:35], 0, v[154:155]
	s_mov_b32 m0, s41
	s_nop 0
	global_load_lds_dwordx4 v[202:203], off
	s_waitcnt lgkmcnt(8)
	s_barrier
	s_setprio 1
	s_waitcnt lgkmcnt(7)
	v_mfma_f32_16x16x32_bf16 v[124:127], v[128:131], v[144:147], v[124:127]
	v_mfma_f32_16x16x32_bf16 v[120:123], v[136:139], v[144:147], v[120:123]
	s_waitcnt lgkmcnt(5)
	v_mfma_f32_16x16x32_bf16 v[116:119], v[128:131], v[168:171], v[116:119]
	v_mfma_f32_16x16x32_bf16 v[112:115], v[136:139], v[168:171], v[112:115]
	s_waitcnt lgkmcnt(3)
	v_mfma_f32_16x16x32_bf16 v[108:111], v[128:131], v[176:179], v[108:111]
	v_mfma_f32_16x16x32_bf16 v[104:107], v[136:139], v[176:179], v[104:107]
	s_waitcnt lgkmcnt(1)
	v_mfma_f32_16x16x32_bf16 v[100:103], v[128:131], v[194:197], v[100:103]
	v_mfma_f32_16x16x32_bf16 v[96:99], v[136:139], v[194:197], v[96:99]
	v_mfma_f32_16x16x32_bf16 v[124:127], v[132:135], v[148:151], v[124:127]
	v_mfma_f32_16x16x32_bf16 v[120:123], v[140:143], v[148:151], v[120:123]
	v_mfma_f32_16x16x32_bf16 v[116:119], v[132:135], v[172:175], v[116:119]
	v_mfma_f32_16x16x32_bf16 v[112:115], v[140:143], v[172:175], v[112:115]
	v_mfma_f32_16x16x32_bf16 v[108:111], v[132:135], v[180:183], v[108:111]
	v_mfma_f32_16x16x32_bf16 v[104:107], v[140:143], v[180:183], v[104:107]
	s_waitcnt lgkmcnt(0)
	v_mfma_f32_16x16x32_bf16 v[100:103], v[132:135], v[198:201], v[100:103]
	v_mfma_f32_16x16x32_bf16 v[96:99], v[140:143], v[198:201], v[96:99]
	s_setprio 0
	s_barrier
	s_add_i32 s34, 0, 0x1c000
	s_add_i32 s35, s52, s38
	v_add_u32_e32 v191, s34, v186
	v_lshl_add_u64 v[218:219], v[218:219], 0, s[0:1]
	s_mov_b32 m0, s35
	ds_read_b128 v[202:205], v191
	ds_read_b128 v[206:209], v191 offset:1024
	ds_read_b128 v[210:213], v191 offset:2048
	ds_read_b128 v[214:217], v191 offset:3072
	global_load_lds_dwordx4 v[218:219], off
	v_lshl_add_u64 v[218:219], v[220:221], 0, s[0:1]
	s_add_i32 m0, s35, 0x2000
	s_nop 0
	global_load_lds_dwordx4 v[218:219], off
	s_barrier
	s_setprio 1
	s_waitcnt lgkmcnt(3)
	v_mfma_f32_16x16x32_bf16 v[60:63], v[202:205], v[144:147], v[60:63]
	s_waitcnt lgkmcnt(1)
	v_mfma_f32_16x16x32_bf16 v[56:59], v[210:213], v[144:147], v[56:59]
	v_mfma_f32_16x16x32_bf16 v[52:55], v[202:205], v[168:171], v[52:55]
	v_mfma_f32_16x16x32_bf16 v[48:51], v[210:213], v[168:171], v[48:51]
	v_mfma_f32_16x16x32_bf16 v[44:47], v[202:205], v[176:179], v[44:47]
	v_mfma_f32_16x16x32_bf16 v[40:43], v[210:213], v[176:179], v[40:43]
	v_mfma_f32_16x16x32_bf16 v[36:39], v[202:205], v[194:197], v[36:39]
	v_mfma_f32_16x16x32_bf16 v[32:35], v[210:213], v[194:197], v[32:35]
	v_mfma_f32_16x16x32_bf16 v[60:63], v[206:209], v[148:151], v[60:63]
	s_waitcnt lgkmcnt(0)
	v_mfma_f32_16x16x32_bf16 v[56:59], v[214:217], v[148:151], v[56:59]
	v_mfma_f32_16x16x32_bf16 v[52:55], v[206:209], v[172:175], v[52:55]
	v_mfma_f32_16x16x32_bf16 v[48:51], v[214:217], v[172:175], v[48:51]
	v_mfma_f32_16x16x32_bf16 v[44:47], v[206:209], v[180:183], v[44:47]
	v_mfma_f32_16x16x32_bf16 v[40:43], v[214:217], v[180:183], v[40:43]
	v_mfma_f32_16x16x32_bf16 v[36:39], v[206:209], v[198:201], v[36:39]
	v_mfma_f32_16x16x32_bf16 v[32:35], v[214:217], v[198:201], v[32:35]
	s_setprio 0
	s_mov_b32 m0, s43
	v_lshl_add_u64 v[218:219], v[222:223], 0, s[0:1]
	s_barrier
; template <class Epi>
; __device__ __forceinline__ void gemm_phase(LAS unsigned char* lds, const GemmD g, const Epi& E) {
;     ...
;         for (int t = 0; t < nt; t += 2) PG8_KITER(t);
;     __device__ __forceinline__ void operator()(const f32x4 (&acc)[2][2][4][2], const Unit& u, int wr, int wc, int fr, int fq) const {
;         const int row0 = u.pm * BM + wr * 64 + fr, col0 = u.pn * BM + wc * 32 + 8 * fq;
; #pragma unroll
;         for (int bj = 0; bj < 2; ++bj) { const int col = col0 + bj * HALF;
;             const f32x4 b0 = *(const f32x4*)(bias + col), b1 = *(const f32x4*)(bias + col + 4), s0 = *(const f32x4*)(scale + col), s1 = *(const f32x4*)(scale + col + 4);
; #pragma unroll
;             for (int ai = 0; ai < 2; ++ai)
; #pragma unroll
;                 for (int m = 0; m < 4; ++m) { const int row = row0 + ai * HALF + m * 16;
;                     const u32x4 z = __builtin_nontemporal_load((const u32x4*)(proj + (size_t)row * NPROJ + C_ZP + col));
	ds_read_b128 v[144:147], v189 offset:49152
	ds_read_b128 v[148:151], v189 offset:50176
	ds_read_b128 v[168:171], v189 offset:51200
	ds_read_b128 v[172:175], v189 offset:52224
	ds_read_b128 v[176:179], v189 offset:53248
	ds_read_b128 v[180:183], v189 offset:54272
	ds_read_b128 v[194:197], v189 offset:55296
	ds_read_b128 v[198:201], v189 offset:56320
	global_load_lds_dwordx4 v[218:219], off
	v_lshl_add_u64 v[218:219], v[224:225], 0, s[0:1]
	s_mov_b32 m0, s44
	s_nop 0
	global_load_lds_dwordx4 v[218:219], off
	s_barrier
	s_setprio 1
	s_waitcnt lgkmcnt(7)
	v_mfma_f32_16x16x32_bf16 v[92:95], v[128:131], v[144:147], v[92:95]
	v_mfma_f32_16x16x32_bf16 v[88:91], v[136:139], v[144:147], v[88:91]
	s_waitcnt lgkmcnt(5)
	v_mfma_f32_16x16x32_bf16 v[84:87], v[128:131], v[168:171], v[84:87]
	v_mfma_f32_16x16x32_bf16 v[80:83], v[136:139], v[168:171], v[80:83]
	s_waitcnt lgkmcnt(3)
	v_mfma_f32_16x16x32_bf16 v[76:79], v[128:131], v[176:179], v[76:79]
	v_mfma_f32_16x16x32_bf16 v[72:75], v[136:139], v[176:179], v[72:75]
	s_waitcnt lgkmcnt(1)
	v_mfma_f32_16x16x32_bf16 v[68:71], v[128:131], v[194:197], v[68:71]
	v_mfma_f32_16x16x32_bf16 v[64:67], v[136:139], v[194:197], v[64:67]
	v_mfma_f32_16x16x32_bf16 v[92:95], v[132:135], v[148:151], v[92:95]
	v_mfma_f32_16x16x32_bf16 v[88:91], v[140:143], v[148:151], v[88:91]
	v_mfma_f32_16x16x32_bf16 v[84:87], v[132:135], v[172:175], v[84:87]
	v_mfma_f32_16x16x32_bf16 v[80:83], v[140:143], v[172:175], v[80:83]
	v_mfma_f32_16x16x32_bf16 v[76:79], v[132:135], v[180:183], v[76:79]
	v_mfma_f32_16x16x32_bf16 v[72:75], v[140:143], v[180:183], v[72:75]
	s_waitcnt lgkmcnt(0)
	v_mfma_f32_16x16x32_bf16 v[68:71], v[132:135], v[198:201], v[68:71]
	v_mfma_f32_16x16x32_bf16 v[64:67], v[140:143], v[198:201], v[64:67]
	s_setprio 0
	s_barrier
	s_add_u32 s30, s30, 0x20080
	s_addc_u32 s31, s31, 0
	s_add_i32 s34, s34, s38
	v_lshl_add_u64 v[128:129], s[30:31], 0, v[156:157]
	s_mov_b32 m0, s34
	s_nop 0
	global_load_lds_dwordx4 v[128:129], off
	v_lshl_add_u64 v[128:129], s[30:31], 0, v[152:153]
	s_add_i32 m0, s34, 0x2000
	s_nop 0
	global_load_lds_dwordx4 v[128:129], off
	s_waitcnt vmcnt(6)
	s_barrier
	s_setprio 1
	v_mfma_f32_16x16x32_bf16 v[28:31], v[202:205], v[144:147], v[28:31]
	v_mfma_f32_16x16x32_bf16 v[24:27], v[210:213], v[144:147], v[24:27]
	v_mfma_f32_16x16x32_bf16 v[20:23], v[202:205], v[168:171], v[20:23]
	v_mfma_f32_16x16x32_bf16 v[16:19], v[210:213], v[168:171], v[16:19]
	v_mfma_f32_16x16x32_bf16 v[12:15], v[202:205], v[176:179], v[12:15]
	v_mfma_f32_16x16x32_bf16 v[8:11], v[210:213], v[176:179], v[8:11]
	v_mfma_f32_16x16x32_bf16 v[4:7], v[202:205], v[194:197], v[4:7]
	v_mfma_f32_16x16x32_bf16 v[0:3], v[210:213], v[194:197], v[0:3]
	v_mfma_f32_16x16x32_bf16 v[28:31], v[206:209], v[148:151], v[28:31]
	v_mfma_f32_16x16x32_bf16 v[24:27], v[214:217], v[148:151], v[24:27]
	v_mfma_f32_16x16x32_bf16 v[20:23], v[206:209], v[172:175], v[20:23]
	v_mfma_f32_16x16x32_bf16 v[16:19], v[214:217], v[172:175], v[16:19]
	v_mfma_f32_16x16x32_bf16 v[12:15], v[206:209], v[180:183], v[12:15]
	v_mfma_f32_16x16x32_bf16 v[8:11], v[214:217], v[180:183], v[8:11]
	v_mfma_f32_16x16x32_bf16 v[4:7], v[206:209], v[198:201], v[4:7]
	v_mfma_f32_16x16x32_bf16 v[0:3], v[214:217], v[198:201], v[0:3]
	s_setprio 0
	s_add_i32 s51, s51, 2
	s_add_u32 s6, s6, 0x100
	s_addc_u32 s7, s7, 0
	s_add_u32 s13, s13, 0x100
	s_addc_u32 s15, s15, 0
	s_cmp_gt_u32 s51, 5
	s_barrier
	s_cbranch_scc0 .LBB0_600
	v_lshl_add_u32 v176, s28, 8, v185
	v_lshl_or_b32 v148, s50, 8, v187
	v_mov_b64_e32 v[178:179], s[92:93]
	v_ashrrev_i32_e32 v149, 31, v148
	v_readlane_b32 s52, v244, 0
	v_mad_i64_i32 v[138:139], s[2:3], v176, s49, v[178:179]
	v_lshlrev_b64 v[136:137], 2, v[148:149]
	v_readlane_b32 s53, v244, 1
	v_lshl_add_u64 v[150:151], v[138:139], 0, s[8:9]
	v_lshlrev_b64 v[174:175], 1, v[148:149]
	v_lshl_add_u64 v[170:171], s[52:53], 0, v[136:137]
	v_lshl_add_u64 v[138:139], v[150:151], 0, v[174:175]
	global_load_dwordx4 v[128:131], v[170:171], off offset:16
	global_load_dwordx4 v[132:135], v[170:171], off
	v_mov_b32_e32 v254, v138
	v_mov_b32_e32 v255, v139
	global_load_dwordx4 v[144:147], v[138:139], off nt
	v_readlane_b32 s54, v244, 2
	v_readlane_b32 s55, v244, 3
	v_ashrrev_i32_e32 v177, 31, v176
	v_lshlrev_b64 v[168:169], 13, v[176:177]
	v_lshl_add_u64 v[172:173], s[54:55], 0, v[136:137]
	global_load_dwordx4 v[140:143], v[172:173], off
	global_load_dwordx4 v[136:139], v[172:173], off offset:16
	v_readlane_b32 s6, v244, 45
	v_readlane_b32 s7, v244, 46
	v_or_b32_e32 v182, 16, v176
	v_mad_i64_i32 v[194:195], s[2:3], v182, s49, v[178:179]
	v_lshl_add_u64 v[180:181], s[6:7], 0, v[168:169]
	v_lshl_add_u64 v[180:181], v[180:181], 0, s[10:11]
	v_lshl_add_u64 v[196:197], v[180:181], 0, v[174:175]
	v_or_b32_e32 v148, 0x80, v148
	v_ashrrev_i32_e32 v149, 31, v148
	v_lshlrev_b64 v[168:169], 1, v[148:149]
	v_lshl_add_u64 v[148:149], v[150:151], 0, v[168:169]
	global_load_dwordx4 v[148:151], v[148:149], off nt
	global_load_dwordx4 v[234:237], v[170:171], off offset:512
	global_load_dwordx4 v[238:241], v[170:171], off offset:528
	global_load_dwordx4 v[246:249], v[172:173], off offset:512
	global_load_dwordx4 v[250:253], v[172:173], off offset:528
	s_mov_b32 s60, 0x6a000
	s_mov_b32 s61, 0
	v_lshl_add_u64 v[206:207], v[254:255], 0, s[60:61]
	global_load_dwordx4 v[206:209], v[206:207], off nt
	s_mov_b32 s60, 0xd4000
	s_mov_b32 s61, 0
	v_lshl_add_u64 v[210:211], v[254:255], 0, s[60:61]
	global_load_dwordx4 v[210:213], v[210:211], off nt
	s_mov_b32 s60, 0x13e000
	s_mov_b32 s61, 0
	v_lshl_add_u64 v[214:215], v[254:255], 0, s[60:61]
	global_load_dwordx4 v[214:217], v[214:215], off nt
	s_mov_b32 s60, 0x350000
	s_mov_b32 s61, 0
	v_lshl_add_u64 v[218:219], v[254:255], 0, s[60:61]
	global_load_dwordx4 v[218:221], v[218:219], off nt
	s_mov_b32 s60, 0x3ba000
	s_mov_b32 s61, 0
	v_lshl_add_u64 v[222:223], v[254:255], 0, s[60:61]
	global_load_dwordx4 v[222:225], v[222:223], off nt
	s_mov_b32 s60, 0x424000
	s_mov_b32 s61, 0
	v_lshl_add_u64 v[226:227], v[254:255], 0, s[60:61]
	global_load_dwordx4 v[226:229], v[226:227], off nt
	s_mov_b32 s60, 0x48e000
	s_mov_b32 s61, 0
	v_lshl_add_u64 v[230:231], v[254:255], 0, s[60:61]
	global_load_dwordx4 v[230:233], v[230:231], off nt
	s_and_b64 vcc, exec, s[4:5]
	s_mov_b32 s50, s12
	s_mov_b32 s28, s14
	s_mov_b64 s[30:31], s[26:27]
	s_mov_b64 s[34:35], s[24:25]
	v_readlane_b32 s56, v244, 4
	v_readlane_b32 s57, v244, 5
	v_readlane_b32 s58, v244, 6
	v_readlane_b32 s59, v244, 7
	s_waitcnt vmcnt(12)
; __device__ __forceinline__ float bflo(unsigned w) { return __uint_as_float(w << 16); }
; __device__ __forceinline__ float bfhi(unsigned w) { return __uint_as_float(w & 0xffff0000u); }
; __device__ __forceinline__ unsigned pk2(float lo, float hi) { unsigned r; asm("v_cvt_pk_bf16_f32 %0, %1, %2" : "=v"(r) : "v"(lo), "v"(hi)); return r; }
; __device__ __forceinline__ float siluf_(float x) { return x * __builtin_amdgcn_rcpf(1.0f + __expf(-x)); }
;     __device__ __forceinline__ void operator()(const f32x4 (&acc)[2][2][4][2], const Unit& u, int wr, int wc, int fr, int fq) const {
;     ...
;         for (int bj = 0; bj < 2; ++bj) { const int col = col0 + bj * HALF;
;             const f32x4 b0 = *(const f32x4*)(bias + col), b1 = *(const f32x4*)(bias + col + 4), s0 = *(const f32x4*)(scale + col), s1 = *(const f32x4*)(scale + col + 4);
; #pragma unroll
;             for (int ai = 0; ai < 2; ++ai)
; #pragma unroll
;                 for (int m = 0; m < 4; ++m) { const int row = row0 + ai * HALF + m * 16;
;                     const u32x4 z = __builtin_nontemporal_load((const u32x4*)(proj + (size_t)row * NPROJ + C_ZP + col));
;                     f32x4 v0 = (acc[ai][bj][m][0] + b0) * s0, v1 = (acc[ai][bj][m][1] + b1) * s1;
;                     v0[0] *= siluf_(bflo(z.x)); v0[1] *= siluf_(bfhi(z.x)); v0[2] *= siluf_(bflo(z.y)); v0[3] *= siluf_(bfhi(z.y));
;                     v1[0] *= siluf_(bflo(z.z)); v1[1] *= siluf_(bfhi(z.z)); v1[2] *= siluf_(bflo(z.w)); v1[3] *= siluf_(bfhi(z.w));
;                     u32x4 w; w.x = pk2(v0[0], v0[1]); w.y = pk2(v0[2], v0[3]); w.z = pk2(v1[0], v1[1]); w.w = pk2(v1[2], v1[3]);
;                     *(u32x4*)(a2 + (size_t)row * 4096 + 2048 + col) = w; } }
	v_pk_add_f32 v[122:123], v[122:123], v[130:131]
	v_pk_add_f32 v[124:125], v[124:125], v[132:133]
	v_lshlrev_b32_e32 v177, 16, v144
	v_and_b32_e32 v144, 0xffff0000, v144
	v_lshlrev_b32_e32 v183, 16, v145
	v_and_b32_e32 v145, 0xffff0000, v145
	v_lshlrev_b32_e32 v191, 16, v146
	v_and_b32_e32 v146, 0xffff0000, v146
	v_lshlrev_b32_e32 v193, 16, v147
	v_and_b32_e32 v147, 0xffff0000, v147
	v_mul_f32_e32 v198, 0xbfb8aa3b, v177
	v_mul_f32_e32 v199, 0xbfb8aa3b, v144
	v_mul_f32_e32 v200, 0xbfb8aa3b, v183
	v_mul_f32_e32 v201, 0xbfb8aa3b, v145
	v_mul_f32_e32 v202, 0xbfb8aa3b, v191
	v_mul_f32_e32 v203, 0xbfb8aa3b, v146
	v_mul_f32_e32 v205, 0xbfb8aa3b, v147
	v_exp_f32_e32 v198, v198
	v_exp_f32_e32 v199, v199
	v_mul_f32_e32 v204, 0xbfb8aa3b, v193
	v_exp_f32_e32 v200, v200
	v_exp_f32_e32 v201, v201
	v_exp_f32_e32 v202, v202
	v_exp_f32_e32 v203, v203
	v_exp_f32_e32 v205, v205
	v_exp_f32_e32 v204, v204
	v_add_f32_e32 v198, 1.0, v198
	v_add_f32_e32 v199, 1.0, v199
	v_add_f32_e32 v200, 1.0, v200
	v_add_f32_e32 v201, 1.0, v201
	v_add_f32_e32 v202, 1.0, v202
	v_add_f32_e32 v203, 1.0, v203
	v_add_f32_e32 v205, 1.0, v205
	v_rcp_f32_e32 v198, v198
	v_rcp_f32_e32 v199, v199
	v_add_f32_e32 v204, 1.0, v204
	v_rcp_f32_e32 v200, v200
	v_rcp_f32_e32 v201, v201
	v_rcp_f32_e32 v202, v202
	v_rcp_f32_e32 v203, v203
	v_rcp_f32_e32 v205, v205
	v_rcp_f32_e32 v204, v204
	v_pk_add_f32 v[126:127], v[126:127], v[134:135]
	v_pk_add_f32 v[120:121], v[120:121], v[128:129]
	v_pk_mul_f32 v[124:125], v[124:125], v[140:141]
	v_mul_f32_e32 v177, v198, v177
	v_mul_f32_e32 v144, v199, v144
	v_pk_mul_f32 v[126:127], v[126:127], v[142:143]
	v_pk_mul_f32 v[122:123], v[122:123], v[138:139]
	v_pk_mul_f32 v[120:121], v[120:121], v[136:137]
	v_mul_f32_e32 v183, v200, v183
	v_mul_f32_e32 v145, v201, v145
	v_mul_f32_e32 v191, v202, v191
	v_mul_f32_e32 v146, v203, v146
	v_mul_f32_e32 v147, v205, v147
	v_mul_f32_e32 v124, v124, v177
	v_mul_f32_e32 v125, v125, v144
	v_mul_f32_e32 v193, v204, v193
	v_mul_f32_e32 v126, v126, v183
	v_mul_f32_e32 v127, v127, v145
	v_mul_f32_e32 v144, v120, v191
	v_mul_f32_e32 v145, v121, v146
	v_mul_f32_e32 v123, v123, v147
	v_cvt_pk_bf16_f32 v120, v124, v125
	v_cvt_pk_bf16_f32 v121, v126, v127
	v_lshl_add_u64 v[124:125], v[194:195], 0, s[8:9]
	v_mul_f32_e32 v146, v122, v193
	v_cvt_pk_bf16_f32 v122, v144, v145
	v_cvt_pk_bf16_f32 v123, v146, v123
	global_store_dwordx4 v[196:197], v[120:123], off
	v_ashrrev_i32_e32 v183, 31, v182
	v_or_b32_e32 v126, 32, v176
	v_lshl_add_u64 v[120:121], v[124:125], 0, v[174:175]
	v_lshlrev_b64 v[122:123], 13, v[182:183]
	v_lshl_add_u64 v[122:123], s[6:7], 0, v[122:123]
	v_pk_add_f32 v[114:115], v[114:115], v[130:131]
	v_mad_i64_i32 v[120:121], s[2:3], v126, s49, v[178:179]
	v_lshl_add_u64 v[122:123], v[122:123], 0, s[10:11]
	v_pk_add_f32 v[118:119], v[118:119], v[134:135]
	v_pk_add_f32 v[116:117], v[116:117], v[132:133]
	v_pk_add_f32 v[112:113], v[112:113], v[128:129]
	v_pk_mul_f32 v[114:115], v[114:115], v[138:139]
	v_lshl_add_u64 v[120:121], v[120:121], 0, s[8:9]
	v_lshl_add_u64 v[194:195], v[122:123], 0, v[174:175]
	v_pk_mul_f32 v[118:119], v[118:119], v[142:143]
	v_pk_mul_f32 v[116:117], v[116:117], v[140:141]
	v_pk_mul_f32 v[112:113], v[112:113], v[136:137]
	v_lshl_add_u64 v[182:183], v[120:121], 0, v[174:175]
	v_pk_add_f32 v[106:107], v[106:107], v[130:131]
	v_pk_add_f32 v[110:111], v[110:111], v[134:135]
	v_pk_add_f32 v[108:109], v[108:109], v[132:133]
	v_pk_add_f32 v[104:105], v[104:105], v[128:129]
	v_pk_mul_f32 v[106:107], v[106:107], v[138:139]
	v_pk_mul_f32 v[110:111], v[110:111], v[142:143]
	v_pk_mul_f32 v[108:109], v[108:109], v[140:141]
	v_pk_mul_f32 v[104:105], v[104:105], v[136:137]
	v_pk_add_f32 v[98:99], v[98:99], v[130:131]
	v_pk_add_f32 v[102:103], v[102:103], v[134:135]
	v_pk_add_f32 v[100:101], v[100:101], v[132:133]
	v_pk_add_f32 v[96:97], v[96:97], v[128:129]
	v_pk_mul_f32 v[98:99], v[98:99], v[138:139]
	v_pk_mul_f32 v[102:103], v[102:103], v[142:143]
	v_pk_mul_f32 v[100:101], v[100:101], v[140:141]
	v_pk_mul_f32 v[96:97], v[96:97], v[136:137]
	v_pk_add_f32 v[90:91], v[90:91], v[130:131]
	v_pk_add_f32 v[94:95], v[94:95], v[134:135]
	v_pk_add_f32 v[92:93], v[92:93], v[132:133]
	v_pk_add_f32 v[88:89], v[88:89], v[128:129]
	v_pk_mul_f32 v[90:91], v[90:91], v[138:139]
	v_pk_mul_f32 v[94:95], v[94:95], v[142:143]
	v_pk_mul_f32 v[92:93], v[92:93], v[140:141]
	v_pk_mul_f32 v[88:89], v[88:89], v[136:137]
	v_pk_add_f32 v[82:83], v[82:83], v[130:131]
	v_pk_add_f32 v[86:87], v[86:87], v[134:135]
	v_pk_add_f32 v[84:85], v[84:85], v[132:133]
	v_pk_add_f32 v[80:81], v[80:81], v[128:129]
	v_pk_mul_f32 v[82:83], v[82:83], v[138:139]
	v_pk_mul_f32 v[86:87], v[86:87], v[142:143]
	v_pk_mul_f32 v[84:85], v[84:85], v[140:141]
	v_pk_mul_f32 v[80:81], v[80:81], v[136:137]
	v_pk_add_f32 v[74:75], v[74:75], v[130:131]
	v_pk_add_f32 v[78:79], v[78:79], v[134:135]
	v_pk_add_f32 v[76:77], v[76:77], v[132:133]
	v_pk_add_f32 v[72:73], v[72:73], v[128:129]
	v_pk_mul_f32 v[74:75], v[74:75], v[138:139]
	v_pk_mul_f32 v[78:79], v[78:79], v[142:143]
	v_pk_mul_f32 v[76:77], v[76:77], v[140:141]
	v_pk_mul_f32 v[72:73], v[72:73], v[136:137]
	v_pk_add_f32 v[66:67], v[66:67], v[130:131]
	v_pk_add_f32 v[70:71], v[70:71], v[134:135]
	v_pk_add_f32 v[68:69], v[68:69], v[132:133]
	v_pk_add_f32 v[64:65], v[64:65], v[128:129]
	v_pk_mul_f32 v[66:67], v[66:67], v[138:139]
	v_pk_mul_f32 v[70:71], v[70:71], v[142:143]
	v_pk_mul_f32 v[68:69], v[68:69], v[140:141]
	v_pk_mul_f32 v[64:65], v[64:65], v[136:137]
	s_waitcnt vmcnt(7)
; __device__ __forceinline__ float bflo(unsigned w) { return __uint_as_float(w << 16); }
; __device__ __forceinline__ float bfhi(unsigned w) { return __uint_as_float(w & 0xffff0000u); }
; __device__ __forceinline__ unsigned pk2(float lo, float hi) { unsigned r; asm("v_cvt_pk_bf16_f32 %0, %1, %2" : "=v"(r) : "v"(lo), "v"(hi)); return r; }
; __device__ __forceinline__ float siluf_(float x) { return x * __builtin_amdgcn_rcpf(1.0f + __expf(-x)); }
;     __device__ __forceinline__ void operator()(const f32x4 (&acc)[2][2][4][2], const Unit& u, int wr, int wc, int fr, int fq) const {
;     ...
;                 for (int m = 0; m < 4; ++m) { const int row = row0 + ai * HALF + m * 16;
;                     const u32x4 z = __builtin_nontemporal_load((const u32x4*)(proj + (size_t)row * NPROJ + C_ZP + col));
;                     f32x4 v0 = (acc[ai][bj][m][0] + b0) * s0, v1 = (acc[ai][bj][m][1] + b1) * s1;
;                     v0[0] *= siluf_(bflo(z.x)); v0[1] *= siluf_(bfhi(z.x)); v0[2] *= siluf_(bflo(z.y)); v0[3] *= siluf_(bfhi(z.y));
;                     v1[0] *= siluf_(bflo(z.z)); v1[1] *= siluf_(bfhi(z.z)); v1[2] *= siluf_(bflo(z.w)); v1[3] *= siluf_(bfhi(z.w));
;                     u32x4 w; w.x = pk2(v0[0], v0[1]); w.y = pk2(v0[2], v0[3]); w.z = pk2(v1[0], v1[1]); w.w = pk2(v1[2], v1[3]);
;                     *(u32x4*)(a2 + (size_t)row * 4096 + 2048 + col) = w; } }
	v_mov_b32_e32 v144, v206
	v_mov_b32_e32 v145, v207
	v_mov_b32_e32 v146, v208
	v_mov_b32_e32 v147, v209
	s_mov_b32 s60, 0x6a100
	s_mov_b32 s61, 0
	v_lshl_add_u64 v[206:207], v[254:255], 0, s[60:61]
	global_load_dwordx4 v[206:209], v[206:207], off nt
	v_lshlrev_b32_e32 v193, 16, v147
	v_and_b32_e32 v147, 0xffff0000, v147
	v_lshlrev_b32_e32 v127, 16, v144
	v_and_b32_e32 v144, 0xffff0000, v144
	v_lshlrev_b32_e32 v177, 16, v145
	v_and_b32_e32 v145, 0xffff0000, v145
	v_lshlrev_b32_e32 v191, 16, v146
	v_and_b32_e32 v146, 0xffff0000, v146
	v_mul_f32_e32 v203, 0xbfb8aa3b, v147
	v_mul_f32_e32 v196, 0xbfb8aa3b, v127
	v_mul_f32_e32 v197, 0xbfb8aa3b, v144
	v_mul_f32_e32 v198, 0xbfb8aa3b, v177
	v_mul_f32_e32 v199, 0xbfb8aa3b, v145
	v_mul_f32_e32 v200, 0xbfb8aa3b, v191
	v_mul_f32_e32 v201, 0xbfb8aa3b, v146
	v_mul_f32_e32 v202, 0xbfb8aa3b, v193
	v_exp_f32_e32 v203, v203
	v_exp_f32_e32 v196, v196
	v_exp_f32_e32 v197, v197
	v_exp_f32_e32 v198, v198
	v_exp_f32_e32 v199, v199
	v_exp_f32_e32 v200, v200
	v_exp_f32_e32 v201, v201
	v_exp_f32_e32 v202, v202
	v_add_f32_e32 v203, 1.0, v203
	v_add_f32_e32 v196, 1.0, v196
	v_add_f32_e32 v197, 1.0, v197
	v_add_f32_e32 v198, 1.0, v198
	v_add_f32_e32 v199, 1.0, v199
	v_add_f32_e32 v200, 1.0, v200
	v_add_f32_e32 v201, 1.0, v201
	v_add_f32_e32 v202, 1.0, v202
	v_rcp_f32_e32 v203, v203
	v_rcp_f32_e32 v196, v196
	v_rcp_f32_e32 v197, v197
	v_rcp_f32_e32 v198, v198
	v_rcp_f32_e32 v199, v199
	v_rcp_f32_e32 v200, v200
	v_rcp_f32_e32 v201, v201
	v_rcp_f32_e32 v202, v202
	v_mul_f32_e32 v147, v203, v147
	v_mul_f32_e32 v127, v196, v127
	v_mul_f32_e32 v144, v197, v144
	v_mul_f32_e32 v177, v198, v177
	v_mul_f32_e32 v145, v199, v145
	v_mul_f32_e32 v191, v200, v191
	v_mul_f32_e32 v146, v201, v146
	v_mul_f32_e32 v193, v202, v193
	v_mul_f32_e32 v115, v115, v147
	v_mul_f32_e32 v116, v116, v127
	v_mul_f32_e32 v117, v117, v144
	v_mul_f32_e32 v118, v118, v177
	v_mul_f32_e32 v119, v119, v145
	v_mul_f32_e32 v127, v112, v191
	v_mul_f32_e32 v144, v113, v146
	v_mul_f32_e32 v145, v114, v193
	v_cvt_pk_bf16_f32 v112, v116, v117
	v_cvt_pk_bf16_f32 v113, v118, v119
	v_cvt_pk_bf16_f32 v114, v127, v144
	v_cvt_pk_bf16_f32 v115, v145, v115
	global_store_dwordx4 v[194:195], v[112:115], off
	v_ashrrev_i32_e32 v127, 31, v126
	v_lshlrev_b64 v[114:115], 13, v[126:127]
	v_or_b32_e32 v144, 48, v176
	v_lshl_add_u64 v[114:115], s[6:7], 0, v[114:115]
	v_mad_i64_i32 v[112:113], s[2:3], v144, s49, v[178:179]
	v_lshl_add_u64 v[114:115], v[114:115], 0, s[10:11]
	v_lshl_add_u64 v[112:113], v[112:113], 0, s[8:9]
	v_lshl_add_u64 v[146:147], v[114:115], 0, v[174:175]
	v_lshl_add_u64 v[126:127], v[112:113], 0, v[174:175]
	s_waitcnt vmcnt(8)
	v_mov_b32_e32 v116, v210
	v_mov_b32_e32 v117, v211
	v_mov_b32_e32 v118, v212
	v_mov_b32_e32 v119, v213
	s_mov_b32 s60, 0xd4100
	s_mov_b32 s61, 0
	v_lshl_add_u64 v[210:211], v[254:255], 0, s[60:61]
	global_load_dwordx4 v[210:213], v[210:211], off nt
	v_lshlrev_b32_e32 v183, 16, v119
	v_and_b32_e32 v119, 0xffff0000, v119
	v_lshlrev_b32_e32 v145, 16, v116
	v_and_b32_e32 v116, 0xffff0000, v116
	v_lshlrev_b32_e32 v177, 16, v117
	v_and_b32_e32 v117, 0xffff0000, v117
	v_lshlrev_b32_e32 v182, 16, v118
	v_and_b32_e32 v118, 0xffff0000, v118
	v_mul_f32_e32 v199, 0xbfb8aa3b, v119
	v_mul_f32_e32 v191, 0xbfb8aa3b, v145
	v_mul_f32_e32 v193, 0xbfb8aa3b, v116
	v_mul_f32_e32 v194, 0xbfb8aa3b, v177
	v_mul_f32_e32 v195, 0xbfb8aa3b, v117
	v_mul_f32_e32 v196, 0xbfb8aa3b, v182
	v_mul_f32_e32 v197, 0xbfb8aa3b, v118
	v_mul_f32_e32 v198, 0xbfb8aa3b, v183
	v_exp_f32_e32 v199, v199
	v_exp_f32_e32 v191, v191
	v_exp_f32_e32 v193, v193
	v_exp_f32_e32 v194, v194
	v_exp_f32_e32 v195, v195
	v_exp_f32_e32 v196, v196
	v_exp_f32_e32 v197, v197
	v_exp_f32_e32 v198, v198
	v_add_f32_e32 v199, 1.0, v199
	v_add_f32_e32 v191, 1.0, v191
	v_add_f32_e32 v193, 1.0, v193
	v_add_f32_e32 v194, 1.0, v194
	v_add_f32_e32 v195, 1.0, v195
	v_add_f32_e32 v196, 1.0, v196
	v_add_f32_e32 v197, 1.0, v197
	v_add_f32_e32 v198, 1.0, v198
	v_rcp_f32_e32 v199, v199
	v_rcp_f32_e32 v191, v191
	v_rcp_f32_e32 v193, v193
	v_rcp_f32_e32 v194, v194
	v_rcp_f32_e32 v195, v195
	v_rcp_f32_e32 v196, v196
	v_rcp_f32_e32 v197, v197
	v_rcp_f32_e32 v198, v198
	v_mul_f32_e32 v119, v199, v119
	v_mul_f32_e32 v145, v191, v145
	v_mul_f32_e32 v116, v193, v116
	v_mul_f32_e32 v177, v194, v177
	v_mul_f32_e32 v117, v195, v117
	v_mul_f32_e32 v182, v196, v182
	v_mul_f32_e32 v118, v197, v118
	v_mul_f32_e32 v183, v198, v183
	v_mul_f32_e32 v107, v107, v119
	v_mul_f32_e32 v108, v108, v145
	v_mul_f32_e32 v109, v109, v116
	v_mul_f32_e32 v110, v110, v177
	v_mul_f32_e32 v111, v111, v117
	v_mul_f32_e32 v116, v104, v182
	v_mul_f32_e32 v117, v105, v118
	v_mul_f32_e32 v118, v106, v183
	v_cvt_pk_bf16_f32 v104, v108, v109
	v_cvt_pk_bf16_f32 v105, v110, v111
	v_cvt_pk_bf16_f32 v106, v116, v117
	v_cvt_pk_bf16_f32 v107, v118, v107
	global_store_dwordx4 v[146:147], v[104:107], off
	v_ashrrev_i32_e32 v145, 31, v144
	v_lshlrev_b64 v[106:107], 13, v[144:145]
	v_add_u32_e32 v116, 0x80, v176
	v_lshl_add_u64 v[106:107], s[6:7], 0, v[106:107]
	v_mad_i64_i32 v[104:105], s[2:3], v116, s49, v[178:179]
	v_lshl_add_u64 v[106:107], v[106:107], 0, s[10:11]
	v_lshl_add_u64 v[104:105], v[104:105], 0, s[8:9]
	v_lshl_add_u64 v[126:127], v[106:107], 0, v[174:175]
	v_lshl_add_u64 v[118:119], v[104:105], 0, v[174:175]
	s_waitcnt vmcnt(9)
; __device__ __forceinline__ float bflo(unsigned w) { return __uint_as_float(w << 16); }
; __device__ __forceinline__ float bfhi(unsigned w) { return __uint_as_float(w & 0xffff0000u); }
; __device__ __forceinline__ unsigned pk2(float lo, float hi) { unsigned r; asm("v_cvt_pk_bf16_f32 %0, %1, %2" : "=v"(r) : "v"(lo), "v"(hi)); return r; }
; __device__ __forceinline__ float siluf_(float x) { return x * __builtin_amdgcn_rcpf(1.0f + __expf(-x)); }
;     __device__ __forceinline__ void operator()(const f32x4 (&acc)[2][2][4][2], const Unit& u, int wr, int wc, int fr, int fq) const {
;     ...
;                 for (int m = 0; m < 4; ++m) { const int row = row0 + ai * HALF + m * 16;
;                     const u32x4 z = __builtin_nontemporal_load((const u32x4*)(proj + (size_t)row * NPROJ + C_ZP + col));
;                     f32x4 v0 = (acc[ai][bj][m][0] + b0) * s0, v1 = (acc[ai][bj][m][1] + b1) * s1;
;                     v0[0] *= siluf_(bflo(z.x)); v0[1] *= siluf_(bfhi(z.x)); v0[2] *= siluf_(bflo(z.y)); v0[3] *= siluf_(bfhi(z.y));
;                     v1[0] *= siluf_(bflo(z.z)); v1[1] *= siluf_(bfhi(z.z)); v1[2] *= siluf_(bflo(z.w)); v1[3] *= siluf_(bfhi(z.w));
;                     u32x4 w; w.x = pk2(v0[0], v0[1]); w.y = pk2(v0[2], v0[3]); w.z = pk2(v1[0], v1[1]); w.w = pk2(v1[2], v1[3]);
;                     *(u32x4*)(a2 + (size_t)row * 4096 + 2048 + col) = w; } }
	v_mov_b32_e32 v108, v214
	v_mov_b32_e32 v109, v215
	v_mov_b32_e32 v110, v216
	v_mov_b32_e32 v111, v217
	s_mov_b32 s60, 0x13e100
	s_mov_b32 s61, 0
	v_lshl_add_u64 v[214:215], v[254:255], 0, s[60:61]
	global_load_dwordx4 v[214:217], v[214:215], off nt
	v_lshlrev_b32_e32 v146, 16, v111
	v_and_b32_e32 v111, 0xffff0000, v111
	v_lshlrev_b32_e32 v117, 16, v108
	v_and_b32_e32 v108, 0xffff0000, v108
	v_lshlrev_b32_e32 v144, 16, v109
	v_and_b32_e32 v109, 0xffff0000, v109
	v_lshlrev_b32_e32 v145, 16, v110
	v_and_b32_e32 v110, 0xffff0000, v110
	v_mul_f32_e32 v195, 0xbfb8aa3b, v111
	v_mul_f32_e32 v147, 0xbfb8aa3b, v117
	v_mul_f32_e32 v177, 0xbfb8aa3b, v108
	v_mul_f32_e32 v182, 0xbfb8aa3b, v144
	v_mul_f32_e32 v183, 0xbfb8aa3b, v109
	v_mul_f32_e32 v191, 0xbfb8aa3b, v145
	v_mul_f32_e32 v193, 0xbfb8aa3b, v110
	v_mul_f32_e32 v194, 0xbfb8aa3b, v146
	v_exp_f32_e32 v195, v195
	v_exp_f32_e32 v147, v147
	v_exp_f32_e32 v177, v177
	v_exp_f32_e32 v182, v182
	v_exp_f32_e32 v183, v183
	v_exp_f32_e32 v191, v191
	v_exp_f32_e32 v193, v193
	v_exp_f32_e32 v194, v194
	v_add_f32_e32 v195, 1.0, v195
	v_add_f32_e32 v147, 1.0, v147
	v_add_f32_e32 v177, 1.0, v177
	v_add_f32_e32 v182, 1.0, v182
	v_add_f32_e32 v183, 1.0, v183
	v_add_f32_e32 v191, 1.0, v191
	v_add_f32_e32 v193, 1.0, v193
	v_add_f32_e32 v194, 1.0, v194
	v_rcp_f32_e32 v195, v195
	v_rcp_f32_e32 v147, v147
	v_rcp_f32_e32 v177, v177
	v_rcp_f32_e32 v182, v182
	v_rcp_f32_e32 v183, v183
	v_rcp_f32_e32 v191, v191
	v_rcp_f32_e32 v193, v193
	v_rcp_f32_e32 v194, v194
	v_mul_f32_e32 v111, v195, v111
	v_mul_f32_e32 v117, v147, v117
	v_mul_f32_e32 v108, v177, v108
	v_mul_f32_e32 v144, v182, v144
	v_mul_f32_e32 v109, v183, v109
	v_mul_f32_e32 v145, v191, v145
	v_mul_f32_e32 v110, v193, v110
	v_mul_f32_e32 v146, v194, v146
	v_mul_f32_e32 v99, v99, v111
	v_mul_f32_e32 v100, v100, v117
	v_mul_f32_e32 v101, v101, v108
	v_mul_f32_e32 v102, v102, v144
	v_mul_f32_e32 v103, v103, v109
	v_mul_f32_e32 v108, v96, v145
	v_mul_f32_e32 v109, v97, v110
	v_mul_f32_e32 v110, v98, v146
	v_cvt_pk_bf16_f32 v96, v100, v101
	v_cvt_pk_bf16_f32 v97, v102, v103
	v_cvt_pk_bf16_f32 v98, v108, v109
	v_cvt_pk_bf16_f32 v99, v110, v99
	global_store_dwordx4 v[126:127], v[96:99], off
	v_ashrrev_i32_e32 v117, 31, v116
	v_lshlrev_b64 v[98:99], 13, v[116:117]
	v_add_u32_e32 v108, 0x90, v176
	v_lshl_add_u64 v[98:99], s[6:7], 0, v[98:99]
	v_mad_i64_i32 v[96:97], s[2:3], v108, s49, v[178:179]
	v_lshl_add_u64 v[98:99], v[98:99], 0, s[10:11]
	v_lshl_add_u64 v[96:97], v[96:97], 0, s[8:9]
	v_lshl_add_u64 v[116:117], v[98:99], 0, v[174:175]
	v_lshl_add_u64 v[110:111], v[96:97], 0, v[174:175]
	s_waitcnt vmcnt(10)
	v_mov_b32_e32 v100, v218
	v_mov_b32_e32 v101, v219
	v_mov_b32_e32 v102, v220
	v_mov_b32_e32 v103, v221
	s_mov_b32 s60, 0x350100
	s_mov_b32 s61, 0
	v_lshl_add_u64 v[218:219], v[254:255], 0, s[60:61]
	global_load_dwordx4 v[218:221], v[218:219], off nt
	v_lshlrev_b32_e32 v126, 16, v103
	v_and_b32_e32 v103, 0xffff0000, v103
	v_lshlrev_b32_e32 v109, 16, v100
	v_and_b32_e32 v100, 0xffff0000, v100
	v_lshlrev_b32_e32 v118, 16, v101
	v_and_b32_e32 v101, 0xffff0000, v101
	v_lshlrev_b32_e32 v119, 16, v102
	v_and_b32_e32 v102, 0xffff0000, v102
	v_mul_f32_e32 v183, 0xbfb8aa3b, v103
	v_mul_f32_e32 v127, 0xbfb8aa3b, v109
	v_mul_f32_e32 v144, 0xbfb8aa3b, v100
	v_mul_f32_e32 v145, 0xbfb8aa3b, v118
	v_mul_f32_e32 v146, 0xbfb8aa3b, v101
	v_mul_f32_e32 v147, 0xbfb8aa3b, v119
	v_mul_f32_e32 v177, 0xbfb8aa3b, v102
	v_mul_f32_e32 v182, 0xbfb8aa3b, v126
	v_exp_f32_e32 v183, v183
	v_exp_f32_e32 v127, v127
	v_exp_f32_e32 v144, v144
	v_exp_f32_e32 v145, v145
	v_exp_f32_e32 v146, v146
	v_exp_f32_e32 v147, v147
	v_exp_f32_e32 v177, v177
	v_exp_f32_e32 v182, v182
	v_add_f32_e32 v183, 1.0, v183
	v_add_f32_e32 v127, 1.0, v127
	v_add_f32_e32 v144, 1.0, v144
	v_add_f32_e32 v145, 1.0, v145
	v_add_f32_e32 v146, 1.0, v146
	v_add_f32_e32 v147, 1.0, v147
	v_add_f32_e32 v177, 1.0, v177
	v_add_f32_e32 v182, 1.0, v182
	v_rcp_f32_e32 v183, v183
	v_rcp_f32_e32 v127, v127
	v_rcp_f32_e32 v144, v144
	v_rcp_f32_e32 v145, v145
	v_rcp_f32_e32 v146, v146
	v_rcp_f32_e32 v147, v147
	v_rcp_f32_e32 v177, v177
	v_rcp_f32_e32 v182, v182
	v_mul_f32_e32 v103, v183, v103
	v_mul_f32_e32 v109, v127, v109
	v_mul_f32_e32 v100, v144, v100
	v_mul_f32_e32 v118, v145, v118
	v_mul_f32_e32 v101, v146, v101
	v_mul_f32_e32 v119, v147, v119
	v_mul_f32_e32 v102, v177, v102
	v_mul_f32_e32 v126, v182, v126
	v_mul_f32_e32 v91, v91, v103
	v_mul_f32_e32 v92, v92, v109
	v_mul_f32_e32 v93, v93, v100
	v_mul_f32_e32 v94, v94, v118
	v_mul_f32_e32 v95, v95, v101
	v_mul_f32_e32 v100, v88, v119
	v_mul_f32_e32 v101, v89, v102
	v_mul_f32_e32 v102, v90, v126
	v_cvt_pk_bf16_f32 v88, v92, v93
	v_cvt_pk_bf16_f32 v89, v94, v95
	v_cvt_pk_bf16_f32 v90, v100, v101
	v_cvt_pk_bf16_f32 v91, v102, v91
	global_store_dwordx4 v[116:117], v[88:91], off
	v_ashrrev_i32_e32 v109, 31, v108
	v_lshlrev_b64 v[90:91], 13, v[108:109]
	v_add_u32_e32 v100, 0xa0, v176
	v_lshl_add_u64 v[90:91], s[6:7], 0, v[90:91]
	v_mad_i64_i32 v[88:89], s[2:3], v100, s49, v[178:179]
	v_lshl_add_u64 v[90:91], v[90:91], 0, s[10:11]
	v_lshl_add_u64 v[88:89], v[88:89], 0, s[8:9]
	v_lshl_add_u64 v[108:109], v[90:91], 0, v[174:175]
	v_lshl_add_u64 v[102:103], v[88:89], 0, v[174:175]
	s_waitcnt vmcnt(11)
; __device__ __forceinline__ float bflo(unsigned w) { return __uint_as_float(w << 16); }
; __device__ __forceinline__ float bfhi(unsigned w) { return __uint_as_float(w & 0xffff0000u); }
; __device__ __forceinline__ unsigned pk2(float lo, float hi) { unsigned r; asm("v_cvt_pk_bf16_f32 %0, %1, %2" : "=v"(r) : "v"(lo), "v"(hi)); return r; }
; __device__ __forceinline__ float siluf_(float x) { return x * __builtin_amdgcn_rcpf(1.0f + __expf(-x)); }
;     __device__ __forceinline__ void operator()(const f32x4 (&acc)[2][2][4][2], const Unit& u, int wr, int wc, int fr, int fq) const {
;     ...
;                 for (int m = 0; m < 4; ++m) { const int row = row0 + ai * HALF + m * 16;
;                     const u32x4 z = __builtin_nontemporal_load((const u32x4*)(proj + (size_t)row * NPROJ + C_ZP + col));
;                     f32x4 v0 = (acc[ai][bj][m][0] + b0) * s0, v1 = (acc[ai][bj][m][1] + b1) * s1;
;                     v0[0] *= siluf_(bflo(z.x)); v0[1] *= siluf_(bfhi(z.x)); v0[2] *= siluf_(bflo(z.y)); v0[3] *= siluf_(bfhi(z.y));
;                     v1[0] *= siluf_(bflo(z.z)); v1[1] *= siluf_(bfhi(z.z)); v1[2] *= siluf_(bflo(z.w)); v1[3] *= siluf_(bfhi(z.w));
;                     u32x4 w; w.x = pk2(v0[0], v0[1]); w.y = pk2(v0[2], v0[3]); w.z = pk2(v1[0], v1[1]); w.w = pk2(v1[2], v1[3]);
;                     *(u32x4*)(a2 + (size_t)row * 4096 + 2048 + col) = w; } }
	v_mov_b32_e32 v92, v222
	v_mov_b32_e32 v93, v223
	v_mov_b32_e32 v94, v224
	v_mov_b32_e32 v95, v225
	s_mov_b32 s60, 0x3ba100
	s_mov_b32 s61, 0
	v_lshl_add_u64 v[222:223], v[254:255], 0, s[60:61]
	global_load_dwordx4 v[222:225], v[222:223], off nt
	v_lshlrev_b32_e32 v116, 16, v95
	v_and_b32_e32 v95, 0xffff0000, v95
	v_lshlrev_b32_e32 v101, 16, v92
	v_and_b32_e32 v92, 0xffff0000, v92
	v_lshlrev_b32_e32 v110, 16, v93
	v_and_b32_e32 v93, 0xffff0000, v93
	v_lshlrev_b32_e32 v111, 16, v94
	v_and_b32_e32 v94, 0xffff0000, v94
	v_mul_f32_e32 v146, 0xbfb8aa3b, v95
	v_mul_f32_e32 v117, 0xbfb8aa3b, v101
	v_mul_f32_e32 v118, 0xbfb8aa3b, v92
	v_mul_f32_e32 v119, 0xbfb8aa3b, v110
	v_mul_f32_e32 v126, 0xbfb8aa3b, v93
	v_mul_f32_e32 v127, 0xbfb8aa3b, v111
	v_mul_f32_e32 v144, 0xbfb8aa3b, v94
	v_mul_f32_e32 v145, 0xbfb8aa3b, v116
	v_exp_f32_e32 v146, v146
	v_exp_f32_e32 v117, v117
	v_exp_f32_e32 v118, v118
	v_exp_f32_e32 v119, v119
	v_exp_f32_e32 v126, v126
	v_exp_f32_e32 v127, v127
	v_exp_f32_e32 v144, v144
	v_exp_f32_e32 v145, v145
	v_add_f32_e32 v146, 1.0, v146
	v_add_f32_e32 v117, 1.0, v117
	v_add_f32_e32 v118, 1.0, v118
	v_add_f32_e32 v119, 1.0, v119
	v_add_f32_e32 v126, 1.0, v126
	v_add_f32_e32 v127, 1.0, v127
	v_add_f32_e32 v144, 1.0, v144
	v_add_f32_e32 v145, 1.0, v145
	v_rcp_f32_e32 v146, v146
	v_rcp_f32_e32 v117, v117
	v_rcp_f32_e32 v118, v118
	v_rcp_f32_e32 v119, v119
	v_rcp_f32_e32 v126, v126
	v_rcp_f32_e32 v127, v127
	v_rcp_f32_e32 v144, v144
	v_rcp_f32_e32 v145, v145
	v_mul_f32_e32 v95, v146, v95
	v_mul_f32_e32 v101, v117, v101
	v_mul_f32_e32 v92, v118, v92
	v_mul_f32_e32 v110, v119, v110
	v_mul_f32_e32 v93, v126, v93
	v_mul_f32_e32 v111, v127, v111
	v_mul_f32_e32 v94, v144, v94
	v_mul_f32_e32 v116, v145, v116
	v_mul_f32_e32 v83, v83, v95
	v_mul_f32_e32 v84, v84, v101
	v_mul_f32_e32 v85, v85, v92
	v_mul_f32_e32 v86, v86, v110
	v_mul_f32_e32 v87, v87, v93
	v_mul_f32_e32 v92, v80, v111
	v_mul_f32_e32 v93, v81, v94
	v_mul_f32_e32 v94, v82, v116
	v_cvt_pk_bf16_f32 v80, v84, v85
	v_cvt_pk_bf16_f32 v81, v86, v87
	v_cvt_pk_bf16_f32 v82, v92, v93
	v_cvt_pk_bf16_f32 v83, v94, v83
	global_store_dwordx4 v[108:109], v[80:83], off
	v_ashrrev_i32_e32 v101, 31, v100
	v_lshlrev_b64 v[84:85], 13, v[100:101]
	v_add_u32_e32 v80, 0xb0, v176
	v_lshl_add_u64 v[84:85], s[6:7], 0, v[84:85]
	v_mad_i64_i32 v[82:83], s[2:3], v80, s49, v[178:179]
	v_lshl_add_u64 v[84:85], v[84:85], 0, s[10:11]
	v_lshl_add_u64 v[82:83], v[82:83], 0, s[8:9]
	v_lshl_add_u64 v[100:101], v[84:85], 0, v[174:175]
	v_lshl_add_u64 v[86:87], v[82:83], 0, v[174:175]
	s_waitcnt vmcnt(12)
	v_mov_b32_e32 v92, v226
	v_mov_b32_e32 v93, v227
	v_mov_b32_e32 v94, v228
	v_mov_b32_e32 v95, v229
	s_mov_b32 s60, 0x424100
	s_mov_b32 s61, 0
	v_lshl_add_u64 v[226:227], v[254:255], 0, s[60:61]
	global_load_dwordx4 v[226:229], v[226:227], off nt
	v_lshlrev_b32_e32 v108, 16, v95
	v_and_b32_e32 v95, 0xffff0000, v95
	v_lshlrev_b32_e32 v81, 16, v92
	v_and_b32_e32 v92, 0xffff0000, v92
	v_lshlrev_b32_e32 v102, 16, v93
	v_and_b32_e32 v93, 0xffff0000, v93
	v_lshlrev_b32_e32 v103, 16, v94
	v_and_b32_e32 v94, 0xffff0000, v94
	v_mul_f32_e32 v126, 0xbfb8aa3b, v95
	v_mul_f32_e32 v109, 0xbfb8aa3b, v81
	v_mul_f32_e32 v110, 0xbfb8aa3b, v92
	v_mul_f32_e32 v111, 0xbfb8aa3b, v102
	v_mul_f32_e32 v116, 0xbfb8aa3b, v93
	v_mul_f32_e32 v117, 0xbfb8aa3b, v103
	v_mul_f32_e32 v118, 0xbfb8aa3b, v94
	v_mul_f32_e32 v119, 0xbfb8aa3b, v108
	v_exp_f32_e32 v126, v126
	v_exp_f32_e32 v109, v109
	v_exp_f32_e32 v110, v110
	v_exp_f32_e32 v111, v111
	v_exp_f32_e32 v116, v116
	v_exp_f32_e32 v117, v117
	v_exp_f32_e32 v118, v118
	v_exp_f32_e32 v119, v119
	v_add_f32_e32 v126, 1.0, v126
	v_add_f32_e32 v109, 1.0, v109
	v_add_f32_e32 v110, 1.0, v110
	v_add_f32_e32 v111, 1.0, v111
	v_add_f32_e32 v116, 1.0, v116
	v_add_f32_e32 v117, 1.0, v117
	v_add_f32_e32 v118, 1.0, v118
	v_add_f32_e32 v119, 1.0, v119
	v_rcp_f32_e32 v126, v126
	v_rcp_f32_e32 v109, v109
	v_rcp_f32_e32 v110, v110
	v_rcp_f32_e32 v111, v111
	v_rcp_f32_e32 v116, v116
	v_rcp_f32_e32 v117, v117
	v_rcp_f32_e32 v118, v118
	v_rcp_f32_e32 v119, v119
	v_mul_f32_e32 v95, v126, v95
	v_mul_f32_e32 v81, v109, v81
	v_mul_f32_e32 v92, v110, v92
	v_mul_f32_e32 v102, v111, v102
	v_mul_f32_e32 v93, v116, v93
	v_mul_f32_e32 v103, v117, v103
	v_mul_f32_e32 v94, v118, v94
	v_mul_f32_e32 v108, v119, v108
	v_mul_f32_e32 v75, v75, v95
	v_mul_f32_e32 v76, v76, v81
	v_mul_f32_e32 v77, v77, v92
	v_mul_f32_e32 v78, v78, v102
	v_mul_f32_e32 v79, v79, v93
	v_mul_f32_e32 v81, v72, v103
	v_mul_f32_e32 v92, v73, v94
	v_mul_f32_e32 v93, v74, v108
	v_cvt_pk_bf16_f32 v72, v76, v77
	v_cvt_pk_bf16_f32 v73, v78, v79
	v_cvt_pk_bf16_f32 v74, v81, v92
	v_cvt_pk_bf16_f32 v75, v93, v75
	global_store_dwordx4 v[100:101], v[72:75], off
	v_ashrrev_i32_e32 v81, 31, v80
	v_lshlrev_b64 v[76:77], 13, v[80:81]
	v_lshl_add_u64 v[76:77], s[6:7], 0, v[76:77]
	v_lshl_add_u64 v[80:81], v[76:77], 0, s[10:11]
	v_lshl_add_u64 v[76:77], v[80:81], 0, v[174:175]
	v_and_b32_e32 v109, 0xffff0000, v151
	v_lshlrev_b32_e32 v108, 16, v151
	s_waitcnt vmcnt(13)
; __device__ __forceinline__ float bflo(unsigned w) { return __uint_as_float(w << 16); }
; __device__ __forceinline__ float bfhi(unsigned w) { return __uint_as_float(w & 0xffff0000u); }
; __device__ __forceinline__ unsigned pk2(float lo, float hi) { unsigned r; asm("v_cvt_pk_bf16_f32 %0, %1, %2" : "=v"(r) : "v"(lo), "v"(hi)); return r; }
; __device__ __forceinline__ float siluf_(float x) { return x * __builtin_amdgcn_rcpf(1.0f + __expf(-x)); }
;     __device__ __forceinline__ void operator()(const f32x4 (&acc)[2][2][4][2], const Unit& u, int wr, int wc, int fr, int fq) const {
;     ...
;         for (int bj = 0; bj < 2; ++bj) { const int col = col0 + bj * HALF;
;             const f32x4 b0 = *(const f32x4*)(bias + col), b1 = *(const f32x4*)(bias + col + 4), s0 = *(const f32x4*)(scale + col), s1 = *(const f32x4*)(scale + col + 4);
; #pragma unroll
;             for (int ai = 0; ai < 2; ++ai)
; #pragma unroll
;                 for (int m = 0; m < 4; ++m) { const int row = row0 + ai * HALF + m * 16;
;                     const u32x4 z = __builtin_nontemporal_load((const u32x4*)(proj + (size_t)row * NPROJ + C_ZP + col));
;                     f32x4 v0 = (acc[ai][bj][m][0] + b0) * s0, v1 = (acc[ai][bj][m][1] + b1) * s1;
;                     v0[0] *= siluf_(bflo(z.x)); v0[1] *= siluf_(bfhi(z.x)); v0[2] *= siluf_(bflo(z.y)); v0[3] *= siluf_(bfhi(z.y));
;                     v1[0] *= siluf_(bflo(z.z)); v1[1] *= siluf_(bfhi(z.z)); v1[2] *= siluf_(bflo(z.w)); v1[3] *= siluf_(bfhi(z.w));
;                     u32x4 w; w.x = pk2(v0[0], v0[1]); w.y = pk2(v0[2], v0[3]); w.z = pk2(v1[0], v1[1]); w.w = pk2(v1[2], v1[3]);
;                     *(u32x4*)(a2 + (size_t)row * 4096 + 2048 + col) = w; } }
	v_mov_b32_e32 v72, v230
	v_mov_b32_e32 v73, v231
	v_mov_b32_e32 v74, v232
	v_mov_b32_e32 v75, v233
	s_mov_b32 s60, 0x48e100
	s_mov_b32 s61, 0
	v_lshl_add_u64 v[230:231], v[254:255], 0, s[60:61]
	global_load_dwordx4 v[230:233], v[230:231], off nt
	v_lshlrev_b32_e32 v87, 16, v75
	v_and_b32_e32 v75, 0xffff0000, v75
	v_lshlrev_b32_e32 v78, 16, v72
	v_and_b32_e32 v72, 0xffff0000, v72
	v_lshlrev_b32_e32 v79, 16, v73
	v_and_b32_e32 v73, 0xffff0000, v73
	v_lshlrev_b32_e32 v86, 16, v74
	v_and_b32_e32 v74, 0xffff0000, v74
	v_mul_f32_e32 v103, 0xbfb8aa3b, v75
	v_mul_f32_e32 v92, 0xbfb8aa3b, v78
	v_mul_f32_e32 v93, 0xbfb8aa3b, v72
	v_mul_f32_e32 v94, 0xbfb8aa3b, v79
	v_mul_f32_e32 v95, 0xbfb8aa3b, v73
	v_mul_f32_e32 v100, 0xbfb8aa3b, v86
	v_mul_f32_e32 v101, 0xbfb8aa3b, v74
	v_mul_f32_e32 v102, 0xbfb8aa3b, v87
	v_exp_f32_e32 v103, v103
	v_exp_f32_e32 v92, v92
	v_exp_f32_e32 v93, v93
	v_exp_f32_e32 v94, v94
	v_exp_f32_e32 v95, v95
	v_exp_f32_e32 v100, v100
	v_exp_f32_e32 v101, v101
	v_exp_f32_e32 v102, v102
	v_add_f32_e32 v103, 1.0, v103
	v_add_f32_e32 v92, 1.0, v92
	v_add_f32_e32 v93, 1.0, v93
	v_add_f32_e32 v94, 1.0, v94
	v_add_f32_e32 v95, 1.0, v95
	v_add_f32_e32 v100, 1.0, v100
	v_add_f32_e32 v101, 1.0, v101
	v_add_f32_e32 v102, 1.0, v102
	v_rcp_f32_e32 v103, v103
	v_rcp_f32_e32 v92, v92
	v_rcp_f32_e32 v93, v93
	v_rcp_f32_e32 v94, v94
	v_rcp_f32_e32 v95, v95
	v_rcp_f32_e32 v100, v100
	v_rcp_f32_e32 v101, v101
	v_rcp_f32_e32 v102, v102
	v_mul_f32_e32 v75, v103, v75
	v_mul_f32_e32 v78, v92, v78
	v_mul_f32_e32 v72, v93, v72
	v_mul_f32_e32 v79, v94, v79
	v_mul_f32_e32 v73, v95, v73
	v_mul_f32_e32 v86, v100, v86
	v_mul_f32_e32 v74, v101, v74
	v_mul_f32_e32 v87, v102, v87
	v_mul_f32_e32 v67, v67, v75
	v_mul_f32_e32 v68, v68, v78
	v_mul_f32_e32 v69, v69, v72
	v_mul_f32_e32 v70, v70, v79
	v_mul_f32_e32 v71, v71, v73
	v_mul_f32_e32 v72, v64, v86
	v_mul_f32_e32 v73, v65, v74
	v_mul_f32_e32 v74, v66, v87
	v_cvt_pk_bf16_f32 v64, v68, v69
	v_cvt_pk_bf16_f32 v65, v70, v71
	v_cvt_pk_bf16_f32 v66, v72, v73
	v_cvt_pk_bf16_f32 v67, v74, v67
	global_store_dwordx4 v[76:77], v[64:67], off
	v_mov_b32_e32 v76, v234
	v_mov_b32_e32 v77, v235
	v_mov_b32_e32 v78, v236
	v_mov_b32_e32 v79, v237
	s_nop 0
	v_mov_b32_e32 v72, v238
	v_mov_b32_e32 v73, v239
	v_mov_b32_e32 v74, v240
	v_mov_b32_e32 v75, v241
	v_mov_b32_e32 v68, v246
	v_mov_b32_e32 v69, v247
	v_mov_b32_e32 v70, v248
	v_mov_b32_e32 v71, v249
	v_mov_b32_e32 v64, v250
	v_mov_b32_e32 v65, v251
	v_mov_b32_e32 v66, v252
	v_mov_b32_e32 v67, v253
	v_lshl_add_u64 v[86:87], v[124:125], 0, v[168:169]
	v_lshlrev_b32_e32 v94, 16, v148
	v_and_b32_e32 v95, 0xffff0000, v148
	v_lshlrev_b32_e32 v100, 16, v149
	v_and_b32_e32 v101, 0xffff0000, v149
	v_lshlrev_b32_e32 v102, 16, v150
	v_and_b32_e32 v103, 0xffff0000, v150
	v_mul_f32_e32 v125, 0xbfb8aa3b, v109
	v_mul_f32_e32 v110, 0xbfb8aa3b, v94
	v_mul_f32_e32 v111, 0xbfb8aa3b, v95
	v_mul_f32_e32 v116, 0xbfb8aa3b, v100
	v_mul_f32_e32 v117, 0xbfb8aa3b, v101
	v_mul_f32_e32 v118, 0xbfb8aa3b, v102
	v_mul_f32_e32 v119, 0xbfb8aa3b, v103
	v_mul_f32_e32 v124, 0xbfb8aa3b, v108
	v_exp_f32_e32 v125, v125
	v_exp_f32_e32 v110, v110
	v_exp_f32_e32 v111, v111
	v_exp_f32_e32 v116, v116
	v_exp_f32_e32 v117, v117
	v_exp_f32_e32 v118, v118
	v_exp_f32_e32 v119, v119
	v_exp_f32_e32 v124, v124
	v_add_f32_e32 v125, 1.0, v125
	v_add_f32_e32 v110, 1.0, v110
	v_add_f32_e32 v111, 1.0, v111
	v_add_f32_e32 v116, 1.0, v116
	v_add_f32_e32 v117, 1.0, v117
	v_add_f32_e32 v118, 1.0, v118
	v_add_f32_e32 v119, 1.0, v119
	v_add_f32_e32 v124, 1.0, v124
	v_rcp_f32_e32 v125, v125
	v_rcp_f32_e32 v110, v110
	v_rcp_f32_e32 v111, v111
	v_rcp_f32_e32 v116, v116
	v_rcp_f32_e32 v117, v117
	v_rcp_f32_e32 v118, v118
	v_rcp_f32_e32 v119, v119
	v_rcp_f32_e32 v124, v124
	v_mul_f32_e32 v109, v125, v109
	v_lshl_add_u64 v[92:93], v[180:181], 0, v[168:169]
	v_mul_f32_e32 v94, v110, v94
	v_mul_f32_e32 v95, v111, v95
	v_mul_f32_e32 v100, v116, v100
	v_mul_f32_e32 v101, v117, v101
	v_mul_f32_e32 v102, v118, v102
	v_mul_f32_e32 v103, v119, v103
	v_mul_f32_e32 v108, v124, v108
	s_nop 0
	v_pk_add_f32 v[62:63], v[62:63], v[78:79]
	v_pk_add_f32 v[58:59], v[58:59], v[74:75]
	v_pk_add_f32 v[60:61], v[60:61], v[76:77]
	v_pk_add_f32 v[56:57], v[56:57], v[72:73]
	v_pk_mul_f32 v[58:59], v[58:59], v[66:67]
	v_pk_mul_f32 v[62:63], v[62:63], v[70:71]
	v_pk_mul_f32 v[60:61], v[60:61], v[68:69]
	v_pk_mul_f32 v[56:57], v[56:57], v[64:65]
	v_mul_f32_e32 v59, v59, v109
	v_mul_f32_e32 v60, v60, v94
	v_mul_f32_e32 v61, v61, v95
	v_mul_f32_e32 v62, v62, v100
	v_mul_f32_e32 v63, v63, v101
	v_mul_f32_e32 v94, v56, v102
	v_mul_f32_e32 v95, v57, v103
	v_mul_f32_e32 v100, v58, v108
	v_cvt_pk_bf16_f32 v56, v60, v61
	v_cvt_pk_bf16_f32 v57, v62, v63
	v_cvt_pk_bf16_f32 v58, v94, v95
	v_cvt_pk_bf16_f32 v59, v100, v59
	global_store_dwordx4 v[92:93], v[56:59], off
	v_pk_add_f32 v[50:51], v[50:51], v[74:75]
	v_pk_add_f32 v[54:55], v[54:55], v[78:79]
	v_pk_add_f32 v[52:53], v[52:53], v[76:77]
	v_pk_add_f32 v[48:49], v[48:49], v[72:73]
	v_pk_mul_f32 v[50:51], v[50:51], v[66:67]
	v_lshl_add_u64 v[62:63], v[122:123], 0, v[168:169]
	v_pk_mul_f32 v[54:55], v[54:55], v[70:71]
	v_pk_mul_f32 v[52:53], v[52:53], v[68:69]
	v_pk_mul_f32 v[48:49], v[48:49], v[64:65]
	v_lshl_add_u64 v[60:61], v[120:121], 0, v[168:169]
	v_pk_add_f32 v[42:43], v[42:43], v[74:75]
	v_pk_add_f32 v[46:47], v[46:47], v[78:79]
	v_pk_add_f32 v[44:45], v[44:45], v[76:77]
	v_pk_add_f32 v[40:41], v[40:41], v[72:73]
	v_pk_mul_f32 v[42:43], v[42:43], v[66:67]
	v_pk_mul_f32 v[46:47], v[46:47], v[70:71]
	v_pk_mul_f32 v[44:45], v[44:45], v[68:69]
	v_pk_mul_f32 v[40:41], v[40:41], v[64:65]
	v_pk_add_f32 v[34:35], v[34:35], v[74:75]
; __device__ __forceinline__ float bflo(unsigned w) { return __uint_as_float(w << 16); }
; __device__ __forceinline__ float bfhi(unsigned w) { return __uint_as_float(w & 0xffff0000u); }
; __device__ __forceinline__ unsigned pk2(float lo, float hi) { unsigned r; asm("v_cvt_pk_bf16_f32 %0, %1, %2" : "=v"(r) : "v"(lo), "v"(hi)); return r; }
; __device__ __forceinline__ float siluf_(float x) { return x * __builtin_amdgcn_rcpf(1.0f + __expf(-x)); }
;     __device__ __forceinline__ void operator()(const f32x4 (&acc)[2][2][4][2], const Unit& u, int wr, int wc, int fr, int fq) const {
;     ...
;         for (int bj = 0; bj < 2; ++bj) { const int col = col0 + bj * HALF;
;             const f32x4 b0 = *(const f32x4*)(bias + col), b1 = *(const f32x4*)(bias + col + 4), s0 = *(const f32x4*)(scale + col), s1 = *(const f32x4*)(scale + col + 4);
; #pragma unroll
;             for (int ai = 0; ai < 2; ++ai)
; #pragma unroll
;                 for (int m = 0; m < 4; ++m) { const int row = row0 + ai * HALF + m * 16;
;                     const u32x4 z = __builtin_nontemporal_load((const u32x4*)(proj + (size_t)row * NPROJ + C_ZP + col));
;                     f32x4 v0 = (acc[ai][bj][m][0] + b0) * s0, v1 = (acc[ai][bj][m][1] + b1) * s1;
;                     v0[0] *= siluf_(bflo(z.x)); v0[1] *= siluf_(bfhi(z.x)); v0[2] *= siluf_(bflo(z.y)); v0[3] *= siluf_(bfhi(z.y));
;                     v1[0] *= siluf_(bflo(z.z)); v1[1] *= siluf_(bfhi(z.z)); v1[2] *= siluf_(bflo(z.w)); v1[3] *= siluf_(bfhi(z.w));
;                     u32x4 w; w.x = pk2(v0[0], v0[1]); w.y = pk2(v0[2], v0[3]); w.z = pk2(v1[0], v1[1]); w.w = pk2(v1[2], v1[3]);
;                     *(u32x4*)(a2 + (size_t)row * 4096 + 2048 + col) = w; } }
	v_pk_add_f32 v[38:39], v[38:39], v[78:79]
	v_pk_add_f32 v[36:37], v[36:37], v[76:77]
	v_pk_add_f32 v[32:33], v[32:33], v[72:73]
	v_pk_mul_f32 v[34:35], v[34:35], v[66:67]
	v_pk_mul_f32 v[38:39], v[38:39], v[70:71]
	v_pk_mul_f32 v[36:37], v[36:37], v[68:69]
	v_pk_mul_f32 v[32:33], v[32:33], v[64:65]
	v_pk_add_f32 v[26:27], v[26:27], v[74:75]
	v_pk_add_f32 v[30:31], v[30:31], v[78:79]
	v_pk_add_f32 v[28:29], v[28:29], v[76:77]
	v_pk_add_f32 v[24:25], v[24:25], v[72:73]
	v_pk_mul_f32 v[26:27], v[26:27], v[66:67]
	v_pk_mul_f32 v[30:31], v[30:31], v[70:71]
	v_pk_mul_f32 v[28:29], v[28:29], v[68:69]
	v_pk_mul_f32 v[24:25], v[24:25], v[64:65]
	v_pk_add_f32 v[18:19], v[18:19], v[74:75]
	v_pk_add_f32 v[22:23], v[22:23], v[78:79]
	v_pk_add_f32 v[20:21], v[20:21], v[76:77]
	v_pk_add_f32 v[16:17], v[16:17], v[72:73]
	v_pk_mul_f32 v[18:19], v[18:19], v[66:67]
	v_pk_mul_f32 v[22:23], v[22:23], v[70:71]
	v_pk_mul_f32 v[20:21], v[20:21], v[68:69]
	v_pk_mul_f32 v[16:17], v[16:17], v[64:65]
	v_pk_add_f32 v[10:11], v[10:11], v[74:75]
	v_pk_add_f32 v[14:15], v[14:15], v[78:79]
	v_pk_add_f32 v[12:13], v[12:13], v[76:77]
	v_pk_add_f32 v[8:9], v[8:9], v[72:73]
	v_pk_mul_f32 v[10:11], v[10:11], v[66:67]
	v_pk_mul_f32 v[14:15], v[14:15], v[70:71]
	v_pk_mul_f32 v[12:13], v[12:13], v[68:69]
	v_pk_mul_f32 v[8:9], v[8:9], v[64:65]
	v_pk_add_f32 v[2:3], v[2:3], v[74:75]
	v_pk_add_f32 v[6:7], v[6:7], v[78:79]
	v_pk_add_f32 v[4:5], v[4:5], v[76:77]
	v_pk_add_f32 v[0:1], v[0:1], v[72:73]
	v_pk_mul_f32 v[2:3], v[2:3], v[66:67]
	v_pk_mul_f32 v[6:7], v[6:7], v[70:71]
	v_pk_mul_f32 v[4:5], v[4:5], v[68:69]
	v_pk_mul_f32 v[0:1], v[0:1], v[64:65]
	s_waitcnt vmcnt(14)
	v_mov_b32_e32 v56, v206
	v_mov_b32_e32 v57, v207
	v_mov_b32_e32 v58, v208
	v_mov_b32_e32 v59, v209
	v_lshlrev_b32_e32 v93, 16, v59
	v_and_b32_e32 v59, 0xffff0000, v59
	v_lshlrev_b32_e32 v86, 16, v56
	v_and_b32_e32 v56, 0xffff0000, v56
	v_lshlrev_b32_e32 v87, 16, v57
	v_and_b32_e32 v57, 0xffff0000, v57
	v_lshlrev_b32_e32 v92, 16, v58
	v_and_b32_e32 v58, 0xffff0000, v58
	v_mul_f32_e32 v109, 0xbfb8aa3b, v59
	v_mul_f32_e32 v94, 0xbfb8aa3b, v86
	v_mul_f32_e32 v95, 0xbfb8aa3b, v56
	v_mul_f32_e32 v100, 0xbfb8aa3b, v87
	v_mul_f32_e32 v101, 0xbfb8aa3b, v57
	v_mul_f32_e32 v102, 0xbfb8aa3b, v92
	v_mul_f32_e32 v103, 0xbfb8aa3b, v58
	v_mul_f32_e32 v108, 0xbfb8aa3b, v93
	v_exp_f32_e32 v109, v109
	v_exp_f32_e32 v94, v94
	v_exp_f32_e32 v95, v95
	v_exp_f32_e32 v100, v100
	v_exp_f32_e32 v101, v101
	v_exp_f32_e32 v102, v102
	v_exp_f32_e32 v103, v103
	v_exp_f32_e32 v108, v108
	v_add_f32_e32 v109, 1.0, v109
	v_add_f32_e32 v94, 1.0, v94
	v_add_f32_e32 v95, 1.0, v95
	v_add_f32_e32 v100, 1.0, v100
	v_add_f32_e32 v101, 1.0, v101
	v_add_f32_e32 v102, 1.0, v102
	v_add_f32_e32 v103, 1.0, v103
	v_add_f32_e32 v108, 1.0, v108
	v_rcp_f32_e32 v109, v109
	v_rcp_f32_e32 v94, v94
	v_rcp_f32_e32 v95, v95
	v_rcp_f32_e32 v100, v100
	v_rcp_f32_e32 v101, v101
	v_rcp_f32_e32 v102, v102
	v_rcp_f32_e32 v103, v103
	v_rcp_f32_e32 v108, v108
	v_mul_f32_e32 v59, v109, v59
	v_mul_f32_e32 v86, v94, v86
	v_mul_f32_e32 v56, v95, v56
	v_mul_f32_e32 v87, v100, v87
	v_mul_f32_e32 v57, v101, v57
	v_mul_f32_e32 v92, v102, v92
	v_mul_f32_e32 v58, v103, v58
	v_mul_f32_e32 v93, v108, v93
	v_mul_f32_e32 v51, v51, v59
	v_mul_f32_e32 v52, v52, v86
	v_mul_f32_e32 v53, v53, v56
	v_mul_f32_e32 v54, v54, v87
	v_mul_f32_e32 v55, v55, v57
	v_mul_f32_e32 v56, v48, v92
	v_mul_f32_e32 v57, v49, v58
	v_mul_f32_e32 v58, v50, v93
	v_cvt_pk_bf16_f32 v48, v52, v53
	v_cvt_pk_bf16_f32 v49, v54, v55
	v_cvt_pk_bf16_f32 v50, v56, v57
	v_cvt_pk_bf16_f32 v51, v58, v51
	global_store_dwordx4 v[62:63], v[48:51], off
	v_lshl_add_u64 v[54:55], v[114:115], 0, v[168:169]
	v_lshl_add_u64 v[52:53], v[112:113], 0, v[168:169]
	s_waitcnt vmcnt(13)
	v_mov_b32_e32 v48, v210
	v_mov_b32_e32 v49, v211
	v_mov_b32_e32 v50, v212
	v_mov_b32_e32 v51, v213
	v_lshlrev_b32_e32 v59, 16, v51
	v_and_b32_e32 v51, 0xffff0000, v51
	v_lshlrev_b32_e32 v56, 16, v48
	v_and_b32_e32 v48, 0xffff0000, v48
	v_lshlrev_b32_e32 v57, 16, v49
	v_and_b32_e32 v49, 0xffff0000, v49
	v_lshlrev_b32_e32 v58, 16, v50
	v_and_b32_e32 v50, 0xffff0000, v50
	v_mul_f32_e32 v93, 0xbfb8aa3b, v51
	v_mul_f32_e32 v60, 0xbfb8aa3b, v56
	v_mul_f32_e32 v61, 0xbfb8aa3b, v48
	v_mul_f32_e32 v62, 0xbfb8aa3b, v57
	v_mul_f32_e32 v63, 0xbfb8aa3b, v49
	v_mul_f32_e32 v86, 0xbfb8aa3b, v58
	v_mul_f32_e32 v87, 0xbfb8aa3b, v50
	v_mul_f32_e32 v92, 0xbfb8aa3b, v59
	v_exp_f32_e32 v93, v93
	v_exp_f32_e32 v60, v60
	v_exp_f32_e32 v61, v61
	v_exp_f32_e32 v62, v62
	v_exp_f32_e32 v63, v63
	v_exp_f32_e32 v86, v86
	v_exp_f32_e32 v87, v87
	v_exp_f32_e32 v92, v92
	v_add_f32_e32 v93, 1.0, v93
	v_add_f32_e32 v60, 1.0, v60
	v_add_f32_e32 v61, 1.0, v61
	v_add_f32_e32 v62, 1.0, v62
	v_add_f32_e32 v63, 1.0, v63
	v_add_f32_e32 v86, 1.0, v86
	v_add_f32_e32 v87, 1.0, v87
	v_add_f32_e32 v92, 1.0, v92
	v_rcp_f32_e32 v93, v93
	v_rcp_f32_e32 v60, v60
	v_rcp_f32_e32 v61, v61
	v_rcp_f32_e32 v62, v62
	v_rcp_f32_e32 v63, v63
	v_rcp_f32_e32 v86, v86
	v_rcp_f32_e32 v87, v87
	v_rcp_f32_e32 v92, v92
	v_mul_f32_e32 v51, v93, v51
	v_mul_f32_e32 v56, v60, v56
	v_mul_f32_e32 v48, v61, v48
	v_mul_f32_e32 v57, v62, v57
	v_mul_f32_e32 v49, v63, v49
	v_mul_f32_e32 v58, v86, v58
	v_mul_f32_e32 v50, v87, v50
	v_mul_f32_e32 v59, v92, v59
	v_mul_f32_e32 v43, v43, v51
	v_mul_f32_e32 v44, v44, v56
	v_mul_f32_e32 v45, v45, v48
	v_mul_f32_e32 v46, v46, v57
	v_mul_f32_e32 v47, v47, v49
	v_mul_f32_e32 v48, v40, v58
	v_mul_f32_e32 v49, v41, v50
	v_mul_f32_e32 v50, v42, v59
	v_cvt_pk_bf16_f32 v40, v44, v45
	v_cvt_pk_bf16_f32 v41, v46, v47
	v_cvt_pk_bf16_f32 v42, v48, v49
	v_cvt_pk_bf16_f32 v43, v50, v43
	global_store_dwordx4 v[54:55], v[40:43], off
	v_lshl_add_u64 v[46:47], v[106:107], 0, v[168:169]
	v_lshl_add_u64 v[44:45], v[104:105], 0, v[168:169]
	s_waitcnt vmcnt(12)
; __device__ __forceinline__ float bflo(unsigned w) { return __uint_as_float(w << 16); }
; __device__ __forceinline__ float bfhi(unsigned w) { return __uint_as_float(w & 0xffff0000u); }
; __device__ __forceinline__ unsigned pk2(float lo, float hi) { unsigned r; asm("v_cvt_pk_bf16_f32 %0, %1, %2" : "=v"(r) : "v"(lo), "v"(hi)); return r; }
; __device__ __forceinline__ float siluf_(float x) { return x * __builtin_amdgcn_rcpf(1.0f + __expf(-x)); }
;     __device__ __forceinline__ void operator()(const f32x4 (&acc)[2][2][4][2], const Unit& u, int wr, int wc, int fr, int fq) const {
;     ...
;         for (int bj = 0; bj < 2; ++bj) { const int col = col0 + bj * HALF;
;             const f32x4 b0 = *(const f32x4*)(bias + col), b1 = *(const f32x4*)(bias + col + 4), s0 = *(const f32x4*)(scale + col), s1 = *(const f32x4*)(scale + col + 4);
; #pragma unroll
;             for (int ai = 0; ai < 2; ++ai)
; #pragma unroll
;                 for (int m = 0; m < 4; ++m) { const int row = row0 + ai * HALF + m * 16;
;                     const u32x4 z = __builtin_nontemporal_load((const u32x4*)(proj + (size_t)row * NPROJ + C_ZP + col));
;                     f32x4 v0 = (acc[ai][bj][m][0] + b0) * s0, v1 = (acc[ai][bj][m][1] + b1) * s1;
;                     v0[0] *= siluf_(bflo(z.x)); v0[1] *= siluf_(bfhi(z.x)); v0[2] *= siluf_(bflo(z.y)); v0[3] *= siluf_(bfhi(z.y));
;                     v1[0] *= siluf_(bflo(z.z)); v1[1] *= siluf_(bfhi(z.z)); v1[2] *= siluf_(bflo(z.w)); v1[3] *= siluf_(bfhi(z.w));
;                     u32x4 w; w.x = pk2(v0[0], v0[1]); w.y = pk2(v0[2], v0[3]); w.z = pk2(v1[0], v1[1]); w.w = pk2(v1[2], v1[3]);
;                     *(u32x4*)(a2 + (size_t)row * 4096 + 2048 + col) = w; } }
	v_mov_b32_e32 v40, v214
	v_mov_b32_e32 v41, v215
	v_mov_b32_e32 v42, v216
	v_mov_b32_e32 v43, v217
	v_lshlrev_b32_e32 v51, 16, v43
	v_and_b32_e32 v43, 0xffff0000, v43
	v_lshlrev_b32_e32 v48, 16, v40
	v_and_b32_e32 v40, 0xffff0000, v40
	v_lshlrev_b32_e32 v49, 16, v41
	v_and_b32_e32 v41, 0xffff0000, v41
	v_lshlrev_b32_e32 v50, 16, v42
	v_and_b32_e32 v42, 0xffff0000, v42
	v_mul_f32_e32 v59, 0xbfb8aa3b, v43
	v_mul_f32_e32 v52, 0xbfb8aa3b, v48
	v_mul_f32_e32 v53, 0xbfb8aa3b, v40
	v_mul_f32_e32 v54, 0xbfb8aa3b, v49
	v_mul_f32_e32 v55, 0xbfb8aa3b, v41
	v_mul_f32_e32 v56, 0xbfb8aa3b, v50
	v_mul_f32_e32 v57, 0xbfb8aa3b, v42
	v_mul_f32_e32 v58, 0xbfb8aa3b, v51
	v_exp_f32_e32 v59, v59
	v_exp_f32_e32 v52, v52
	v_exp_f32_e32 v53, v53
	v_exp_f32_e32 v54, v54
	v_exp_f32_e32 v55, v55
	v_exp_f32_e32 v56, v56
	v_exp_f32_e32 v57, v57
	v_exp_f32_e32 v58, v58
	v_add_f32_e32 v59, 1.0, v59
	v_add_f32_e32 v52, 1.0, v52
	v_add_f32_e32 v53, 1.0, v53
	v_add_f32_e32 v54, 1.0, v54
	v_add_f32_e32 v55, 1.0, v55
	v_add_f32_e32 v56, 1.0, v56
	v_add_f32_e32 v57, 1.0, v57
	v_add_f32_e32 v58, 1.0, v58
	v_rcp_f32_e32 v59, v59
	v_rcp_f32_e32 v52, v52
	v_rcp_f32_e32 v53, v53
	v_rcp_f32_e32 v54, v54
	v_rcp_f32_e32 v55, v55
	v_rcp_f32_e32 v56, v56
	v_rcp_f32_e32 v57, v57
	v_rcp_f32_e32 v58, v58
	v_mul_f32_e32 v43, v59, v43
	v_mul_f32_e32 v48, v52, v48
	v_mul_f32_e32 v40, v53, v40
	v_mul_f32_e32 v49, v54, v49
	v_mul_f32_e32 v41, v55, v41
	v_mul_f32_e32 v50, v56, v50
	v_mul_f32_e32 v42, v57, v42
	v_mul_f32_e32 v51, v58, v51
	v_mul_f32_e32 v35, v35, v43
	v_mul_f32_e32 v36, v36, v48
	v_mul_f32_e32 v37, v37, v40
	v_mul_f32_e32 v38, v38, v49
	v_mul_f32_e32 v39, v39, v41
	v_mul_f32_e32 v40, v32, v50
	v_mul_f32_e32 v41, v33, v42
	v_mul_f32_e32 v42, v34, v51
	v_cvt_pk_bf16_f32 v32, v36, v37
	v_cvt_pk_bf16_f32 v33, v38, v39
	v_cvt_pk_bf16_f32 v34, v40, v41
	v_cvt_pk_bf16_f32 v35, v42, v35
	global_store_dwordx4 v[46:47], v[32:35], off
	v_lshl_add_u64 v[38:39], v[98:99], 0, v[168:169]
	v_lshl_add_u64 v[36:37], v[96:97], 0, v[168:169]
	s_waitcnt vmcnt(11)
	v_mov_b32_e32 v32, v218
	v_mov_b32_e32 v33, v219
	v_mov_b32_e32 v34, v220
	v_mov_b32_e32 v35, v221
	v_lshlrev_b32_e32 v43, 16, v35
	v_and_b32_e32 v35, 0xffff0000, v35
	v_lshlrev_b32_e32 v40, 16, v32
	v_and_b32_e32 v32, 0xffff0000, v32
	v_lshlrev_b32_e32 v41, 16, v33
	v_and_b32_e32 v33, 0xffff0000, v33
	v_lshlrev_b32_e32 v42, 16, v34
	v_and_b32_e32 v34, 0xffff0000, v34
	v_mul_f32_e32 v51, 0xbfb8aa3b, v35
	v_mul_f32_e32 v44, 0xbfb8aa3b, v40
	v_mul_f32_e32 v45, 0xbfb8aa3b, v32
	v_mul_f32_e32 v46, 0xbfb8aa3b, v41
	v_mul_f32_e32 v47, 0xbfb8aa3b, v33
	v_mul_f32_e32 v48, 0xbfb8aa3b, v42
	v_mul_f32_e32 v49, 0xbfb8aa3b, v34
	v_mul_f32_e32 v50, 0xbfb8aa3b, v43
	v_exp_f32_e32 v51, v51
	v_exp_f32_e32 v44, v44
	v_exp_f32_e32 v45, v45
	v_exp_f32_e32 v46, v46
	v_exp_f32_e32 v47, v47
	v_exp_f32_e32 v48, v48
	v_exp_f32_e32 v49, v49
	v_exp_f32_e32 v50, v50
	v_add_f32_e32 v51, 1.0, v51
	v_add_f32_e32 v44, 1.0, v44
	v_add_f32_e32 v45, 1.0, v45
	v_add_f32_e32 v46, 1.0, v46
	v_add_f32_e32 v47, 1.0, v47
	v_add_f32_e32 v48, 1.0, v48
	v_add_f32_e32 v49, 1.0, v49
	v_add_f32_e32 v50, 1.0, v50
	v_rcp_f32_e32 v51, v51
	v_rcp_f32_e32 v44, v44
	v_rcp_f32_e32 v45, v45
	v_rcp_f32_e32 v46, v46
	v_rcp_f32_e32 v47, v47
	v_rcp_f32_e32 v48, v48
	v_rcp_f32_e32 v49, v49
	v_rcp_f32_e32 v50, v50
	v_mul_f32_e32 v35, v51, v35
	v_mul_f32_e32 v40, v44, v40
	v_mul_f32_e32 v32, v45, v32
	v_mul_f32_e32 v41, v46, v41
	v_mul_f32_e32 v33, v47, v33
	v_mul_f32_e32 v42, v48, v42
	v_mul_f32_e32 v34, v49, v34
	v_mul_f32_e32 v43, v50, v43
	v_mul_f32_e32 v27, v27, v35
	v_mul_f32_e32 v28, v28, v40
	v_mul_f32_e32 v29, v29, v32
	v_mul_f32_e32 v30, v30, v41
	v_mul_f32_e32 v31, v31, v33
	v_mul_f32_e32 v32, v24, v42
	v_mul_f32_e32 v33, v25, v34
	v_mul_f32_e32 v34, v26, v43
	v_cvt_pk_bf16_f32 v24, v28, v29
	v_cvt_pk_bf16_f32 v25, v30, v31
	v_cvt_pk_bf16_f32 v26, v32, v33
	v_cvt_pk_bf16_f32 v27, v34, v27
	global_store_dwordx4 v[38:39], v[24:27], off
	v_lshl_add_u64 v[30:31], v[90:91], 0, v[168:169]
	v_lshl_add_u64 v[28:29], v[88:89], 0, v[168:169]
	s_waitcnt vmcnt(10)
; __device__ __forceinline__ float bflo(unsigned w) { return __uint_as_float(w << 16); }
; __device__ __forceinline__ float bfhi(unsigned w) { return __uint_as_float(w & 0xffff0000u); }
; __device__ __forceinline__ unsigned pk2(float lo, float hi) { unsigned r; asm("v_cvt_pk_bf16_f32 %0, %1, %2" : "=v"(r) : "v"(lo), "v"(hi)); return r; }
; __device__ __forceinline__ float siluf_(float x) { return x * __builtin_amdgcn_rcpf(1.0f + __expf(-x)); }
; #define PG8_WAIT_V(n) asm volatile("s_waitcnt vmcnt(" #n ")" ::: "memory")
; #define PG8_BAR __builtin_amdgcn_s_barrier()
; template <class Epi>
; __device__ __forceinline__ void gemm_phase(LAS unsigned char* lds, const GemmD g, const Epi& E) {
;     ...
;     PG8_WAIT_V(0);
;     if (wr == 0) PG8_BAR;
;     PG8_BAR;
;     __device__ __forceinline__ void operator()(const f32x4 (&acc)[2][2][4][2], const Unit& u, int wr, int wc, int fr, int fq) const {
;     ...
;                 for (int m = 0; m < 4; ++m) { const int row = row0 + ai * HALF + m * 16;
;                     const u32x4 z = __builtin_nontemporal_load((const u32x4*)(proj + (size_t)row * NPROJ + C_ZP + col));
;                     f32x4 v0 = (acc[ai][bj][m][0] + b0) * s0, v1 = (acc[ai][bj][m][1] + b1) * s1;
;                     v0[0] *= siluf_(bflo(z.x)); v0[1] *= siluf_(bfhi(z.x)); v0[2] *= siluf_(bflo(z.y)); v0[3] *= siluf_(bfhi(z.y));
;                     v1[0] *= siluf_(bflo(z.z)); v1[1] *= siluf_(bfhi(z.z)); v1[2] *= siluf_(bflo(z.w)); v1[3] *= siluf_(bfhi(z.w));
;                     u32x4 w; w.x = pk2(v0[0], v0[1]); w.y = pk2(v0[2], v0[3]); w.z = pk2(v1[0], v1[1]); w.w = pk2(v1[2], v1[3]);
;                     *(u32x4*)(a2 + (size_t)row * 4096 + 2048 + col) = w; } }
	v_mov_b32_e32 v24, v222
	v_mov_b32_e32 v25, v223
	v_mov_b32_e32 v26, v224
	v_mov_b32_e32 v27, v225
	v_lshlrev_b32_e32 v35, 16, v27
	v_and_b32_e32 v27, 0xffff0000, v27
	v_lshlrev_b32_e32 v32, 16, v24
	v_and_b32_e32 v24, 0xffff0000, v24
	v_lshlrev_b32_e32 v33, 16, v25
	v_and_b32_e32 v25, 0xffff0000, v25
	v_lshlrev_b32_e32 v34, 16, v26
	v_and_b32_e32 v26, 0xffff0000, v26
	v_mul_f32_e32 v43, 0xbfb8aa3b, v27
	v_mul_f32_e32 v36, 0xbfb8aa3b, v32
	v_mul_f32_e32 v37, 0xbfb8aa3b, v24
	v_mul_f32_e32 v38, 0xbfb8aa3b, v33
	v_mul_f32_e32 v39, 0xbfb8aa3b, v25
	v_mul_f32_e32 v40, 0xbfb8aa3b, v34
	v_mul_f32_e32 v41, 0xbfb8aa3b, v26
	v_mul_f32_e32 v42, 0xbfb8aa3b, v35
	v_exp_f32_e32 v43, v43
	v_exp_f32_e32 v36, v36
	v_exp_f32_e32 v37, v37
	v_exp_f32_e32 v38, v38
	v_exp_f32_e32 v39, v39
	v_exp_f32_e32 v40, v40
	v_exp_f32_e32 v41, v41
	v_exp_f32_e32 v42, v42
	v_add_f32_e32 v43, 1.0, v43
	v_add_f32_e32 v36, 1.0, v36
	v_add_f32_e32 v37, 1.0, v37
	v_add_f32_e32 v38, 1.0, v38
	v_add_f32_e32 v39, 1.0, v39
	v_add_f32_e32 v40, 1.0, v40
	v_add_f32_e32 v41, 1.0, v41
	v_add_f32_e32 v42, 1.0, v42
	v_rcp_f32_e32 v43, v43
	v_rcp_f32_e32 v36, v36
	v_rcp_f32_e32 v37, v37
	v_rcp_f32_e32 v38, v38
	v_rcp_f32_e32 v39, v39
	v_rcp_f32_e32 v40, v40
	v_rcp_f32_e32 v41, v41
	v_rcp_f32_e32 v42, v42
	v_mul_f32_e32 v27, v43, v27
	v_mul_f32_e32 v32, v36, v32
	v_mul_f32_e32 v24, v37, v24
	v_mul_f32_e32 v33, v38, v33
	v_mul_f32_e32 v25, v39, v25
	v_mul_f32_e32 v34, v40, v34
	v_mul_f32_e32 v26, v41, v26
	v_mul_f32_e32 v35, v42, v35
	v_mul_f32_e32 v19, v19, v27
	v_mul_f32_e32 v20, v20, v32
	v_mul_f32_e32 v21, v21, v24
	v_mul_f32_e32 v22, v22, v33
	v_mul_f32_e32 v23, v23, v25
	v_mul_f32_e32 v24, v16, v34
	v_mul_f32_e32 v25, v17, v26
	v_mul_f32_e32 v26, v18, v35
	v_cvt_pk_bf16_f32 v16, v20, v21
	v_cvt_pk_bf16_f32 v17, v22, v23
	v_cvt_pk_bf16_f32 v18, v24, v25
	v_cvt_pk_bf16_f32 v19, v26, v19
	global_store_dwordx4 v[30:31], v[16:19], off
	v_lshl_add_u64 v[22:23], v[84:85], 0, v[168:169]
	v_lshl_add_u64 v[20:21], v[82:83], 0, v[168:169]
	s_waitcnt vmcnt(9)
	v_mov_b32_e32 v16, v226
	v_mov_b32_e32 v17, v227
	v_mov_b32_e32 v18, v228
	v_mov_b32_e32 v19, v229
	v_lshlrev_b32_e32 v27, 16, v19
	v_and_b32_e32 v19, 0xffff0000, v19
	v_lshlrev_b32_e32 v24, 16, v16
	v_and_b32_e32 v16, 0xffff0000, v16
	v_lshlrev_b32_e32 v25, 16, v17
	v_and_b32_e32 v17, 0xffff0000, v17
	v_lshlrev_b32_e32 v26, 16, v18
	v_and_b32_e32 v18, 0xffff0000, v18
	v_mul_f32_e32 v35, 0xbfb8aa3b, v19
	v_mul_f32_e32 v28, 0xbfb8aa3b, v24
	v_mul_f32_e32 v29, 0xbfb8aa3b, v16
	v_mul_f32_e32 v30, 0xbfb8aa3b, v25
	v_mul_f32_e32 v31, 0xbfb8aa3b, v17
	v_mul_f32_e32 v32, 0xbfb8aa3b, v26
	v_mul_f32_e32 v33, 0xbfb8aa3b, v18
	v_mul_f32_e32 v34, 0xbfb8aa3b, v27
	v_exp_f32_e32 v35, v35
	v_exp_f32_e32 v28, v28
	v_exp_f32_e32 v29, v29
	v_exp_f32_e32 v30, v30
	v_exp_f32_e32 v31, v31
	v_exp_f32_e32 v32, v32
	v_exp_f32_e32 v33, v33
	v_exp_f32_e32 v34, v34
	v_add_f32_e32 v35, 1.0, v35
	v_add_f32_e32 v28, 1.0, v28
	v_add_f32_e32 v29, 1.0, v29
	v_add_f32_e32 v30, 1.0, v30
	v_add_f32_e32 v31, 1.0, v31
	v_add_f32_e32 v32, 1.0, v32
	v_add_f32_e32 v33, 1.0, v33
	v_add_f32_e32 v34, 1.0, v34
	v_rcp_f32_e32 v35, v35
	v_rcp_f32_e32 v28, v28
	v_rcp_f32_e32 v29, v29
	v_rcp_f32_e32 v30, v30
	v_rcp_f32_e32 v31, v31
	v_rcp_f32_e32 v32, v32
	v_rcp_f32_e32 v33, v33
	v_rcp_f32_e32 v34, v34
	v_mul_f32_e32 v19, v35, v19
	v_mul_f32_e32 v24, v28, v24
	v_mul_f32_e32 v16, v29, v16
	v_mul_f32_e32 v25, v30, v25
	v_mul_f32_e32 v17, v31, v17
	v_mul_f32_e32 v26, v32, v26
	v_mul_f32_e32 v18, v33, v18
	v_mul_f32_e32 v27, v34, v27
	v_mul_f32_e32 v11, v11, v19
	v_mul_f32_e32 v12, v12, v24
	v_mul_f32_e32 v13, v13, v16
	v_mul_f32_e32 v14, v14, v25
	v_mul_f32_e32 v15, v15, v17
	v_mul_f32_e32 v16, v8, v26
	v_mul_f32_e32 v17, v9, v18
	v_mul_f32_e32 v18, v10, v27
	v_cvt_pk_bf16_f32 v8, v12, v13
	v_cvt_pk_bf16_f32 v9, v14, v15
	v_cvt_pk_bf16_f32 v10, v16, v17
	v_cvt_pk_bf16_f32 v11, v18, v11
	global_store_dwordx4 v[22:23], v[8:11], off
	v_lshl_add_u64 v[12:13], v[80:81], 0, v[168:169]
	s_waitcnt vmcnt(8)
	v_mov_b32_e32 v8, v230
	v_mov_b32_e32 v9, v231
	v_mov_b32_e32 v10, v232
	v_mov_b32_e32 v11, v233
	v_lshlrev_b32_e32 v17, 16, v11
	v_and_b32_e32 v11, 0xffff0000, v11
	v_lshlrev_b32_e32 v14, 16, v8
	v_and_b32_e32 v8, 0xffff0000, v8
	v_lshlrev_b32_e32 v15, 16, v9
	v_and_b32_e32 v9, 0xffff0000, v9
	v_lshlrev_b32_e32 v16, 16, v10
	v_and_b32_e32 v10, 0xffff0000, v10
	v_mul_f32_e32 v25, 0xbfb8aa3b, v11
	v_mul_f32_e32 v18, 0xbfb8aa3b, v14
	v_mul_f32_e32 v19, 0xbfb8aa3b, v8
	v_mul_f32_e32 v20, 0xbfb8aa3b, v15
	v_mul_f32_e32 v21, 0xbfb8aa3b, v9
	v_mul_f32_e32 v22, 0xbfb8aa3b, v16
	v_mul_f32_e32 v23, 0xbfb8aa3b, v10
	v_mul_f32_e32 v24, 0xbfb8aa3b, v17
	v_exp_f32_e32 v25, v25
	v_exp_f32_e32 v18, v18
	v_exp_f32_e32 v19, v19
	v_exp_f32_e32 v20, v20
	v_exp_f32_e32 v21, v21
	v_exp_f32_e32 v22, v22
	v_exp_f32_e32 v23, v23
	v_exp_f32_e32 v24, v24
	v_add_f32_e32 v25, 1.0, v25
	v_add_f32_e32 v18, 1.0, v18
	v_add_f32_e32 v19, 1.0, v19
	v_add_f32_e32 v20, 1.0, v20
	v_add_f32_e32 v21, 1.0, v21
	v_add_f32_e32 v22, 1.0, v22
	v_add_f32_e32 v23, 1.0, v23
	v_add_f32_e32 v24, 1.0, v24
	v_rcp_f32_e32 v25, v25
	v_rcp_f32_e32 v18, v18
	v_rcp_f32_e32 v19, v19
	v_rcp_f32_e32 v20, v20
	v_rcp_f32_e32 v21, v21
	v_rcp_f32_e32 v22, v22
	v_rcp_f32_e32 v23, v23
	v_rcp_f32_e32 v24, v24
	v_mul_f32_e32 v11, v25, v11
	v_mul_f32_e32 v14, v18, v14
	v_mul_f32_e32 v8, v19, v8
	v_mul_f32_e32 v15, v20, v15
	v_mul_f32_e32 v9, v21, v9
	v_mul_f32_e32 v16, v22, v16
	v_mul_f32_e32 v10, v23, v10
	v_mul_f32_e32 v17, v24, v17
	v_mul_f32_e32 v3, v3, v11
	v_mul_f32_e32 v4, v4, v14
	v_mul_f32_e32 v5, v5, v8
	v_mul_f32_e32 v6, v6, v15
	v_mul_f32_e32 v7, v7, v9
	v_mul_f32_e32 v8, v0, v16
	v_mul_f32_e32 v9, v1, v10
	v_mul_f32_e32 v10, v2, v17
	v_cvt_pk_bf16_f32 v0, v4, v5
	v_cvt_pk_bf16_f32 v1, v6, v7
	v_cvt_pk_bf16_f32 v2, v8, v9
	v_cvt_pk_bf16_f32 v3, v10, v3
	global_store_dwordx4 v[12:13], v[0:3], off
	s_cbranch_vccz .LBB0_595
	s_waitcnt vmcnt(0)
	s_cmpk_gt_u32 s33, 0xff
	s_cbranch_scc1 .LBB0_604
	s_barrier

.LBB0_697:
	s_add_u32 s34, vcc_lo, 0xfff80080
	s_addc_u32 s35, vcc_hi, -1
	s_add_i32 s84, 0, 0x10000
	v_add_u32_e32 v0, s84, v155
	ds_read_b128 v[146:149], v0
	ds_read_b128 v[150:153], v0 offset:1024
	ds_read_b128 v[158:161], v0 offset:2048
	ds_read_b128 v[162:165], v0 offset:3072
	s_cmp_eq_u32 s95, 28
	s_cselect_b32 s57, s1, s35
	s_cselect_b32 s56, s36, s34
	s_cselect_b32 s35, s31, s66
	s_cselect_b32 s34, s37, s51
	v_lshl_add_u64 v[170:171], vcc, 0, v[142:143]
	s_add_i32 m0, s2, 0xc000
	ds_read_b128 v[166:169], v157
	ds_read_b128 v[180:183], v157 offset:1024
	ds_read_b128 v[184:187], v157 offset:2048
	ds_read_b128 v[188:191], v157 offset:3072
	ds_read_b128 v[204:207], v157 offset:4096
	ds_read_b128 v[208:211], v157 offset:5120
	ds_read_b128 v[212:215], v157 offset:6144
	ds_read_b128 v[216:219], v157 offset:7168
	global_load_lds_dwordx4 v[170:171], off
	v_lshl_add_u64 v[170:171], vcc, 0, v[144:145]
	s_add_i32 m0, s2, 0xe000
	s_nop 0
	global_load_lds_dwordx4 v[170:171], off
	s_waitcnt lgkmcnt(8)
	s_barrier
	s_setprio 1
	s_waitcnt lgkmcnt(7)
	v_mfma_f32_16x16x32_bf16 v[126:129], v[146:149], v[166:169], v[126:129]
	v_mfma_f32_16x16x32_bf16 v[122:125], v[158:161], v[166:169], v[122:125]
	s_waitcnt lgkmcnt(5)
	v_mfma_f32_16x16x32_bf16 v[110:113], v[146:149], v[184:187], v[110:113]
	v_mfma_f32_16x16x32_bf16 v[106:109], v[158:161], v[184:187], v[106:109]
	s_waitcnt lgkmcnt(3)
	v_mfma_f32_16x16x32_bf16 v[94:97], v[146:149], v[204:207], v[94:97]
	v_mfma_f32_16x16x32_bf16 v[90:93], v[158:161], v[204:207], v[90:93]
	s_waitcnt lgkmcnt(1)
	v_mfma_f32_16x16x32_bf16 v[78:81], v[146:149], v[212:215], v[78:81]
	v_mfma_f32_16x16x32_bf16 v[74:77], v[158:161], v[212:215], v[74:77]
	v_mfma_f32_16x16x32_bf16 v[126:129], v[150:153], v[180:183], v[126:129]
	v_mfma_f32_16x16x32_bf16 v[122:125], v[162:165], v[180:183], v[122:125]
	v_mfma_f32_16x16x32_bf16 v[110:113], v[150:153], v[188:191], v[110:113]
	v_mfma_f32_16x16x32_bf16 v[106:109], v[162:165], v[188:191], v[106:109]
	v_mfma_f32_16x16x32_bf16 v[94:97], v[150:153], v[208:211], v[94:97]
	v_mfma_f32_16x16x32_bf16 v[90:93], v[162:165], v[208:211], v[90:93]
	s_waitcnt lgkmcnt(0)
	v_mfma_f32_16x16x32_bf16 v[78:81], v[150:153], v[216:219], v[78:81]
	v_mfma_f32_16x16x32_bf16 v[74:77], v[162:165], v[216:219], v[74:77]
	s_setprio 0
	s_barrier
	s_add_i32 s86, 0, 0x14000
	s_add_i32 s84, s84, s97
	v_add_u32_e32 v0, s86, v155
	v_lshl_add_u64 v[170:171], s[34:35], 0, v[132:133]
	s_mov_b32 m0, s84
	ds_read_b128 v[220:223], v0
	ds_read_b128 v[224:227], v0 offset:1024
	ds_read_b128 v[228:231], v0 offset:2048
	ds_read_b128 v[232:235], v0 offset:3072
	global_load_lds_dwordx4 v[170:171], off
	v_lshl_add_u64 v[236:237], s[34:35], 0, v[136:137]
	s_add_i32 m0, s84, 0x2000
	s_nop 0
	global_load_lds_dwordx4 v[236:237], off
	s_barrier
	s_setprio 1
	s_waitcnt lgkmcnt(3)
	v_mfma_f32_16x16x32_bf16 v[118:121], v[220:223], v[166:169], v[118:121]
	s_waitcnt lgkmcnt(1)
	v_mfma_f32_16x16x32_bf16 v[114:117], v[228:231], v[166:169], v[114:117]
	v_mfma_f32_16x16x32_bf16 v[102:105], v[220:223], v[184:187], v[102:105]
	v_mfma_f32_16x16x32_bf16 v[98:101], v[228:231], v[184:187], v[98:101]
	v_mfma_f32_16x16x32_bf16 v[86:89], v[220:223], v[204:207], v[86:89]
	v_mfma_f32_16x16x32_bf16 v[82:85], v[228:231], v[204:207], v[82:85]
	v_mfma_f32_16x16x32_bf16 v[70:73], v[220:223], v[212:215], v[70:73]
	v_mfma_f32_16x16x32_bf16 v[66:69], v[228:231], v[212:215], v[66:69]
	v_mfma_f32_16x16x32_bf16 v[118:121], v[224:227], v[180:183], v[118:121]
	s_waitcnt lgkmcnt(0)
	v_mfma_f32_16x16x32_bf16 v[114:117], v[232:235], v[180:183], v[114:117]
	v_mfma_f32_16x16x32_bf16 v[102:105], v[224:227], v[188:191], v[102:105]
	v_mfma_f32_16x16x32_bf16 v[98:101], v[232:235], v[188:191], v[98:101]
	v_mfma_f32_16x16x32_bf16 v[86:89], v[224:227], v[208:211], v[86:89]
	v_mfma_f32_16x16x32_bf16 v[82:85], v[232:235], v[208:211], v[82:85]
	v_mfma_f32_16x16x32_bf16 v[70:73], v[224:227], v[216:219], v[70:73]
	v_mfma_f32_16x16x32_bf16 v[66:69], v[232:235], v[216:219], v[66:69]
	s_setprio 0
	s_mov_b32 m0, s2
	v_lshl_add_u64 v[238:239], s[56:57], 0, v[130:131]
	s_barrier
	ds_read_b128 v[166:169], v157 offset:16384
	ds_read_b128 v[180:183], v157 offset:17408
	ds_read_b128 v[184:187], v157 offset:18432
	ds_read_b128 v[188:191], v157 offset:19456
	ds_read_b128 v[204:207], v157 offset:20480
	ds_read_b128 v[208:211], v157 offset:21504
	ds_read_b128 v[212:215], v157 offset:22528
	ds_read_b128 v[216:219], v157 offset:23552
	global_load_lds_dwordx4 v[238:239], off
	v_lshl_add_u64 v[240:241], s[56:57], 0, v[134:135]
	s_mov_b32 m0, s3
	s_nop 0
	global_load_lds_dwordx4 v[240:241], off
	s_barrier
	s_setprio 1
	s_waitcnt lgkmcnt(7)
	v_mfma_f32_16x16x32_bf16 v[62:65], v[146:149], v[166:169], v[62:65]
	v_mfma_f32_16x16x32_bf16 v[58:61], v[158:161], v[166:169], v[58:61]
	s_waitcnt lgkmcnt(5)
	v_mfma_f32_16x16x32_bf16 v[46:49], v[146:149], v[184:187], v[46:49]
	v_mfma_f32_16x16x32_bf16 v[42:45], v[158:161], v[184:187], v[42:45]
	s_waitcnt lgkmcnt(3)
	v_mfma_f32_16x16x32_bf16 v[30:33], v[146:149], v[204:207], v[30:33]
	v_mfma_f32_16x16x32_bf16 v[26:29], v[158:161], v[204:207], v[26:29]
	s_waitcnt lgkmcnt(1)
	v_mfma_f32_16x16x32_bf16 v[14:17], v[146:149], v[212:215], v[14:17]
	v_mfma_f32_16x16x32_bf16 v[10:13], v[158:161], v[212:215], v[10:13]
	v_mfma_f32_16x16x32_bf16 v[62:65], v[150:153], v[180:183], v[62:65]
	v_mfma_f32_16x16x32_bf16 v[58:61], v[162:165], v[180:183], v[58:61]
	v_mfma_f32_16x16x32_bf16 v[46:49], v[150:153], v[188:191], v[46:49]
	v_mfma_f32_16x16x32_bf16 v[42:45], v[162:165], v[188:191], v[42:45]
	v_mfma_f32_16x16x32_bf16 v[30:33], v[150:153], v[208:211], v[30:33]
	v_mfma_f32_16x16x32_bf16 v[26:29], v[162:165], v[208:211], v[26:29]
	s_waitcnt lgkmcnt(0)
	v_mfma_f32_16x16x32_bf16 v[14:17], v[150:153], v[216:219], v[14:17]
	v_mfma_f32_16x16x32_bf16 v[10:13], v[162:165], v[216:219], v[10:13]
	s_setprio 0
	s_barrier
	s_add_u32 s84, s34, 0x80000
	s_addc_u32 s85, s35, 0
	s_add_i32 s86, s86, s97
	v_lshl_add_u64 v[146:147], s[84:85], 0, v[132:133]
	s_mov_b32 m0, s86
	s_nop 0
	global_load_lds_dwordx4 v[146:147], off
	v_lshl_add_u64 v[146:147], s[84:85], 0, v[136:137]
	s_add_i32 m0, s86, 0x2000
	s_nop 0
	global_load_lds_dwordx4 v[146:147], off
	s_waitcnt vmcnt(6)
	s_barrier
	s_setprio 1
	v_mfma_f32_16x16x32_bf16 v[54:57], v[220:223], v[166:169], v[54:57]
	v_mfma_f32_16x16x32_bf16 v[50:53], v[228:231], v[166:169], v[50:53]
	v_mfma_f32_16x16x32_bf16 v[38:41], v[220:223], v[184:187], v[38:41]
	v_mfma_f32_16x16x32_bf16 v[34:37], v[228:231], v[184:187], v[34:37]
	v_mfma_f32_16x16x32_bf16 v[22:25], v[220:223], v[204:207], v[22:25]
	v_mfma_f32_16x16x32_bf16 v[18:21], v[228:231], v[204:207], v[18:21]
	v_mfma_f32_16x16x32_bf16 v[6:9], v[220:223], v[212:215], v[6:9]
	v_mfma_f32_16x16x32_bf16 v[2:5], v[228:231], v[212:215], v[2:5]
	v_mfma_f32_16x16x32_bf16 v[54:57], v[224:227], v[180:183], v[54:57]
	v_mfma_f32_16x16x32_bf16 v[50:53], v[232:235], v[180:183], v[50:53]
	v_mfma_f32_16x16x32_bf16 v[38:41], v[224:227], v[188:191], v[38:41]
	v_mfma_f32_16x16x32_bf16 v[34:37], v[232:235], v[188:191], v[34:37]
	v_mfma_f32_16x16x32_bf16 v[22:25], v[224:227], v[208:211], v[22:25]
	v_mfma_f32_16x16x32_bf16 v[18:21], v[232:235], v[208:211], v[18:21]
	v_mfma_f32_16x16x32_bf16 v[6:9], v[224:227], v[216:219], v[6:9]
	v_mfma_f32_16x16x32_bf16 v[2:5], v[232:235], v[216:219], v[2:5]
	s_setprio 0
	s_add_i32 s84, 0, 0x18000
	v_add_u32_e32 v0, s84, v155
	s_barrier
	ds_read_b128 v[146:149], v0
	ds_read_b128 v[150:153], v0 offset:1024
	ds_read_b128 v[158:161], v0 offset:2048
	ds_read_b128 v[162:165], v0 offset:3072
	s_add_u32 s56, s56, 0x80000
	s_addc_u32 s57, s57, 0
	s_mov_b32 m0, s83
	v_lshl_add_u64 v[220:221], s[56:57], 0, v[130:131]
	ds_read_b128 v[166:169], v157 offset:32768
	ds_read_b128 v[180:183], v157 offset:33792
	ds_read_b128 v[184:187], v157 offset:34816
	ds_read_b128 v[188:191], v157 offset:35840
	ds_read_b128 v[204:207], v157 offset:36864
	ds_read_b128 v[208:211], v157 offset:37888
	ds_read_b128 v[212:215], v157 offset:38912
	ds_read_b128 v[216:219], v157 offset:39936
	global_load_lds_dwordx4 v[220:221], off
	v_lshl_add_u64 v[220:221], s[56:57], 0, v[134:135]
	s_mov_b32 m0, s70
	s_nop 0
	global_load_lds_dwordx4 v[220:221], off
	s_waitcnt lgkmcnt(8)
	s_barrier
	s_setprio 1
	s_waitcnt lgkmcnt(7)
	v_mfma_f32_16x16x32_bf16 v[126:129], v[146:149], v[166:169], v[126:129]
	v_mfma_f32_16x16x32_bf16 v[122:125], v[158:161], v[166:169], v[122:125]
	s_waitcnt lgkmcnt(5)
	v_mfma_f32_16x16x32_bf16 v[110:113], v[146:149], v[184:187], v[110:113]
	v_mfma_f32_16x16x32_bf16 v[106:109], v[158:161], v[184:187], v[106:109]
	s_waitcnt lgkmcnt(3)
	v_mfma_f32_16x16x32_bf16 v[94:97], v[146:149], v[204:207], v[94:97]
	v_mfma_f32_16x16x32_bf16 v[90:93], v[158:161], v[204:207], v[90:93]
	s_waitcnt lgkmcnt(1)
	v_mfma_f32_16x16x32_bf16 v[78:81], v[146:149], v[212:215], v[78:81]
	v_mfma_f32_16x16x32_bf16 v[74:77], v[158:161], v[212:215], v[74:77]
	v_mfma_f32_16x16x32_bf16 v[126:129], v[150:153], v[180:183], v[126:129]
	v_mfma_f32_16x16x32_bf16 v[122:125], v[162:165], v[180:183], v[122:125]
	v_mfma_f32_16x16x32_bf16 v[110:113], v[150:153], v[188:191], v[110:113]
	v_mfma_f32_16x16x32_bf16 v[106:109], v[162:165], v[188:191], v[106:109]
	v_mfma_f32_16x16x32_bf16 v[94:97], v[150:153], v[208:211], v[94:97]
	v_mfma_f32_16x16x32_bf16 v[90:93], v[162:165], v[208:211], v[90:93]
	s_waitcnt lgkmcnt(0)
	v_mfma_f32_16x16x32_bf16 v[78:81], v[150:153], v[216:219], v[78:81]
	v_mfma_f32_16x16x32_bf16 v[74:77], v[162:165], v[216:219], v[74:77]
	s_setprio 0
	s_barrier
	s_add_i32 s56, 0, 0x1c000
	s_add_i32 s57, s84, s97
	v_add_u32_e32 v0, s56, v155
	v_lshl_add_u64 v[170:171], v[170:171], 0, s[48:49]
	s_mov_b32 m0, s57
	ds_read_b128 v[220:223], v0
	ds_read_b128 v[224:227], v0 offset:1024
	ds_read_b128 v[228:231], v0 offset:2048
	ds_read_b128 v[232:235], v0 offset:3072
	global_load_lds_dwordx4 v[170:171], off
	v_lshl_add_u64 v[170:171], v[236:237], 0, s[48:49]
	s_add_i32 m0, s57, 0x2000
	s_nop 0
	global_load_lds_dwordx4 v[170:171], off
	s_barrier
	s_setprio 1
	s_waitcnt lgkmcnt(3)
	v_mfma_f32_16x16x32_bf16 v[118:121], v[220:223], v[166:169], v[118:121]
	s_waitcnt lgkmcnt(1)
	v_mfma_f32_16x16x32_bf16 v[114:117], v[228:231], v[166:169], v[114:117]
	v_mfma_f32_16x16x32_bf16 v[102:105], v[220:223], v[184:187], v[102:105]
	v_mfma_f32_16x16x32_bf16 v[98:101], v[228:231], v[184:187], v[98:101]
	v_mfma_f32_16x16x32_bf16 v[86:89], v[220:223], v[204:207], v[86:89]
	v_mfma_f32_16x16x32_bf16 v[82:85], v[228:231], v[204:207], v[82:85]
	v_mfma_f32_16x16x32_bf16 v[70:73], v[220:223], v[212:215], v[70:73]
	v_mfma_f32_16x16x32_bf16 v[66:69], v[228:231], v[212:215], v[66:69]
	v_mfma_f32_16x16x32_bf16 v[118:121], v[224:227], v[180:183], v[118:121]
	s_waitcnt lgkmcnt(0)
	v_mfma_f32_16x16x32_bf16 v[114:117], v[232:235], v[180:183], v[114:117]
	v_mfma_f32_16x16x32_bf16 v[102:105], v[224:227], v[188:191], v[102:105]
	v_mfma_f32_16x16x32_bf16 v[98:101], v[232:235], v[188:191], v[98:101]
	v_mfma_f32_16x16x32_bf16 v[86:89], v[224:227], v[208:211], v[86:89]
	v_mfma_f32_16x16x32_bf16 v[82:85], v[232:235], v[208:211], v[82:85]
	v_mfma_f32_16x16x32_bf16 v[70:73], v[224:227], v[216:219], v[70:73]
	v_mfma_f32_16x16x32_bf16 v[66:69], v[232:235], v[216:219], v[66:69]
	s_setprio 0
	s_mov_b32 m0, s74
	v_lshl_add_u64 v[170:171], v[238:239], 0, s[48:49]
	s_barrier
;     __device__ __forceinline__ void operator()(const f32x4 (&acc)[2][2][4][2], const Unit& u, int wr, int wc, int fr, int fq) const {
;         const int row0 = u.pm * BM + wr * 64 + fr, col0 = u.pn * BM + wc * 32 + 8 * fq;
; #pragma unroll
;         for (int ai = 0; ai < 2; ++ai)
; #pragma unroll
;             for (int m = 0; m < 4; ++m) { const int row = row0 + ai * HALF + m * 16;
;                 const float* src = row_src(p, row); float* dst = row_dst(p, row); float ss = 0.f;
;                 if (dst) {
; #pragma unroll
;                     for (int bj = 0; bj < 2; ++bj) { const int col = col0 + bj * HALF;
;                         const f32x4 h0 = __builtin_nontemporal_load((const f32x4*)(src + col)), h1 = __builtin_nontemporal_load((const f32x4*)(src + col + 4));
	ds_read_b128 v[166:169], v157 offset:49152
	ds_read_b128 v[180:183], v157 offset:50176
	ds_read_b128 v[184:187], v157 offset:51200
	ds_read_b128 v[188:191], v157 offset:52224
	ds_read_b128 v[204:207], v157 offset:53248
	ds_read_b128 v[208:211], v157 offset:54272
	ds_read_b128 v[212:215], v157 offset:55296
	ds_read_b128 v[216:219], v157 offset:56320
	global_load_lds_dwordx4 v[170:171], off
	v_lshl_add_u64 v[170:171], v[240:241], 0, s[48:49]
	s_mov_b32 m0, s75
	s_nop 0
	global_load_lds_dwordx4 v[170:171], off
	s_barrier
	s_setprio 1
	s_waitcnt lgkmcnt(7)
	v_mfma_f32_16x16x32_bf16 v[62:65], v[146:149], v[166:169], v[62:65]
	v_mfma_f32_16x16x32_bf16 v[58:61], v[158:161], v[166:169], v[58:61]
	s_waitcnt lgkmcnt(5)
	v_mfma_f32_16x16x32_bf16 v[46:49], v[146:149], v[184:187], v[46:49]
	v_mfma_f32_16x16x32_bf16 v[42:45], v[158:161], v[184:187], v[42:45]
	s_waitcnt lgkmcnt(3)
	v_mfma_f32_16x16x32_bf16 v[30:33], v[146:149], v[204:207], v[30:33]
	v_mfma_f32_16x16x32_bf16 v[26:29], v[158:161], v[204:207], v[26:29]
	s_waitcnt lgkmcnt(1)
	v_mfma_f32_16x16x32_bf16 v[14:17], v[146:149], v[212:215], v[14:17]
	v_mfma_f32_16x16x32_bf16 v[10:13], v[158:161], v[212:215], v[10:13]
	v_mfma_f32_16x16x32_bf16 v[62:65], v[150:153], v[180:183], v[62:65]
	v_mfma_f32_16x16x32_bf16 v[58:61], v[162:165], v[180:183], v[58:61]
	v_mfma_f32_16x16x32_bf16 v[46:49], v[150:153], v[188:191], v[46:49]
	v_mfma_f32_16x16x32_bf16 v[42:45], v[162:165], v[188:191], v[42:45]
	v_mfma_f32_16x16x32_bf16 v[30:33], v[150:153], v[208:211], v[30:33]
	v_mfma_f32_16x16x32_bf16 v[26:29], v[162:165], v[208:211], v[26:29]
	s_waitcnt lgkmcnt(0)
	v_mfma_f32_16x16x32_bf16 v[14:17], v[150:153], v[216:219], v[14:17]
	v_mfma_f32_16x16x32_bf16 v[10:13], v[162:165], v[216:219], v[10:13]
	s_setprio 0
	s_barrier
	s_add_u32 s34, s34, 0x80080
	s_addc_u32 s35, s35, 0
	s_add_i32 s56, s56, s97
	v_lshl_add_u64 v[146:147], s[34:35], 0, v[132:133]
	s_mov_b32 m0, s56
	s_nop 0
	global_load_lds_dwordx4 v[146:147], off
	v_lshl_add_u64 v[146:147], s[34:35], 0, v[136:137]
	s_add_i32 m0, s56, 0x2000
	s_nop 0
	global_load_lds_dwordx4 v[146:147], off
	s_waitcnt vmcnt(6)
	s_barrier
	s_setprio 1
	v_mfma_f32_16x16x32_bf16 v[54:57], v[220:223], v[166:169], v[54:57]
	v_mfma_f32_16x16x32_bf16 v[50:53], v[228:231], v[166:169], v[50:53]
	v_mfma_f32_16x16x32_bf16 v[38:41], v[220:223], v[184:187], v[38:41]
	v_mfma_f32_16x16x32_bf16 v[34:37], v[228:231], v[184:187], v[34:37]
	v_mfma_f32_16x16x32_bf16 v[22:25], v[220:223], v[204:207], v[22:25]
	v_mfma_f32_16x16x32_bf16 v[18:21], v[228:231], v[204:207], v[18:21]
	v_mfma_f32_16x16x32_bf16 v[6:9], v[220:223], v[212:215], v[6:9]
	v_mfma_f32_16x16x32_bf16 v[2:5], v[228:231], v[212:215], v[2:5]
	v_mfma_f32_16x16x32_bf16 v[54:57], v[224:227], v[180:183], v[54:57]
	v_mfma_f32_16x16x32_bf16 v[50:53], v[232:235], v[180:183], v[50:53]
	v_mfma_f32_16x16x32_bf16 v[38:41], v[224:227], v[188:191], v[38:41]
	v_mfma_f32_16x16x32_bf16 v[34:37], v[232:235], v[188:191], v[34:37]
	v_mfma_f32_16x16x32_bf16 v[22:25], v[224:227], v[208:211], v[22:25]
	v_mfma_f32_16x16x32_bf16 v[18:21], v[232:235], v[208:211], v[18:21]
	v_mfma_f32_16x16x32_bf16 v[6:9], v[224:227], v[216:219], v[6:9]
	v_mfma_f32_16x16x32_bf16 v[2:5], v[232:235], v[216:219], v[2:5]
	s_setprio 0
	s_add_i32 s95, s95, 2
	s_add_u32 vcc_lo, vcc_lo, 0x100
	s_addc_u32 vcc_hi, vcc_hi, 0
	s_add_u32 s51, s51, 0x100
	s_addc_u32 s66, s66, 0
	s_cmp_gt_u32 s95, 29
	s_barrier
	s_cbranch_scc0 .LBB0_697
	v_lshl_add_u32 v148, s0, 8, v154
	v_readlane_b32 s4, v244, 12
	v_readlane_b32 s5, v244, 13
	v_readlane_b32 s6, v244, 14
	v_readlane_b32 s7, v244, 15
	v_readlane_b32 s12, v244, 22
	v_readlane_b32 s13, v244, 23
	v_lshl_or_b32 v190, s50, 8, v156
	v_mov_b32_e32 v191, 0
	v_mov_b32_e32 v188, 0x1000
	v_lshlrev_b32_e32 v190, 2, v190
	s_mov_b32 s8, 0xfff00000
	s_mov_b32 s9, -1
	s_mov_b32 s10, 0xfbc00000
	s_mov_b32 s11, -1
	v_lshl_add_u64 v[182:183], v[190:191], 0, s[4:5]
	v_lshl_add_u64 v[184:185], v[190:191], 0, s[6:7]
	v_lshl_add_u64 v[186:187], v[190:191], 0, s[12:13]
	v_lshl_add_u64 v[182:183], v[182:183], 0, s[8:9]
	v_lshl_add_u64 v[184:185], v[184:185], 0, s[10:11]
	v_mov_b32_e32 v238, v148
	v_mul_hi_i32 v239, v238, s90
	v_lshlrev_b32_e32 v241, 13, v238
	v_ashrrev_i32_e32 v239, 10, v239
	v_mul_i32_i24_e32 v240, 0xfffff780, v239
	v_lshlrev_b32_e32 v239, 24, v239
	v_add_u32_e32 v240, v240, v238
	v_cmp_gt_i32_e32 vcc, 0x2200, v238
	v_max_i32_e32 v238, 0x80, v240
	v_lshl_add_u32 v239, v238, 13, v239
	v_cndmask_b32_e32 v190, v241, v239, vcc
	v_cndmask_b32_e32 v236, v184, v182, vcc
	v_cndmask_b32_e32 v237, v185, v183, vcc
	v_cndmask_b32_e32 v240, v188, v240, vcc
	v_lshl_add_u64 v[236:237], v[190:191], 0, v[236:237]
	v_add_u32_e32 v190, 0xffffff90, v240
	v_cmp_gt_i32_e32 vcc, 0x80, v240
	v_max_i32_e32 v190, 0, v190
	v_lshlrev_b32_e32 v190, 13, v190
	v_lshl_add_u64 v[238:239], v[190:191], 0, v[186:187]
	v_cndmask_b32_e32 v236, v236, v238, vcc
	v_cndmask_b32_e32 v237, v237, v239, vcc
	global_load_dwordx4 v[204:207], v[236:237], off offset:16 nt
	global_load_dwordx4 v[208:211], v[236:237], off nt
	global_load_dwordx4 v[212:215], v[236:237], off offset:528 nt
	global_load_dwordx4 v[216:219], v[236:237], off offset:512 nt
	v_add_u32_e32 v238, 0x10, v148
	v_mul_hi_i32 v239, v238, s90
	v_lshlrev_b32_e32 v241, 13, v238
	v_ashrrev_i32_e32 v239, 10, v239
	v_mul_i32_i24_e32 v240, 0xfffff780, v239
	v_lshlrev_b32_e32 v239, 24, v239
	v_add_u32_e32 v240, v240, v238
	v_cmp_gt_i32_e32 vcc, 0x2200, v238
	v_max_i32_e32 v238, 0x80, v240
	v_lshl_add_u32 v239, v238, 13, v239
	v_cndmask_b32_e32 v190, v241, v239, vcc
	v_cndmask_b32_e32 v236, v184, v182, vcc
	v_cndmask_b32_e32 v237, v185, v183, vcc
	v_cndmask_b32_e32 v240, v188, v240, vcc
	v_lshl_add_u64 v[236:237], v[190:191], 0, v[236:237]
	v_add_u32_e32 v190, 0xffffff90, v240
	v_cmp_gt_i32_e32 vcc, 0x80, v240
	v_max_i32_e32 v190, 0, v190
	v_lshlrev_b32_e32 v190, 13, v190
	v_lshl_add_u64 v[238:239], v[190:191], 0, v[186:187]
	v_cndmask_b32_e32 v236, v236, v238, vcc
	v_cndmask_b32_e32 v237, v237, v239, vcc
	global_load_dwordx4 v[220:223], v[236:237], off offset:16 nt
	global_load_dwordx4 v[224:227], v[236:237], off nt
	global_load_dwordx4 v[228:231], v[236:237], off offset:528 nt
	global_load_dwordx4 v[232:235], v[236:237], off offset:512 nt
	s_movk_i32 s0, 0x21ff
	v_cmp_lt_i32_e32 vcc, s0, v148
	v_add_u32_e32 v146, 0xffffde00, v148
	s_and_saveexec_b64 s[0:1], vcc
	s_xor_b64 s[0:1], exec, s[0:1]
	s_cbranch_execz .LBB0_700
	v_mov_b32_e32 v147, v1
	v_readlane_b32 s4, v244, 12
	v_lshlrev_b64 v[150:151], 13, v[146:147]
	v_readlane_b32 s6, v244, 14
	v_readlane_b32 s7, v244, 15
	v_readlane_b32 s5, v244, 13
	v_readlane_b32 s8, v244, 16
	v_readlane_b32 s9, v244, 17
	v_readlane_b32 s10, v244, 18
	v_readlane_b32 s11, v244, 19
	v_readlane_b32 s12, v244, 20
	v_readlane_b32 s13, v244, 21
	v_readlane_b32 s14, v244, 22
	v_readlane_b32 s15, v244, 23
	v_readlane_b32 s16, v244, 24
	v_readlane_b32 s17, v244, 25
	v_readlane_b32 s18, v244, 26
	v_readlane_b32 s19, v244, 27
	v_lshl_add_u64 v[150:151], s[6:7], 0, v[150:151]

.LBB0_848:
	s_add_u32 s24, s36, 0xfff00080
	s_addc_u32 s25, s37, -1
	s_add_i32 s75, 0, 0x10000
	v_add_u32_e32 v152, s75, v159
	ds_read_b128 v[140:143], v152
	ds_read_b128 v[144:147], v152 offset:1024
	ds_read_b128 v[148:151], v152 offset:2048
	ds_read_b128 v[152:155], v152 offset:3072
	s_cmp_eq_u32 s74, 28
	s_cselect_b32 s39, s29, s25
	s_cselect_b32 s38, s70, s24
	s_cselect_b32 s25, s27, s73
	s_cselect_b32 s24, s71, s72
	v_lshl_add_u64 v[156:157], s[36:37], 0, v[136:137]
	s_add_i32 m0, s40, 0xc000
	ds_read_b128 v[162:165], v161
	ds_read_b128 v[166:169], v161 offset:1024
	ds_read_b128 v[180:183], v161 offset:2048
	ds_read_b128 v[184:187], v161 offset:3072
	ds_read_b128 v[188:191], v161 offset:4096
	ds_read_b128 v[204:207], v161 offset:5120
	ds_read_b128 v[208:211], v161 offset:6144
	ds_read_b128 v[212:215], v161 offset:7168
	global_load_lds_dwordx4 v[156:157], off
	v_lshl_add_u64 v[156:157], s[36:37], 0, v[138:139]
	s_add_i32 m0, s40, 0xe000
	s_nop 0
	global_load_lds_dwordx4 v[156:157], off
	s_waitcnt lgkmcnt(8)
	s_barrier
	s_setprio 1
	s_waitcnt lgkmcnt(7)
	v_mfma_f32_16x16x32_bf16 v[126:129], v[140:143], v[162:165], v[126:129]
	v_mfma_f32_16x16x32_bf16 v[122:125], v[148:151], v[162:165], v[122:125]
	s_waitcnt lgkmcnt(5)
	v_mfma_f32_16x16x32_bf16 v[110:113], v[140:143], v[180:183], v[110:113]
	v_mfma_f32_16x16x32_bf16 v[106:109], v[148:151], v[180:183], v[106:109]
	s_waitcnt lgkmcnt(3)
	v_mfma_f32_16x16x32_bf16 v[94:97], v[140:143], v[188:191], v[94:97]
	v_mfma_f32_16x16x32_bf16 v[90:93], v[148:151], v[188:191], v[90:93]
	s_waitcnt lgkmcnt(1)
	v_mfma_f32_16x16x32_bf16 v[78:81], v[140:143], v[208:211], v[78:81]
	v_mfma_f32_16x16x32_bf16 v[74:77], v[148:151], v[208:211], v[74:77]
	v_mfma_f32_16x16x32_bf16 v[126:129], v[144:147], v[166:169], v[126:129]
	v_mfma_f32_16x16x32_bf16 v[122:125], v[152:155], v[166:169], v[122:125]
	v_mfma_f32_16x16x32_bf16 v[110:113], v[144:147], v[184:187], v[110:113]
	v_mfma_f32_16x16x32_bf16 v[106:109], v[152:155], v[184:187], v[106:109]
	v_mfma_f32_16x16x32_bf16 v[94:97], v[144:147], v[204:207], v[94:97]
	v_mfma_f32_16x16x32_bf16 v[90:93], v[152:155], v[204:207], v[90:93]
	s_waitcnt lgkmcnt(0)
	v_mfma_f32_16x16x32_bf16 v[78:81], v[144:147], v[212:215], v[78:81]
	v_mfma_f32_16x16x32_bf16 v[74:77], v[152:155], v[212:215], v[74:77]
	s_setprio 0
	s_barrier
	s_add_i32 s83, 0, 0x14000
	v_add_u32_e32 v156, s83, v159
	s_add_i32 s75, s75, s3
	ds_read_b128 v[216:219], v156
	ds_read_b128 v[220:223], v156 offset:1024
	ds_read_b128 v[224:227], v156 offset:2048
	ds_read_b128 v[228:231], v156 offset:3072
	v_lshl_add_u64 v[156:157], s[24:25], 0, v[0:1]
	s_mov_b32 m0, s75
	v_lshl_add_u64 v[170:171], s[24:25], 0, v[134:135]
	global_load_lds_dwordx4 v[156:157], off
	s_add_i32 m0, s75, 0x2000
	s_nop 0
	global_load_lds_dwordx4 v[170:171], off
	s_barrier
	s_setprio 1
	s_waitcnt lgkmcnt(3)
	v_mfma_f32_16x16x32_bf16 v[118:121], v[216:219], v[162:165], v[118:121]
	s_waitcnt lgkmcnt(1)
	v_mfma_f32_16x16x32_bf16 v[114:117], v[224:227], v[162:165], v[114:117]
	v_mfma_f32_16x16x32_bf16 v[102:105], v[216:219], v[180:183], v[102:105]
	v_mfma_f32_16x16x32_bf16 v[98:101], v[224:227], v[180:183], v[98:101]
	v_mfma_f32_16x16x32_bf16 v[86:89], v[216:219], v[188:191], v[86:89]
	v_mfma_f32_16x16x32_bf16 v[82:85], v[224:227], v[188:191], v[82:85]
	v_mfma_f32_16x16x32_bf16 v[70:73], v[216:219], v[208:211], v[70:73]
	v_mfma_f32_16x16x32_bf16 v[66:69], v[224:227], v[208:211], v[66:69]
	v_mfma_f32_16x16x32_bf16 v[118:121], v[220:223], v[166:169], v[118:121]
	s_waitcnt lgkmcnt(0)
	v_mfma_f32_16x16x32_bf16 v[114:117], v[228:231], v[166:169], v[114:117]
	v_mfma_f32_16x16x32_bf16 v[102:105], v[220:223], v[184:187], v[102:105]
	v_mfma_f32_16x16x32_bf16 v[98:101], v[228:231], v[184:187], v[98:101]
	v_mfma_f32_16x16x32_bf16 v[86:89], v[220:223], v[204:207], v[86:89]
	v_mfma_f32_16x16x32_bf16 v[82:85], v[228:231], v[204:207], v[82:85]
	v_mfma_f32_16x16x32_bf16 v[70:73], v[220:223], v[212:215], v[70:73]
	v_mfma_f32_16x16x32_bf16 v[66:69], v[228:231], v[212:215], v[66:69]
	s_setprio 0
	s_mov_b32 m0, s40
	v_lshl_add_u64 v[232:233], s[38:39], 0, v[130:131]
	s_barrier
	ds_read_b128 v[162:165], v161 offset:16384
	ds_read_b128 v[166:169], v161 offset:17408
	ds_read_b128 v[180:183], v161 offset:18432
	ds_read_b128 v[184:187], v161 offset:19456
	ds_read_b128 v[188:191], v161 offset:20480
	ds_read_b128 v[204:207], v161 offset:21504
	ds_read_b128 v[208:211], v161 offset:22528
	ds_read_b128 v[212:215], v161 offset:23552
	global_load_lds_dwordx4 v[232:233], off
	v_lshl_add_u64 v[234:235], s[38:39], 0, v[132:133]
	s_mov_b32 m0, s41
	s_nop 0
	global_load_lds_dwordx4 v[234:235], off
	s_barrier
	s_setprio 1
	s_waitcnt lgkmcnt(7)
	v_mfma_f32_16x16x32_bf16 v[62:65], v[140:143], v[162:165], v[62:65]
	v_mfma_f32_16x16x32_bf16 v[58:61], v[148:151], v[162:165], v[58:61]
	s_waitcnt lgkmcnt(5)
	v_mfma_f32_16x16x32_bf16 v[46:49], v[140:143], v[180:183], v[46:49]
	v_mfma_f32_16x16x32_bf16 v[42:45], v[148:151], v[180:183], v[42:45]
	s_waitcnt lgkmcnt(3)
	v_mfma_f32_16x16x32_bf16 v[30:33], v[140:143], v[188:191], v[30:33]
	v_mfma_f32_16x16x32_bf16 v[26:29], v[148:151], v[188:191], v[26:29]
	s_waitcnt lgkmcnt(1)
	v_mfma_f32_16x16x32_bf16 v[14:17], v[140:143], v[208:211], v[14:17]
	v_mfma_f32_16x16x32_bf16 v[10:13], v[148:151], v[208:211], v[10:13]
	v_mfma_f32_16x16x32_bf16 v[62:65], v[144:147], v[166:169], v[62:65]
	v_mfma_f32_16x16x32_bf16 v[58:61], v[152:155], v[166:169], v[58:61]
	v_mfma_f32_16x16x32_bf16 v[46:49], v[144:147], v[184:187], v[46:49]
	v_mfma_f32_16x16x32_bf16 v[42:45], v[152:155], v[184:187], v[42:45]
	v_mfma_f32_16x16x32_bf16 v[30:33], v[144:147], v[204:207], v[30:33]
	v_mfma_f32_16x16x32_bf16 v[26:29], v[152:155], v[204:207], v[26:29]
	s_waitcnt lgkmcnt(0)
	v_mfma_f32_16x16x32_bf16 v[14:17], v[144:147], v[212:215], v[14:17]
	v_mfma_f32_16x16x32_bf16 v[10:13], v[152:155], v[212:215], v[10:13]
	s_setprio 0
	s_barrier
	s_add_u32 s94, s24, 0x100000
	s_addc_u32 s95, s25, 0
	s_add_i32 s75, s83, s3
	v_lshl_add_u64 v[140:141], s[94:95], 0, v[0:1]
	s_mov_b32 m0, s75
	s_nop 0
	global_load_lds_dwordx4 v[140:141], off
	v_lshl_add_u64 v[140:141], s[94:95], 0, v[134:135]
	s_add_i32 m0, s75, 0x2000
	s_nop 0
	global_load_lds_dwordx4 v[140:141], off
	s_waitcnt vmcnt(6)
	s_barrier
	s_setprio 1
	v_mfma_f32_16x16x32_bf16 v[54:57], v[216:219], v[162:165], v[54:57]
	v_mfma_f32_16x16x32_bf16 v[50:53], v[224:227], v[162:165], v[50:53]
	v_mfma_f32_16x16x32_bf16 v[38:41], v[216:219], v[180:183], v[38:41]
	v_mfma_f32_16x16x32_bf16 v[34:37], v[224:227], v[180:183], v[34:37]
	v_mfma_f32_16x16x32_bf16 v[22:25], v[216:219], v[188:191], v[22:25]
	v_mfma_f32_16x16x32_bf16 v[18:21], v[224:227], v[188:191], v[18:21]
	v_mfma_f32_16x16x32_bf16 v[6:9], v[216:219], v[208:211], v[6:9]
	v_mfma_f32_16x16x32_bf16 v[2:5], v[224:227], v[208:211], v[2:5]
	v_mfma_f32_16x16x32_bf16 v[54:57], v[220:223], v[166:169], v[54:57]
	v_mfma_f32_16x16x32_bf16 v[50:53], v[228:231], v[166:169], v[50:53]
	v_mfma_f32_16x16x32_bf16 v[38:41], v[220:223], v[184:187], v[38:41]
	v_mfma_f32_16x16x32_bf16 v[34:37], v[228:231], v[184:187], v[34:37]
	v_mfma_f32_16x16x32_bf16 v[22:25], v[220:223], v[204:207], v[22:25]
	v_mfma_f32_16x16x32_bf16 v[18:21], v[228:231], v[204:207], v[18:21]
	v_mfma_f32_16x16x32_bf16 v[6:9], v[220:223], v[212:215], v[6:9]
	v_mfma_f32_16x16x32_bf16 v[2:5], v[228:231], v[212:215], v[2:5]
	s_setprio 0
	s_add_i32 s75, 0, 0x18000
	v_add_u32_e32 v152, s75, v159
	s_barrier
	ds_read_b128 v[140:143], v152
	ds_read_b128 v[144:147], v152 offset:1024
	ds_read_b128 v[148:151], v152 offset:2048
	ds_read_b128 v[152:155], v152 offset:3072
	s_add_u32 s38, s38, 0x100000
	s_addc_u32 s39, s39, 0
	s_mov_b32 m0, s46
	v_lshl_add_u64 v[216:217], s[38:39], 0, v[130:131]
	ds_read_b128 v[162:165], v161 offset:32768
	ds_read_b128 v[166:169], v161 offset:33792
	ds_read_b128 v[180:183], v161 offset:34816
	ds_read_b128 v[184:187], v161 offset:35840
	ds_read_b128 v[188:191], v161 offset:36864
	ds_read_b128 v[204:207], v161 offset:37888
	ds_read_b128 v[208:211], v161 offset:38912
	ds_read_b128 v[212:215], v161 offset:39936
	global_load_lds_dwordx4 v[216:217], off
	v_lshl_add_u64 v[216:217], s[38:39], 0, v[132:133]
	s_mov_b32 m0, s47
	s_nop 0
	global_load_lds_dwordx4 v[216:217], off
	s_waitcnt lgkmcnt(8)
	s_barrier
	s_setprio 1
	s_waitcnt lgkmcnt(7)
	v_mfma_f32_16x16x32_bf16 v[126:129], v[140:143], v[162:165], v[126:129]
	v_mfma_f32_16x16x32_bf16 v[122:125], v[148:151], v[162:165], v[122:125]
	s_waitcnt lgkmcnt(5)
	v_mfma_f32_16x16x32_bf16 v[110:113], v[140:143], v[180:183], v[110:113]
	v_mfma_f32_16x16x32_bf16 v[106:109], v[148:151], v[180:183], v[106:109]
	s_waitcnt lgkmcnt(3)
	v_mfma_f32_16x16x32_bf16 v[94:97], v[140:143], v[188:191], v[94:97]
	v_mfma_f32_16x16x32_bf16 v[90:93], v[148:151], v[188:191], v[90:93]
	s_waitcnt lgkmcnt(1)
	v_mfma_f32_16x16x32_bf16 v[78:81], v[140:143], v[208:211], v[78:81]
	v_mfma_f32_16x16x32_bf16 v[74:77], v[148:151], v[208:211], v[74:77]
	v_mfma_f32_16x16x32_bf16 v[126:129], v[144:147], v[166:169], v[126:129]
	v_mfma_f32_16x16x32_bf16 v[122:125], v[152:155], v[166:169], v[122:125]
	v_mfma_f32_16x16x32_bf16 v[110:113], v[144:147], v[184:187], v[110:113]
	v_mfma_f32_16x16x32_bf16 v[106:109], v[152:155], v[184:187], v[106:109]
	v_mfma_f32_16x16x32_bf16 v[94:97], v[144:147], v[204:207], v[94:97]
	v_mfma_f32_16x16x32_bf16 v[90:93], v[152:155], v[204:207], v[90:93]
	s_waitcnt lgkmcnt(0)
	v_mfma_f32_16x16x32_bf16 v[78:81], v[144:147], v[212:215], v[78:81]
	v_mfma_f32_16x16x32_bf16 v[74:77], v[152:155], v[212:215], v[74:77]
	s_setprio 0
	s_barrier
	s_add_i32 s38, 0, 0x1c000
	s_add_i32 s39, s75, s3
	v_add_u32_e32 v203, s38, v159
	v_lshl_add_u64 v[156:157], v[156:157], 0, s[48:49]
	s_mov_b32 m0, s39
	ds_read_b128 v[216:219], v203
	ds_read_b128 v[220:223], v203 offset:1024
	ds_read_b128 v[224:227], v203 offset:2048
	ds_read_b128 v[228:231], v203 offset:3072
	global_load_lds_dwordx4 v[156:157], off
	v_lshl_add_u64 v[156:157], v[170:171], 0, s[48:49]
	s_add_i32 m0, s39, 0x2000
	s_nop 0
	global_load_lds_dwordx4 v[156:157], off
	s_barrier
	s_setprio 1
	s_waitcnt lgkmcnt(3)
	v_mfma_f32_16x16x32_bf16 v[118:121], v[216:219], v[162:165], v[118:121]
	s_waitcnt lgkmcnt(1)
	v_mfma_f32_16x16x32_bf16 v[114:117], v[224:227], v[162:165], v[114:117]
	v_mfma_f32_16x16x32_bf16 v[102:105], v[216:219], v[180:183], v[102:105]
	v_mfma_f32_16x16x32_bf16 v[98:101], v[224:227], v[180:183], v[98:101]
	v_mfma_f32_16x16x32_bf16 v[86:89], v[216:219], v[188:191], v[86:89]
	v_mfma_f32_16x16x32_bf16 v[82:85], v[224:227], v[188:191], v[82:85]
	v_mfma_f32_16x16x32_bf16 v[70:73], v[216:219], v[208:211], v[70:73]
	v_mfma_f32_16x16x32_bf16 v[66:69], v[224:227], v[208:211], v[66:69]
	v_mfma_f32_16x16x32_bf16 v[118:121], v[220:223], v[166:169], v[118:121]
	s_waitcnt lgkmcnt(0)
	v_mfma_f32_16x16x32_bf16 v[114:117], v[228:231], v[166:169], v[114:117]
	v_mfma_f32_16x16x32_bf16 v[102:105], v[220:223], v[184:187], v[102:105]
	v_mfma_f32_16x16x32_bf16 v[98:101], v[228:231], v[184:187], v[98:101]
	v_mfma_f32_16x16x32_bf16 v[86:89], v[220:223], v[204:207], v[86:89]
	v_mfma_f32_16x16x32_bf16 v[82:85], v[228:231], v[204:207], v[82:85]
	v_mfma_f32_16x16x32_bf16 v[70:73], v[220:223], v[212:215], v[70:73]
	v_mfma_f32_16x16x32_bf16 v[66:69], v[228:231], v[212:215], v[66:69]
	s_setprio 0
	s_mov_b32 m0, s50
	v_lshl_add_u64 v[156:157], v[232:233], 0, s[48:49]
	s_barrier
; template <class Epi>
; __device__ __forceinline__ void gemm_phase(LAS unsigned char* lds, const GemmD g, const Epi& E) {
;     ...
;         for (int t = 0; t < nt; t += 2) PG8_KITER(t);
	ds_read_b128 v[162:165], v161 offset:49152
	ds_read_b128 v[166:169], v161 offset:50176
	ds_read_b128 v[180:183], v161 offset:51200
	ds_read_b128 v[184:187], v161 offset:52224
	ds_read_b128 v[188:191], v161 offset:53248
	ds_read_b128 v[204:207], v161 offset:54272
	ds_read_b128 v[208:211], v161 offset:55296
	ds_read_b128 v[212:215], v161 offset:56320
	global_load_lds_dwordx4 v[156:157], off
	v_lshl_add_u64 v[156:157], v[234:235], 0, s[48:49]
	s_mov_b32 m0, s51
	s_nop 0
	global_load_lds_dwordx4 v[156:157], off
	s_barrier
	s_setprio 1
	s_waitcnt lgkmcnt(7)
	v_mfma_f32_16x16x32_bf16 v[62:65], v[140:143], v[162:165], v[62:65]
	v_mfma_f32_16x16x32_bf16 v[58:61], v[148:151], v[162:165], v[58:61]
	s_waitcnt lgkmcnt(5)
	v_mfma_f32_16x16x32_bf16 v[46:49], v[140:143], v[180:183], v[46:49]
	v_mfma_f32_16x16x32_bf16 v[42:45], v[148:151], v[180:183], v[42:45]
	s_waitcnt lgkmcnt(3)
	v_mfma_f32_16x16x32_bf16 v[30:33], v[140:143], v[188:191], v[30:33]
	v_mfma_f32_16x16x32_bf16 v[26:29], v[148:151], v[188:191], v[26:29]
	s_waitcnt lgkmcnt(1)
	v_mfma_f32_16x16x32_bf16 v[14:17], v[140:143], v[208:211], v[14:17]
	v_mfma_f32_16x16x32_bf16 v[10:13], v[148:151], v[208:211], v[10:13]
	v_mfma_f32_16x16x32_bf16 v[62:65], v[144:147], v[166:169], v[62:65]
	v_mfma_f32_16x16x32_bf16 v[58:61], v[152:155], v[166:169], v[58:61]
	v_mfma_f32_16x16x32_bf16 v[46:49], v[144:147], v[184:187], v[46:49]
	v_mfma_f32_16x16x32_bf16 v[42:45], v[152:155], v[184:187], v[42:45]
	v_mfma_f32_16x16x32_bf16 v[30:33], v[144:147], v[204:207], v[30:33]
	v_mfma_f32_16x16x32_bf16 v[26:29], v[152:155], v[204:207], v[26:29]
	s_waitcnt lgkmcnt(0)
	v_mfma_f32_16x16x32_bf16 v[14:17], v[144:147], v[212:215], v[14:17]
	v_mfma_f32_16x16x32_bf16 v[10:13], v[152:155], v[212:215], v[10:13]
	s_setprio 0
	s_barrier
	s_add_u32 s24, s24, 0x100080
	s_addc_u32 s25, s25, 0
	s_add_i32 s38, s38, s3
	v_lshl_add_u64 v[140:141], s[24:25], 0, v[0:1]
	s_mov_b32 m0, s38
	s_nop 0
	global_load_lds_dwordx4 v[140:141], off
	v_lshl_add_u64 v[140:141], s[24:25], 0, v[134:135]
	s_add_i32 m0, s38, 0x2000
	s_nop 0
	global_load_lds_dwordx4 v[140:141], off
	s_waitcnt vmcnt(6)
	s_barrier
	s_setprio 1
	v_mfma_f32_16x16x32_bf16 v[54:57], v[216:219], v[162:165], v[54:57]
	v_mfma_f32_16x16x32_bf16 v[50:53], v[224:227], v[162:165], v[50:53]
	v_mfma_f32_16x16x32_bf16 v[38:41], v[216:219], v[180:183], v[38:41]
	v_mfma_f32_16x16x32_bf16 v[34:37], v[224:227], v[180:183], v[34:37]
	v_mfma_f32_16x16x32_bf16 v[22:25], v[216:219], v[188:191], v[22:25]
	v_mfma_f32_16x16x32_bf16 v[18:21], v[224:227], v[188:191], v[18:21]
	v_mfma_f32_16x16x32_bf16 v[6:9], v[216:219], v[208:211], v[6:9]
	v_mfma_f32_16x16x32_bf16 v[2:5], v[224:227], v[208:211], v[2:5]
	v_mfma_f32_16x16x32_bf16 v[54:57], v[220:223], v[166:169], v[54:57]
	v_mfma_f32_16x16x32_bf16 v[50:53], v[228:231], v[166:169], v[50:53]
	v_mfma_f32_16x16x32_bf16 v[38:41], v[220:223], v[184:187], v[38:41]
	v_mfma_f32_16x16x32_bf16 v[34:37], v[228:231], v[184:187], v[34:37]
	v_mfma_f32_16x16x32_bf16 v[22:25], v[220:223], v[204:207], v[22:25]
	v_mfma_f32_16x16x32_bf16 v[18:21], v[228:231], v[204:207], v[18:21]
	v_mfma_f32_16x16x32_bf16 v[6:9], v[220:223], v[212:215], v[6:9]
	v_mfma_f32_16x16x32_bf16 v[2:5], v[228:231], v[212:215], v[2:5]
	s_setprio 0
	s_add_i32 s74, s74, 2
	s_add_u32 s36, s36, 0x100
	s_addc_u32 s37, s37, 0
	s_add_u32 s72, s72, 0x100
	s_addc_u32 s73, s73, 0
	s_cmp_gt_u32 s74, 29
	s_barrier
	s_cbranch_scc0 .LBB0_848
; __device__ __forceinline__ float bflo(unsigned w) { return __uint_as_float(w << 16); }
; __device__ __forceinline__ float bfhi(unsigned w) { return __uint_as_float(w & 0xffff0000u); }
;     __device__ __forceinline__ void mid(f32x4 (&acc)[2][2][4][2], const Unit& u, int wr, int wc, int fr, int fq) const {
;         const int row0 = u.pm * BM + wr * 64 + fr, col0 = u.pn * BM + wc * 32 + 8 * fq;
;         u32x4 rv[2][4][2];
; #pragma unroll
;         for (int ai = 0; ai < 2; ++ai)
; #pragma unroll
;             for (int m = 0; m < 4; ++m) { const bf16_t* rp = proj + (size_t)(row0 + ai * HALF + m * 16) * NPROJ + C_GS + col0; rv[ai][m][0] = __builtin_nontemporal_load((const u32x4*)(rp)); rv[ai][m][1] = __builtin_nontemporal_load((const u32x4*)(rp + HALF)); }
; #pragma unroll
;         for (int ai = 0; ai < 2; ++ai)
; #pragma unroll
;             for (int m = 0; m < 4; ++m)
; #pragma unroll
;                 for (int bj = 0; bj < 2; ++bj) { const u32x4 r = rv[ai][m][bj];
;                     acc[ai][bj][m][0] *= (f32x4){bflo(r.x), bfhi(r.x), bflo(r.y), bfhi(r.y)}; acc[ai][bj][m][1] *= (f32x4){bflo(r.z), bfhi(r.z), bflo(r.w), bfhi(r.w)}; }
	v_lshl_add_u32 v142, s66, 8, v158
	v_mov_b64_e32 v[144:145], s[92:93]
	v_lshl_or_b32 v140, s57, 8, v160
	v_mad_i64_i32 v[144:145], s[24:25], v142, s91, v[144:145]
	v_lshl_add_u64 v[148:149], v[144:145], 0, s[76:77]
	v_ashrrev_i32_e32 v141, 31, v140
	v_lshl_add_u64 v[146:147], v[140:141], 1, v[148:149]
	v_mov_b32_e32 v240, v146
	v_mov_b32_e32 v241, v147
	s_mov_b32 s74, 0x0
	s_mov_b32 s75, 0
	v_lshl_add_u64 v[204:205], v[240:241], 0, s[74:75]
	global_load_dwordx4 v[204:207], v[204:205], off
	s_mov_b32 s74, 0xfffff000
	s_mov_b32 s75, -1
	v_lshl_add_u64 v[208:209], v[240:241], 0, s[74:75]
	global_load_dwordx4 v[208:211], v[208:209], off
	s_mov_b32 s74, 0x100
	s_mov_b32 s75, 0
	v_lshl_add_u64 v[212:213], v[240:241], 0, s[74:75]
	global_load_dwordx4 v[212:215], v[212:213], off
	s_mov_b32 s74, 0xfffff100
	s_mov_b32 s75, -1
	v_lshl_add_u64 v[216:217], v[240:241], 0, s[74:75]
	global_load_dwordx4 v[216:219], v[216:217], off
	s_mov_b32 s74, 0x6a000
	s_mov_b32 s75, 0
	v_lshl_add_u64 v[220:221], v[240:241], 0, s[74:75]
	global_load_dwordx4 v[220:223], v[220:221], off
	s_mov_b32 s74, 0x69000
	s_mov_b32 s75, 0
	v_lshl_add_u64 v[224:225], v[240:241], 0, s[74:75]
	global_load_dwordx4 v[224:227], v[224:225], off
	s_mov_b32 s74, 0x6a100
	s_mov_b32 s75, 0
	v_lshl_add_u64 v[228:229], v[240:241], 0, s[74:75]
	global_load_dwordx4 v[228:231], v[228:229], off
	s_mov_b32 s74, 0x69100
	s_mov_b32 s75, 0
	v_lshl_add_u64 v[232:233], v[240:241], 0, s[74:75]
	global_load_dwordx4 v[232:235], v[232:233], off
	s_mov_b32 s74, 0xd4000
	s_mov_b32 s75, 0
	v_lshl_add_u64 v[236:237], v[240:241], 0, s[74:75]
	global_load_dwordx4 v[236:239], v[236:237], off
	s_mov_b32 s74, 0xd3000
	s_mov_b32 s75, 0
	v_lshl_add_u64 v[180:181], v[240:241], 0, s[74:75]
	global_load_dwordx4 v[180:183], v[180:181], off
	s_mov_b32 s74, 0xd4100
	s_mov_b32 s75, 0
	v_lshl_add_u64 v[184:185], v[240:241], 0, s[74:75]
	global_load_dwordx4 v[184:187], v[184:185], off
	s_mov_b32 s74, 0xd3100
	s_mov_b32 s75, 0
	v_lshl_add_u64 v[188:189], v[240:241], 0, s[74:75]
	global_load_dwordx4 v[188:191], v[188:189], off
	s_mov_b32 s74, 0x13e000
	s_mov_b32 s75, 0
	v_lshl_add_u64 v[166:167], v[240:241], 0, s[74:75]
	global_load_dwordx4 v[166:169], v[166:167], off
	s_mov_b32 s74, 0x13d000
	s_mov_b32 s75, 0
	v_lshl_add_u64 v[246:247], v[240:241], 0, s[74:75]
	global_load_dwordx4 v[246:249], v[246:247], off
	v_cndmask_b32_e64 v143, 0, 1, s[62:63]
	v_cmp_ne_u32_e64 s[36:37], 1, v143
	s_andn2_b64 vcc, exec, s[62:63]
	s_waitcnt vmcnt(13)
	v_mov_b32_e32 v150, v204
	v_mov_b32_e32 v151, v205
	v_mov_b32_e32 v152, v206
	v_mov_b32_e32 v153, v207
	s_mov_b32 s74, 0x13e100
	s_mov_b32 s75, 0
	v_lshl_add_u64 v[204:205], v[240:241], 0, s[74:75]
	global_load_dwordx4 v[204:207], v[204:205], off
	v_lshlrev_b32_e32 v154, 16, v150
	v_and_b32_e32 v155, 0xffff0000, v150
	v_lshlrev_b32_e32 v156, 16, v151
	v_and_b32_e32 v157, 0xffff0000, v151
	v_lshlrev_b32_e32 v150, 16, v152
	v_and_b32_e32 v151, 0xffff0000, v152
	v_lshlrev_b32_e32 v152, 16, v153
	v_and_b32_e32 v153, 0xffff0000, v153
	s_cbranch_vccnz .LBB0_851
	v_lshl_add_u64 v[146:147], v[140:141], 1, v[144:145]
	v_add_co_u32_e32 v146, vcc, 0x4000, v146
	s_nop 1
	v_addc_co_u32_e32 v147, vcc, 0, v147, vcc
	s_waitcnt vmcnt(13)
	v_mov_b32_e32 v162, v208
	v_mov_b32_e32 v163, v209
	v_mov_b32_e32 v164, v210
	v_mov_b32_e32 v165, v211
	v_lshlrev_b32_e32 v146, 16, v162
	v_and_b32_e32 v147, 0xffff0000, v162
	v_lshlrev_b32_e32 v162, 16, v163
	v_and_b32_e32 v163, 0xffff0000, v163
	v_pk_mul_f32 v[156:157], v[156:157], v[162:163]
	v_pk_mul_f32 v[154:155], v[154:155], v[146:147]
	v_lshlrev_b32_e32 v146, 16, v164
	v_and_b32_e32 v147, 0xffff0000, v164
	v_lshlrev_b32_e32 v162, 16, v165
	v_and_b32_e32 v163, 0xffff0000, v165
	v_pk_mul_f32 v[152:153], v[152:153], v[162:163]
	v_pk_mul_f32 v[150:151], v[150:151], v[146:147]

.LBB0_903:
	s_add_u32 s24, s30, 0xfff00080
	s_addc_u32 s25, s31, -1
	s_add_i32 s29, 0, 0x10000
	v_add_u32_e32 v0, s29, v204
	ds_read_b128 v[132:135], v0
	ds_read_b128 v[136:139], v0 offset:1024
	ds_read_b128 v[140:143], v0 offset:2048
	ds_read_b128 v[144:147], v0 offset:3072
	s_cmp_eq_u32 s27, 28
	s_cselect_b32 s35, s1, s25
	s_cselect_b32 s34, s0, s24
	s_cselect_b32 s25, s39, s3
	s_cselect_b32 s24, s38, s2
	v_lshl_add_u64 v[2:3], s[30:31], 0, v[188:189]
	s_add_i32 m0, s46, 0xc000
	ds_read_b128 v[148:151], v206
	ds_read_b128 v[152:155], v206 offset:1024
	ds_read_b128 v[156:159], v206 offset:2048
	ds_read_b128 v[160:163], v206 offset:3072
	ds_read_b128 v[164:167], v206 offset:4096
	ds_read_b128 v[168:171], v206 offset:5120
	ds_read_b128 v[208:211], v206 offset:6144
	ds_read_b128 v[212:215], v206 offset:7168
	global_load_lds_dwordx4 v[2:3], off
	v_lshl_add_u64 v[2:3], s[30:31], 0, v[190:191]
	s_add_i32 m0, s46, 0xe000
	s_nop 0
	global_load_lds_dwordx4 v[2:3], off
	s_waitcnt lgkmcnt(8)
	s_barrier
	s_setprio 1
	s_waitcnt lgkmcnt(7)
	v_mfma_f32_16x16x32_bf16 v[2:5], v[132:135], v[148:151], v[4:7]
	v_mfma_f32_16x16x32_bf16 v[6:9], v[140:143], v[148:151], v[8:11]
	s_waitcnt lgkmcnt(5)
	v_mfma_f32_16x16x32_bf16 v[12:15], v[132:135], v[156:159], v[12:15]
	v_mfma_f32_16x16x32_bf16 v[16:19], v[140:143], v[156:159], v[16:19]
	s_waitcnt lgkmcnt(3)
	v_mfma_f32_16x16x32_bf16 v[20:23], v[132:135], v[164:167], v[20:23]
	v_mfma_f32_16x16x32_bf16 v[24:27], v[140:143], v[164:167], v[24:27]
	s_waitcnt lgkmcnt(1)
	v_mfma_f32_16x16x32_bf16 v[28:31], v[132:135], v[208:211], v[28:31]
	v_mfma_f32_16x16x32_bf16 v[32:35], v[140:143], v[208:211], v[32:35]
	v_mfma_f32_16x16x32_bf16 v[2:5], v[136:139], v[152:155], v[2:5]
	v_mfma_f32_16x16x32_bf16 v[8:11], v[144:147], v[152:155], v[6:9]
	v_mfma_f32_16x16x32_bf16 v[12:15], v[136:139], v[160:163], v[12:15]
	v_mfma_f32_16x16x32_bf16 v[16:19], v[144:147], v[160:163], v[16:19]
	v_mfma_f32_16x16x32_bf16 v[20:23], v[136:139], v[168:171], v[20:23]
	v_mfma_f32_16x16x32_bf16 v[24:27], v[144:147], v[168:171], v[24:27]
	s_waitcnt lgkmcnt(0)
	v_mfma_f32_16x16x32_bf16 v[28:31], v[136:139], v[212:215], v[28:31]
	v_mfma_f32_16x16x32_bf16 v[32:35], v[144:147], v[212:215], v[32:35]
	s_setprio 0
	s_barrier
	s_add_i32 s73, 0, 0x14000
	s_add_i32 s29, s29, s41
	v_add_u32_e32 v0, s73, v204
	v_lshl_add_u64 v[232:233], s[24:25], 0, v[184:185]
	s_mov_b32 m0, s29
	ds_read_b128 v[216:219], v0
	ds_read_b128 v[220:223], v0 offset:1024
	ds_read_b128 v[224:227], v0 offset:2048
	ds_read_b128 v[228:231], v0 offset:3072
	global_load_lds_dwordx4 v[232:233], off
	v_lshl_add_u64 v[234:235], s[24:25], 0, v[180:181]
	s_add_i32 m0, s29, 0x2000
	s_nop 0
	global_load_lds_dwordx4 v[234:235], off
	s_barrier
	s_setprio 1
	s_waitcnt lgkmcnt(3)
	v_mfma_f32_16x16x32_bf16 v[36:39], v[216:219], v[148:151], v[36:39]
	s_waitcnt lgkmcnt(1)
	v_mfma_f32_16x16x32_bf16 v[40:43], v[224:227], v[148:151], v[40:43]
	v_mfma_f32_16x16x32_bf16 v[44:47], v[216:219], v[156:159], v[44:47]
	v_mfma_f32_16x16x32_bf16 v[48:51], v[224:227], v[156:159], v[48:51]
	v_mfma_f32_16x16x32_bf16 v[52:55], v[216:219], v[164:167], v[52:55]
	v_mfma_f32_16x16x32_bf16 v[56:59], v[224:227], v[164:167], v[56:59]
	v_mfma_f32_16x16x32_bf16 v[60:63], v[216:219], v[208:211], v[60:63]
	v_mfma_f32_16x16x32_bf16 v[64:67], v[224:227], v[208:211], v[64:67]
	v_mfma_f32_16x16x32_bf16 v[36:39], v[220:223], v[152:155], v[36:39]
	s_waitcnt lgkmcnt(0)
	v_mfma_f32_16x16x32_bf16 v[40:43], v[228:231], v[152:155], v[40:43]
	v_mfma_f32_16x16x32_bf16 v[44:47], v[220:223], v[160:163], v[44:47]
	v_mfma_f32_16x16x32_bf16 v[48:51], v[228:231], v[160:163], v[48:51]
	v_mfma_f32_16x16x32_bf16 v[52:55], v[220:223], v[168:171], v[52:55]
	v_mfma_f32_16x16x32_bf16 v[56:59], v[228:231], v[168:171], v[56:59]
	v_mfma_f32_16x16x32_bf16 v[60:63], v[220:223], v[212:215], v[60:63]
	v_mfma_f32_16x16x32_bf16 v[64:67], v[228:231], v[212:215], v[64:67]
	s_setprio 0
	s_mov_b32 m0, s46
	v_lshl_add_u64 v[236:237], s[34:35], 0, v[186:187]
	s_barrier
	ds_read_b128 v[148:151], v206 offset:16384
	ds_read_b128 v[152:155], v206 offset:17408
	ds_read_b128 v[156:159], v206 offset:18432
	ds_read_b128 v[160:163], v206 offset:19456
	ds_read_b128 v[164:167], v206 offset:20480
	ds_read_b128 v[168:171], v206 offset:21504
	ds_read_b128 v[208:211], v206 offset:22528
	ds_read_b128 v[212:215], v206 offset:23552
	global_load_lds_dwordx4 v[236:237], off
	v_lshl_add_u64 v[238:239], s[34:35], 0, v[182:183]
	s_mov_b32 m0, s47
	s_nop 0
	global_load_lds_dwordx4 v[238:239], off
	s_barrier
	s_setprio 1
	s_waitcnt lgkmcnt(7)
	v_mfma_f32_16x16x32_bf16 v[68:71], v[132:135], v[148:151], v[68:71]
	v_mfma_f32_16x16x32_bf16 v[72:75], v[140:143], v[148:151], v[72:75]
	s_waitcnt lgkmcnt(5)
	v_mfma_f32_16x16x32_bf16 v[76:79], v[132:135], v[156:159], v[76:79]
	v_mfma_f32_16x16x32_bf16 v[80:83], v[140:143], v[156:159], v[80:83]
	s_waitcnt lgkmcnt(3)
	v_mfma_f32_16x16x32_bf16 v[84:87], v[132:135], v[164:167], v[84:87]
	v_mfma_f32_16x16x32_bf16 v[88:91], v[140:143], v[164:167], v[88:91]
	s_waitcnt lgkmcnt(1)
	v_mfma_f32_16x16x32_bf16 v[92:95], v[132:135], v[208:211], v[92:95]
	v_mfma_f32_16x16x32_bf16 v[96:99], v[140:143], v[208:211], v[96:99]
	v_mfma_f32_16x16x32_bf16 v[68:71], v[136:139], v[152:155], v[68:71]
	v_mfma_f32_16x16x32_bf16 v[72:75], v[144:147], v[152:155], v[72:75]
	v_mfma_f32_16x16x32_bf16 v[76:79], v[136:139], v[160:163], v[76:79]
	v_mfma_f32_16x16x32_bf16 v[80:83], v[144:147], v[160:163], v[80:83]
	v_mfma_f32_16x16x32_bf16 v[84:87], v[136:139], v[168:171], v[84:87]
	v_mfma_f32_16x16x32_bf16 v[88:91], v[144:147], v[168:171], v[88:91]
	s_waitcnt lgkmcnt(0)
	v_mfma_f32_16x16x32_bf16 v[92:95], v[136:139], v[212:215], v[92:95]
	v_mfma_f32_16x16x32_bf16 v[96:99], v[144:147], v[212:215], v[96:99]
	s_setprio 0
	s_barrier
	s_add_u32 s74, s24, 0x100000
	s_addc_u32 s75, s25, 0
	s_add_i32 s29, s73, s41
	v_lshl_add_u64 v[6:7], s[74:75], 0, v[184:185]
	s_mov_b32 m0, s29
	s_nop 0
	global_load_lds_dwordx4 v[6:7], off
	v_lshl_add_u64 v[6:7], s[74:75], 0, v[180:181]
	s_add_i32 m0, s29, 0x2000
	s_nop 0
	global_load_lds_dwordx4 v[6:7], off
	s_waitcnt vmcnt(6)
	s_barrier
	s_setprio 1
	v_mfma_f32_16x16x32_bf16 v[100:103], v[216:219], v[148:151], v[100:103]
	v_mfma_f32_16x16x32_bf16 v[104:107], v[224:227], v[148:151], v[104:107]
	v_mfma_f32_16x16x32_bf16 v[108:111], v[216:219], v[156:159], v[108:111]
	v_mfma_f32_16x16x32_bf16 v[112:115], v[224:227], v[156:159], v[112:115]
	v_mfma_f32_16x16x32_bf16 v[116:119], v[216:219], v[164:167], v[116:119]
	v_mfma_f32_16x16x32_bf16 v[120:123], v[224:227], v[164:167], v[120:123]
	v_mfma_f32_16x16x32_bf16 v[124:127], v[216:219], v[208:211], v[124:127]
	v_mfma_f32_16x16x32_bf16 v[128:131], v[224:227], v[208:211], v[128:131]
	v_mfma_f32_16x16x32_bf16 v[100:103], v[220:223], v[152:155], v[100:103]
	v_mfma_f32_16x16x32_bf16 v[104:107], v[228:231], v[152:155], v[104:107]
	v_mfma_f32_16x16x32_bf16 v[108:111], v[220:223], v[160:163], v[108:111]
	v_mfma_f32_16x16x32_bf16 v[112:115], v[228:231], v[160:163], v[112:115]
	v_mfma_f32_16x16x32_bf16 v[116:119], v[220:223], v[168:171], v[116:119]
	v_mfma_f32_16x16x32_bf16 v[120:123], v[228:231], v[168:171], v[120:123]
	v_mfma_f32_16x16x32_bf16 v[124:127], v[220:223], v[212:215], v[124:127]
	v_mfma_f32_16x16x32_bf16 v[128:131], v[228:231], v[212:215], v[128:131]
	s_setprio 0
	s_add_i32 s29, 0, 0x18000
	v_add_u32_e32 v0, s29, v204
	s_barrier
	ds_read_b128 v[132:135], v0
	ds_read_b128 v[136:139], v0 offset:1024
	ds_read_b128 v[140:143], v0 offset:2048
	ds_read_b128 v[144:147], v0 offset:3072
	s_add_u32 s34, s34, 0x100000
	s_addc_u32 s35, s35, 0
	s_mov_b32 m0, s50
	v_lshl_add_u64 v[6:7], s[34:35], 0, v[186:187]
	ds_read_b128 v[148:151], v206 offset:32768
	ds_read_b128 v[152:155], v206 offset:33792
	ds_read_b128 v[156:159], v206 offset:34816
	ds_read_b128 v[160:163], v206 offset:35840
	ds_read_b128 v[164:167], v206 offset:36864
	ds_read_b128 v[168:171], v206 offset:37888
	ds_read_b128 v[208:211], v206 offset:38912
	ds_read_b128 v[212:215], v206 offset:39936
	global_load_lds_dwordx4 v[6:7], off
	v_lshl_add_u64 v[6:7], s[34:35], 0, v[182:183]
	s_mov_b32 m0, s51
	s_nop 0
	global_load_lds_dwordx4 v[6:7], off
	s_waitcnt lgkmcnt(8)
	s_barrier
	s_setprio 1
	s_waitcnt lgkmcnt(7)
	v_mfma_f32_16x16x32_bf16 v[2:5], v[132:135], v[148:151], v[2:5]
	v_mfma_f32_16x16x32_bf16 v[8:11], v[140:143], v[148:151], v[8:11]
	s_waitcnt lgkmcnt(5)
	v_mfma_f32_16x16x32_bf16 v[12:15], v[132:135], v[156:159], v[12:15]
	v_mfma_f32_16x16x32_bf16 v[16:19], v[140:143], v[156:159], v[16:19]
	s_waitcnt lgkmcnt(3)
	v_mfma_f32_16x16x32_bf16 v[20:23], v[132:135], v[164:167], v[20:23]
	v_mfma_f32_16x16x32_bf16 v[24:27], v[140:143], v[164:167], v[24:27]
	s_waitcnt lgkmcnt(1)
	v_mfma_f32_16x16x32_bf16 v[28:31], v[132:135], v[208:211], v[28:31]
	v_mfma_f32_16x16x32_bf16 v[32:35], v[140:143], v[208:211], v[32:35]
	v_mfma_f32_16x16x32_bf16 v[4:7], v[136:139], v[152:155], v[2:5]
	v_mfma_f32_16x16x32_bf16 v[8:11], v[144:147], v[152:155], v[8:11]
	v_mfma_f32_16x16x32_bf16 v[12:15], v[136:139], v[160:163], v[12:15]
	v_mfma_f32_16x16x32_bf16 v[16:19], v[144:147], v[160:163], v[16:19]
	v_mfma_f32_16x16x32_bf16 v[20:23], v[136:139], v[168:171], v[20:23]
	v_mfma_f32_16x16x32_bf16 v[24:27], v[144:147], v[168:171], v[24:27]
	s_waitcnt lgkmcnt(0)
	v_mfma_f32_16x16x32_bf16 v[28:31], v[136:139], v[212:215], v[28:31]
	v_mfma_f32_16x16x32_bf16 v[32:35], v[144:147], v[212:215], v[32:35]
	s_setprio 0
	s_barrier
	s_add_i32 s34, 0, 0x1c000
	s_add_i32 s29, s29, s41
	v_add_u32_e32 v0, s34, v204
	v_lshl_add_u64 v[2:3], v[232:233], 0, s[48:49]
	s_mov_b32 m0, s29
	ds_read_b128 v[216:219], v0
	ds_read_b128 v[220:223], v0 offset:1024
	ds_read_b128 v[224:227], v0 offset:2048
	ds_read_b128 v[228:231], v0 offset:3072
	global_load_lds_dwordx4 v[2:3], off
	v_lshl_add_u64 v[2:3], v[234:235], 0, s[48:49]
	s_add_i32 m0, s29, 0x2000
	s_nop 0
	global_load_lds_dwordx4 v[2:3], off
	s_barrier
	s_setprio 1
	s_waitcnt lgkmcnt(3)
	v_mfma_f32_16x16x32_bf16 v[36:39], v[216:219], v[148:151], v[36:39]
	s_waitcnt lgkmcnt(1)
	v_mfma_f32_16x16x32_bf16 v[40:43], v[224:227], v[148:151], v[40:43]
	v_mfma_f32_16x16x32_bf16 v[44:47], v[216:219], v[156:159], v[44:47]
	v_mfma_f32_16x16x32_bf16 v[48:51], v[224:227], v[156:159], v[48:51]
	v_mfma_f32_16x16x32_bf16 v[52:55], v[216:219], v[164:167], v[52:55]
	v_mfma_f32_16x16x32_bf16 v[56:59], v[224:227], v[164:167], v[56:59]
	v_mfma_f32_16x16x32_bf16 v[60:63], v[216:219], v[208:211], v[60:63]
	v_mfma_f32_16x16x32_bf16 v[64:67], v[224:227], v[208:211], v[64:67]
	v_mfma_f32_16x16x32_bf16 v[36:39], v[220:223], v[152:155], v[36:39]
	s_waitcnt lgkmcnt(0)
	v_mfma_f32_16x16x32_bf16 v[40:43], v[228:231], v[152:155], v[40:43]
	v_mfma_f32_16x16x32_bf16 v[44:47], v[220:223], v[160:163], v[44:47]
	v_mfma_f32_16x16x32_bf16 v[48:51], v[228:231], v[160:163], v[48:51]
	v_mfma_f32_16x16x32_bf16 v[52:55], v[220:223], v[168:171], v[52:55]
	v_mfma_f32_16x16x32_bf16 v[56:59], v[228:231], v[168:171], v[56:59]
	v_mfma_f32_16x16x32_bf16 v[60:63], v[220:223], v[212:215], v[60:63]
	v_mfma_f32_16x16x32_bf16 v[64:67], v[228:231], v[212:215], v[64:67]
	s_setprio 0
	s_mov_b32 m0, s56
	v_lshl_add_u64 v[2:3], v[236:237], 0, s[48:49]
	s_barrier
;     __device__ __forceinline__ void operator()(const f32x4 (&acc)[2][2][4][2], const Unit& u, int wr, int wc, int fr, int fq) const {
;         const int row0 = u.pm * BM + wr * 64 + fr, col0 = u.pn * BM + wc * 32 + 8 * fq;
; #pragma unroll
;         for (int ai = 0; ai < 2; ++ai)
; #pragma unroll
;             for (int m = 0; m < 4; ++m) { const int row = row0 + ai * HALF + m * 16;
; #pragma unroll
;                 for (int bj = 0; bj < 2; ++bj) { const int col = col0 + bj * HALF;
;                     const u32x4 gp = *(const u32x4*)(proj + (size_t)row * NPROJ + C_GP + col);
	ds_read_b128 v[148:151], v206 offset:49152
	ds_read_b128 v[152:155], v206 offset:50176
	ds_read_b128 v[156:159], v206 offset:51200
	ds_read_b128 v[160:163], v206 offset:52224
	ds_read_b128 v[164:167], v206 offset:53248
	ds_read_b128 v[168:171], v206 offset:54272
	ds_read_b128 v[208:211], v206 offset:55296
	ds_read_b128 v[212:215], v206 offset:56320
	global_load_lds_dwordx4 v[2:3], off
	v_lshl_add_u64 v[2:3], v[238:239], 0, s[48:49]
	s_mov_b32 m0, s57
	s_nop 0
	global_load_lds_dwordx4 v[2:3], off
	s_barrier
	s_setprio 1
	s_waitcnt lgkmcnt(7)
	v_mfma_f32_16x16x32_bf16 v[68:71], v[132:135], v[148:151], v[68:71]
	v_mfma_f32_16x16x32_bf16 v[72:75], v[140:143], v[148:151], v[72:75]
	s_waitcnt lgkmcnt(5)
	v_mfma_f32_16x16x32_bf16 v[76:79], v[132:135], v[156:159], v[76:79]
	v_mfma_f32_16x16x32_bf16 v[80:83], v[140:143], v[156:159], v[80:83]
	s_waitcnt lgkmcnt(3)
	v_mfma_f32_16x16x32_bf16 v[84:87], v[132:135], v[164:167], v[84:87]
	v_mfma_f32_16x16x32_bf16 v[88:91], v[140:143], v[164:167], v[88:91]
	s_waitcnt lgkmcnt(1)
	v_mfma_f32_16x16x32_bf16 v[92:95], v[132:135], v[208:211], v[92:95]
	v_mfma_f32_16x16x32_bf16 v[96:99], v[140:143], v[208:211], v[96:99]
	v_mfma_f32_16x16x32_bf16 v[68:71], v[136:139], v[152:155], v[68:71]
	v_mfma_f32_16x16x32_bf16 v[72:75], v[144:147], v[152:155], v[72:75]
	v_mfma_f32_16x16x32_bf16 v[76:79], v[136:139], v[160:163], v[76:79]
	v_mfma_f32_16x16x32_bf16 v[80:83], v[144:147], v[160:163], v[80:83]
	v_mfma_f32_16x16x32_bf16 v[84:87], v[136:139], v[168:171], v[84:87]
	v_mfma_f32_16x16x32_bf16 v[88:91], v[144:147], v[168:171], v[88:91]
	s_waitcnt lgkmcnt(0)
	v_mfma_f32_16x16x32_bf16 v[92:95], v[136:139], v[212:215], v[92:95]
	v_mfma_f32_16x16x32_bf16 v[96:99], v[144:147], v[212:215], v[96:99]
	s_setprio 0
	s_barrier
	s_add_u32 s24, s24, 0x100080
	s_addc_u32 s25, s25, 0
	s_add_i32 s29, s34, s41
	v_lshl_add_u64 v[2:3], s[24:25], 0, v[184:185]
	s_mov_b32 m0, s29
	s_nop 0
	global_load_lds_dwordx4 v[2:3], off
	v_lshl_add_u64 v[2:3], s[24:25], 0, v[180:181]
	s_add_i32 m0, s29, 0x2000
	s_nop 0
	global_load_lds_dwordx4 v[2:3], off
	s_waitcnt vmcnt(6)
	s_barrier
	s_setprio 1
	v_mfma_f32_16x16x32_bf16 v[100:103], v[216:219], v[148:151], v[100:103]
	v_mfma_f32_16x16x32_bf16 v[104:107], v[224:227], v[148:151], v[104:107]
	v_mfma_f32_16x16x32_bf16 v[108:111], v[216:219], v[156:159], v[108:111]
	v_mfma_f32_16x16x32_bf16 v[112:115], v[224:227], v[156:159], v[112:115]
	v_mfma_f32_16x16x32_bf16 v[116:119], v[216:219], v[164:167], v[116:119]
	v_mfma_f32_16x16x32_bf16 v[120:123], v[224:227], v[164:167], v[120:123]
	v_mfma_f32_16x16x32_bf16 v[124:127], v[216:219], v[208:211], v[124:127]
	v_mfma_f32_16x16x32_bf16 v[128:131], v[224:227], v[208:211], v[128:131]
	v_mfma_f32_16x16x32_bf16 v[100:103], v[220:223], v[152:155], v[100:103]
	v_mfma_f32_16x16x32_bf16 v[104:107], v[228:231], v[152:155], v[104:107]
	v_mfma_f32_16x16x32_bf16 v[108:111], v[220:223], v[160:163], v[108:111]
	v_mfma_f32_16x16x32_bf16 v[112:115], v[228:231], v[160:163], v[112:115]
	v_mfma_f32_16x16x32_bf16 v[116:119], v[220:223], v[168:171], v[116:119]
	v_mfma_f32_16x16x32_bf16 v[120:123], v[228:231], v[168:171], v[120:123]
	v_mfma_f32_16x16x32_bf16 v[124:127], v[220:223], v[212:215], v[124:127]
	v_mfma_f32_16x16x32_bf16 v[128:131], v[228:231], v[212:215], v[128:131]
	s_setprio 0
	s_add_i32 s27, s27, 2
	s_add_u32 s30, s30, 0x100
	s_addc_u32 s31, s31, 0
	s_add_u32 s2, s2, 0x100
	s_addc_u32 s3, s3, 0
	s_cmp_gt_u32 s27, 29
	s_barrier
	s_cbranch_scc0 .LBB0_903
	s_cmp_lg_u32 s70, 0
	s_cselect_b64 s[30:31], -1, 0
	v_lshl_add_u32 v144, s72, 8, v203
	v_lshl_or_b32 v146, s71, 8, v205
	s_and_b64 vcc, exec, s[30:31]
	v_ashrrev_i32_e32 v147, 31, v146
	v_or_b32_e32 v142, 16, v144
	v_or_b32_e32 v140, 32, v144
	v_or_b32_e32 v138, 48, v144
	v_add_u32_e32 v136, 0x80, v144
	v_add_u32_e32 v134, 0x90, v144
	v_add_u32_e32 v132, 0xa0, v144
	v_add_u32_e32 v2, 0xb0, v144
	s_cbranch_vccz .LBB0_910
	v_mov_b64_e32 v[150:151], s[92:93]
	v_mad_i64_i32 v[148:149], s[2:3], v144, s91, v[150:151]
	v_lshl_add_u64 v[158:159], v[148:149], 0, s[76:77]
	v_lshlrev_b64 v[148:149], 1, v[146:147]
	v_lshl_add_u64 v[152:153], v[158:159], 0, v[148:149]
	v_mov_b32_e32 v170, v152
	v_mov_b32_e32 v171, v153
	s_mov_b32 s74, 0x0
	s_mov_b32 s75, 0
	v_lshl_add_u64 v[208:209], v[170:171], 0, s[74:75]
	global_load_dwordx4 v[208:211], v[208:209], off
	s_mov_b32 s74, 0x100
	s_mov_b32 s75, 0
	v_lshl_add_u64 v[212:213], v[170:171], 0, s[74:75]
	global_load_dwordx4 v[212:215], v[212:213], off
	s_mov_b32 s74, 0x6a000
	s_mov_b32 s75, 0
	v_lshl_add_u64 v[216:217], v[170:171], 0, s[74:75]
	global_load_dwordx4 v[216:219], v[216:217], off
	s_mov_b32 s74, 0x6a100
	s_mov_b32 s75, 0
	v_lshl_add_u64 v[220:221], v[170:171], 0, s[74:75]
	global_load_dwordx4 v[220:223], v[220:221], off
	s_mov_b32 s74, 0xd4000
	s_mov_b32 s75, 0
	v_lshl_add_u64 v[224:225], v[170:171], 0, s[74:75]
	global_load_dwordx4 v[224:227], v[224:225], off
	s_mov_b32 s74, 0xd4100
	s_mov_b32 s75, 0
	v_lshl_add_u64 v[228:229], v[170:171], 0, s[74:75]
	global_load_dwordx4 v[228:231], v[228:229], off
	s_mov_b32 s74, 0x13e000
	s_mov_b32 s75, 0
	v_lshl_add_u64 v[232:233], v[170:171], 0, s[74:75]
	global_load_dwordx4 v[232:235], v[232:233], off
	s_mov_b32 s74, 0x13e100
	s_mov_b32 s75, 0
	v_lshl_add_u64 v[236:237], v[170:171], 0, s[74:75]
	global_load_dwordx4 v[236:239], v[236:237], off
	s_mov_b32 s74, 0x350000
	s_mov_b32 s75, 0
	v_lshl_add_u64 v[166:167], v[170:171], 0, s[74:75]
	global_load_dwordx4 v[166:169], v[166:167], off
	s_mov_b32 s74, 0x350100
	s_mov_b32 s75, 0
	v_lshl_add_u64 v[246:247], v[170:171], 0, s[74:75]
	global_load_dwordx4 v[246:249], v[246:247], off
	s_mov_b32 s74, 0x3ba000
	s_mov_b32 s75, 0
	v_lshl_add_u64 v[250:251], v[170:171], 0, s[74:75]
	global_load_dwordx4 v[250:253], v[250:251], off
	v_ashrrev_i32_e32 v145, 31, v144
	v_readlane_b32 s4, v244, 47
	v_lshlrev_b64 v[156:157], 12, v[144:145]
	v_readlane_b32 s8, v244, 51
	v_readlane_b32 s9, v244, 52
	v_ashrrev_i32_e32 v143, 31, v142
	v_lshlrev_b64 v[162:163], 12, v[142:143]
	v_lshl_add_u64 v[156:157], s[8:9], 0, v[156:157]
	v_lshl_add_u64 v[160:161], v[156:157], 0, v[148:149]
	v_ashrrev_i32_e32 v141, 31, v140
	v_ashrrev_i32_e32 v139, 31, v138
	v_ashrrev_i32_e32 v137, 31, v136
	v_ashrrev_i32_e32 v135, 31, v134
	v_ashrrev_i32_e32 v133, 31, v132
	v_readlane_b32 s5, v244, 48
	v_readlane_b32 s6, v244, 49
	v_readlane_b32 s7, v244, 50
	v_readlane_b32 s10, v244, 53
	v_readlane_b32 s11, v244, 54
	s_waitcnt vmcnt(10)
; __device__ __forceinline__ float bflo(unsigned w) { return __uint_as_float(w << 16); }
; __device__ __forceinline__ float bfhi(unsigned w) { return __uint_as_float(w & 0xffff0000u); }
; __device__ __forceinline__ unsigned pk2(float lo, float hi) { unsigned r; asm("v_cvt_pk_bf16_f32 %0, %1, %2" : "=v"(r) : "v"(lo), "v"(hi)); return r; }
;     __device__ __forceinline__ void operator()(const f32x4 (&acc)[2][2][4][2], const Unit& u, int wr, int wc, int fr, int fq) const {
;     ...
; #pragma unroll
;                 for (int bj = 0; bj < 2; ++bj) { const int col = col0 + bj * HALF;
;                     const u32x4 gp = *(const u32x4*)(proj + (size_t)row * NPROJ + C_GP + col);
;                     const f32x4 v0 = acc[ai][bj][m][0], v1 = acc[ai][bj][m][1];
;                     u32x4 w; w.x = pk2(v0[0] * bflo(gp.x), v0[1] * bfhi(gp.x)); w.y = pk2(v0[2] * bflo(gp.y), v0[3] * bfhi(gp.y));
;                     w.z = pk2(v1[0] * bflo(gp.z), v1[1] * bfhi(gp.z)); w.w = pk2(v1[2] * bflo(gp.w), v1[3] * bfhi(gp.w));
;                     *(u32x4*)(merged + (size_t)row * DM + col) = w; } }
	v_mov_b32_e32 v152, v208
	v_mov_b32_e32 v153, v209
	v_mov_b32_e32 v154, v210
	v_mov_b32_e32 v155, v211
	s_mov_b32 s74, 0x3ba100
	s_mov_b32 s75, 0
	v_lshl_add_u64 v[208:209], v[170:171], 0, s[74:75]
	global_load_dwordx4 v[208:211], v[208:209], off
	v_lshlrev_b32_e32 v0, 16, v152
	v_and_b32_e32 v3, 0xffff0000, v152
	v_mul_f32_e32 v0, v4, v0
	v_mul_f32_e32 v3, v5, v3
	v_cvt_pk_bf16_f32 v152, v0, v3
	v_lshlrev_b32_e32 v0, 16, v153
	v_and_b32_e32 v3, 0xffff0000, v153
	v_mul_f32_e32 v0, v6, v0
	v_mul_f32_e32 v3, v7, v3
	v_cvt_pk_bf16_f32 v153, v0, v3
	v_lshlrev_b32_e32 v0, 16, v154
	v_and_b32_e32 v3, 0xffff0000, v154
	v_mul_f32_e32 v0, v8, v0
	v_mul_f32_e32 v3, v9, v3
	v_cvt_pk_bf16_f32 v154, v0, v3
	v_lshlrev_b32_e32 v0, 16, v155
	v_and_b32_e32 v3, 0xffff0000, v155
	v_mul_f32_e32 v0, v10, v0
	v_mul_f32_e32 v3, v11, v3
	v_cvt_pk_bf16_f32 v155, v0, v3
	global_store_dwordx4 v[160:161], v[152:155], off
	s_nop 1
	v_or_b32_e32 v152, 0x80, v146
	v_ashrrev_i32_e32 v153, 31, v152
	v_lshlrev_b64 v[152:153], 1, v[152:153]
	v_lshl_add_u64 v[154:155], v[158:159], 0, v[152:153]
	s_waitcnt vmcnt(11)
	v_mov_b32_e32 v154, v212
	v_mov_b32_e32 v155, v213
	v_mov_b32_e32 v156, v214
	v_mov_b32_e32 v157, v215
	s_mov_b32 s74, 0x424000
	s_mov_b32 s75, 0
	v_lshl_add_u64 v[212:213], v[170:171], 0, s[74:75]
	global_load_dwordx4 v[212:215], v[212:213], off
	v_lshlrev_b32_e32 v0, 16, v154
	v_and_b32_e32 v3, 0xffff0000, v154
	v_mul_f32_e32 v0, v36, v0
	v_mul_f32_e32 v3, v37, v3
	v_cvt_pk_bf16_f32 v154, v0, v3
	v_lshlrev_b32_e32 v0, 16, v155
	v_and_b32_e32 v3, 0xffff0000, v155
	v_mul_f32_e32 v0, v38, v0
	v_mul_f32_e32 v3, v39, v3
	v_cvt_pk_bf16_f32 v155, v0, v3
	v_lshlrev_b32_e32 v0, 16, v156
	v_and_b32_e32 v3, 0xffff0000, v156
	v_mul_f32_e32 v0, v40, v0
	v_mul_f32_e32 v3, v41, v3
	v_cvt_pk_bf16_f32 v156, v0, v3
	v_lshlrev_b32_e32 v0, 16, v157
	v_and_b32_e32 v3, 0xffff0000, v157
	v_mul_f32_e32 v0, v42, v0
	v_mul_f32_e32 v3, v43, v3
	v_cvt_pk_bf16_f32 v157, v0, v3
	global_store_dwordx4 v[160:161], v[154:157], off offset:256
	s_nop 1
	v_mad_i64_i32 v[154:155], s[2:3], v142, s91, v[150:151]
	v_lshl_add_u64 v[164:165], v[154:155], 0, s[76:77]
	v_lshl_add_u64 v[154:155], v[164:165], 0, v[148:149]
	s_waitcnt vmcnt(12)
	v_mov_b32_e32 v154, v216
	v_mov_b32_e32 v155, v217
	v_mov_b32_e32 v156, v218
	v_mov_b32_e32 v157, v219
	s_mov_b32 s74, 0x424100
	s_mov_b32 s75, 0
	v_lshl_add_u64 v[216:217], v[170:171], 0, s[74:75]
	global_load_dwordx4 v[216:219], v[216:217], off
	v_lshlrev_b32_e32 v0, 16, v154
	v_and_b32_e32 v3, 0xffff0000, v154
	v_mul_f32_e32 v0, v12, v0
	v_mul_f32_e32 v3, v13, v3
	v_cvt_pk_bf16_f32 v158, v0, v3
	v_lshlrev_b32_e32 v0, 16, v155
	v_and_b32_e32 v3, 0xffff0000, v155
	v_mul_f32_e32 v0, v14, v0
	v_mul_f32_e32 v3, v15, v3
	v_cvt_pk_bf16_f32 v159, v0, v3
	v_lshlrev_b32_e32 v0, 16, v156
	v_and_b32_e32 v3, 0xffff0000, v156
	v_mul_f32_e32 v0, v16, v0
	v_mul_f32_e32 v3, v17, v3
	v_lshl_add_u64 v[154:155], s[8:9], 0, v[162:163]
	v_cvt_pk_bf16_f32 v160, v0, v3
	v_lshlrev_b32_e32 v0, 16, v157
	v_and_b32_e32 v3, 0xffff0000, v157
	v_lshl_add_u64 v[154:155], v[154:155], 0, v[148:149]
	v_lshl_add_u64 v[156:157], v[164:165], 0, v[152:153]
	v_mul_f32_e32 v0, v18, v0
	v_mul_f32_e32 v3, v19, v3
	v_cvt_pk_bf16_f32 v161, v0, v3
	global_store_dwordx4 v[154:155], v[158:161], off
	v_lshlrev_b64 v[162:163], 12, v[140:141]
	s_waitcnt vmcnt(13)
	v_mov_b32_e32 v156, v220
	v_mov_b32_e32 v157, v221
	v_mov_b32_e32 v158, v222
	v_mov_b32_e32 v159, v223
	s_mov_b32 s74, 0x48e000
	s_mov_b32 s75, 0
	v_lshl_add_u64 v[220:221], v[170:171], 0, s[74:75]
	global_load_dwordx4 v[220:223], v[220:221], off
	v_lshlrev_b32_e32 v0, 16, v156
	v_and_b32_e32 v3, 0xffff0000, v156
	v_mul_f32_e32 v0, v44, v0
	v_mul_f32_e32 v3, v45, v3
	v_cvt_pk_bf16_f32 v156, v0, v3
	v_lshlrev_b32_e32 v0, 16, v157
	v_and_b32_e32 v3, 0xffff0000, v157
	v_mul_f32_e32 v0, v46, v0
	v_mul_f32_e32 v3, v47, v3
	v_cvt_pk_bf16_f32 v157, v0, v3
	v_lshlrev_b32_e32 v0, 16, v158
	v_and_b32_e32 v3, 0xffff0000, v158
	v_mul_f32_e32 v0, v48, v0
	v_mul_f32_e32 v3, v49, v3
	v_cvt_pk_bf16_f32 v158, v0, v3
	v_lshlrev_b32_e32 v0, 16, v159
	v_and_b32_e32 v3, 0xffff0000, v159
	v_mul_f32_e32 v0, v50, v0
	v_mul_f32_e32 v3, v51, v3
	v_cvt_pk_bf16_f32 v159, v0, v3
	global_store_dwordx4 v[154:155], v[156:159], off offset:256
	v_mad_i64_i32 v[154:155], s[2:3], v140, s91, v[150:151]
	v_lshl_add_u64 v[164:165], v[154:155], 0, s[76:77]
	v_lshl_add_u64 v[154:155], v[164:165], 0, v[148:149]
	s_waitcnt vmcnt(14)
	v_mov_b32_e32 v154, v224
	v_mov_b32_e32 v155, v225
	v_mov_b32_e32 v156, v226
	v_mov_b32_e32 v157, v227
	s_mov_b32 s74, 0x48e100
	s_mov_b32 s75, 0
	v_lshl_add_u64 v[224:225], v[170:171], 0, s[74:75]
	global_load_dwordx4 v[224:227], v[224:225], off
	v_lshlrev_b32_e32 v0, 16, v154
	v_and_b32_e32 v3, 0xffff0000, v154
	v_mul_f32_e32 v0, v20, v0
	v_mul_f32_e32 v3, v21, v3
	v_cvt_pk_bf16_f32 v158, v0, v3
	v_lshlrev_b32_e32 v0, 16, v155
	v_and_b32_e32 v3, 0xffff0000, v155
	v_mul_f32_e32 v0, v22, v0
	v_mul_f32_e32 v3, v23, v3
	v_cvt_pk_bf16_f32 v159, v0, v3
	v_lshlrev_b32_e32 v0, 16, v156
	v_and_b32_e32 v3, 0xffff0000, v156
	v_mul_f32_e32 v0, v24, v0
	v_mul_f32_e32 v3, v25, v3
	v_lshl_add_u64 v[154:155], s[8:9], 0, v[162:163]
	v_cvt_pk_bf16_f32 v160, v0, v3
	v_lshlrev_b32_e32 v0, 16, v157
	v_and_b32_e32 v3, 0xffff0000, v157
	v_lshl_add_u64 v[154:155], v[154:155], 0, v[148:149]
	v_lshl_add_u64 v[156:157], v[164:165], 0, v[152:153]
	v_mul_f32_e32 v0, v26, v0
	v_mul_f32_e32 v3, v27, v3
	v_cvt_pk_bf16_f32 v161, v0, v3
	global_store_dwordx4 v[154:155], v[158:161], off
	v_lshlrev_b64 v[162:163], 12, v[138:139]
	s_waitcnt vmcnt(15)
; __device__ __forceinline__ float bflo(unsigned w) { return __uint_as_float(w << 16); }
; __device__ __forceinline__ float bfhi(unsigned w) { return __uint_as_float(w & 0xffff0000u); }
; __device__ __forceinline__ unsigned pk2(float lo, float hi) { unsigned r; asm("v_cvt_pk_bf16_f32 %0, %1, %2" : "=v"(r) : "v"(lo), "v"(hi)); return r; }
;     __device__ __forceinline__ void operator()(const f32x4 (&acc)[2][2][4][2], const Unit& u, int wr, int wc, int fr, int fq) const {
;     ...
; #pragma unroll
;                 for (int bj = 0; bj < 2; ++bj) { const int col = col0 + bj * HALF;
;                     const u32x4 gp = *(const u32x4*)(proj + (size_t)row * NPROJ + C_GP + col);
;                     const f32x4 v0 = acc[ai][bj][m][0], v1 = acc[ai][bj][m][1];
;                     u32x4 w; w.x = pk2(v0[0] * bflo(gp.x), v0[1] * bfhi(gp.x)); w.y = pk2(v0[2] * bflo(gp.y), v0[3] * bfhi(gp.y));
;                     w.z = pk2(v1[0] * bflo(gp.z), v1[1] * bfhi(gp.z)); w.w = pk2(v1[2] * bflo(gp.w), v1[3] * bfhi(gp.w));
;                     *(u32x4*)(merged + (size_t)row * DM + col) = w; } }
	v_mov_b32_e32 v156, v228
	v_mov_b32_e32 v157, v229
	v_mov_b32_e32 v158, v230
	v_mov_b32_e32 v159, v231
	v_lshlrev_b32_e32 v0, 16, v156
	v_and_b32_e32 v3, 0xffff0000, v156
	v_mul_f32_e32 v0, v52, v0
	v_mul_f32_e32 v3, v53, v3
	v_cvt_pk_bf16_f32 v156, v0, v3
	v_lshlrev_b32_e32 v0, 16, v157
	v_and_b32_e32 v3, 0xffff0000, v157
	v_mul_f32_e32 v0, v54, v0
	v_mul_f32_e32 v3, v55, v3
	v_cvt_pk_bf16_f32 v157, v0, v3
	v_lshlrev_b32_e32 v0, 16, v158
	v_and_b32_e32 v3, 0xffff0000, v158
	v_mul_f32_e32 v0, v56, v0
	v_mul_f32_e32 v3, v57, v3
	v_cvt_pk_bf16_f32 v158, v0, v3
	v_lshlrev_b32_e32 v0, 16, v159
	v_and_b32_e32 v3, 0xffff0000, v159
	v_mul_f32_e32 v0, v58, v0
	v_mul_f32_e32 v3, v59, v3
	v_cvt_pk_bf16_f32 v159, v0, v3
	global_store_dwordx4 v[154:155], v[156:159], off offset:256
	v_mad_i64_i32 v[154:155], s[2:3], v138, s91, v[150:151]
	v_lshl_add_u64 v[164:165], v[154:155], 0, s[76:77]
	v_lshl_add_u64 v[154:155], v[164:165], 0, v[148:149]
	s_waitcnt vmcnt(15)
	v_mov_b32_e32 v154, v232
	v_mov_b32_e32 v155, v233
	v_mov_b32_e32 v156, v234
	v_mov_b32_e32 v157, v235
	v_lshlrev_b32_e32 v0, 16, v154
	v_and_b32_e32 v3, 0xffff0000, v154
	v_mul_f32_e32 v0, v28, v0
	v_mul_f32_e32 v3, v29, v3
	v_cvt_pk_bf16_f32 v158, v0, v3
	v_lshlrev_b32_e32 v0, 16, v155
	v_and_b32_e32 v3, 0xffff0000, v155
	v_mul_f32_e32 v0, v30, v0
	v_mul_f32_e32 v3, v31, v3
	v_cvt_pk_bf16_f32 v159, v0, v3
	v_lshlrev_b32_e32 v0, 16, v156
	v_and_b32_e32 v3, 0xffff0000, v156
	v_mul_f32_e32 v0, v32, v0
	v_mul_f32_e32 v3, v33, v3
	v_lshl_add_u64 v[154:155], s[8:9], 0, v[162:163]
	v_cvt_pk_bf16_f32 v160, v0, v3
	v_lshlrev_b32_e32 v0, 16, v157
	v_and_b32_e32 v3, 0xffff0000, v157
	v_lshl_add_u64 v[154:155], v[154:155], 0, v[148:149]
	v_lshl_add_u64 v[156:157], v[164:165], 0, v[152:153]
	v_mul_f32_e32 v0, v34, v0
	v_mul_f32_e32 v3, v35, v3
	v_cvt_pk_bf16_f32 v161, v0, v3
	global_store_dwordx4 v[154:155], v[158:161], off
	v_lshlrev_b64 v[162:163], 12, v[136:137]
	s_waitcnt vmcnt(15)
	v_mov_b32_e32 v156, v236
	v_mov_b32_e32 v157, v237
	v_mov_b32_e32 v158, v238
	v_mov_b32_e32 v159, v239
	v_lshlrev_b32_e32 v0, 16, v156
	v_and_b32_e32 v3, 0xffff0000, v156
	v_mul_f32_e32 v0, v60, v0
	v_mul_f32_e32 v3, v61, v3
	v_cvt_pk_bf16_f32 v156, v0, v3
	v_lshlrev_b32_e32 v0, 16, v157
	v_and_b32_e32 v3, 0xffff0000, v157
	v_mul_f32_e32 v0, v62, v0
	v_mul_f32_e32 v3, v63, v3
	v_cvt_pk_bf16_f32 v157, v0, v3
	v_lshlrev_b32_e32 v0, 16, v158
	v_and_b32_e32 v3, 0xffff0000, v158
	v_mul_f32_e32 v0, v64, v0
	v_mul_f32_e32 v3, v65, v3
	v_cvt_pk_bf16_f32 v158, v0, v3
	v_lshlrev_b32_e32 v0, 16, v159
	v_and_b32_e32 v3, 0xffff0000, v159
	v_mul_f32_e32 v0, v66, v0
	v_mul_f32_e32 v3, v67, v3
	v_cvt_pk_bf16_f32 v159, v0, v3
	global_store_dwordx4 v[154:155], v[156:159], off offset:256
	v_mad_i64_i32 v[154:155], s[2:3], v136, s91, v[150:151]
	v_lshl_add_u64 v[164:165], v[154:155], 0, s[76:77]
	v_lshl_add_u64 v[154:155], v[164:165], 0, v[148:149]
	s_waitcnt vmcnt(15)
	v_mov_b32_e32 v154, v166
	v_mov_b32_e32 v155, v167
	v_mov_b32_e32 v156, v168
	v_mov_b32_e32 v157, v169
	v_lshlrev_b32_e32 v0, 16, v154
	v_and_b32_e32 v3, 0xffff0000, v154
	v_mul_f32_e32 v0, v68, v0
	v_mul_f32_e32 v3, v69, v3
	v_cvt_pk_bf16_f32 v158, v0, v3
	v_lshlrev_b32_e32 v0, 16, v155
	v_and_b32_e32 v3, 0xffff0000, v155
	v_mul_f32_e32 v0, v70, v0
	v_mul_f32_e32 v3, v71, v3
	v_cvt_pk_bf16_f32 v159, v0, v3
	v_lshlrev_b32_e32 v0, 16, v156
	v_and_b32_e32 v3, 0xffff0000, v156
	v_mul_f32_e32 v0, v72, v0
	v_mul_f32_e32 v3, v73, v3
	v_lshl_add_u64 v[154:155], s[8:9], 0, v[162:163]
	v_cvt_pk_bf16_f32 v160, v0, v3
	v_lshlrev_b32_e32 v0, 16, v157
	v_and_b32_e32 v3, 0xffff0000, v157
	v_lshl_add_u64 v[154:155], v[154:155], 0, v[148:149]
	v_lshl_add_u64 v[156:157], v[164:165], 0, v[152:153]
	v_mul_f32_e32 v0, v74, v0
	v_mul_f32_e32 v3, v75, v3
	v_cvt_pk_bf16_f32 v161, v0, v3
	global_store_dwordx4 v[154:155], v[158:161], off
	v_lshlrev_b64 v[162:163], 12, v[134:135]
	s_waitcnt vmcnt(15)
	v_mov_b32_e32 v156, v246
	v_mov_b32_e32 v157, v247
	v_mov_b32_e32 v158, v248
	v_mov_b32_e32 v159, v249
	v_lshlrev_b32_e32 v0, 16, v156
	v_and_b32_e32 v3, 0xffff0000, v156
	v_mul_f32_e32 v0, v100, v0
	v_mul_f32_e32 v3, v101, v3
	v_cvt_pk_bf16_f32 v156, v0, v3
	v_lshlrev_b32_e32 v0, 16, v157
	v_and_b32_e32 v3, 0xffff0000, v157
	v_mul_f32_e32 v0, v102, v0
	v_mul_f32_e32 v3, v103, v3
	v_cvt_pk_bf16_f32 v157, v0, v3
	v_lshlrev_b32_e32 v0, 16, v158
	v_and_b32_e32 v3, 0xffff0000, v158
	v_mul_f32_e32 v0, v104, v0
	v_mul_f32_e32 v3, v105, v3
	v_cvt_pk_bf16_f32 v158, v0, v3
	v_lshlrev_b32_e32 v0, 16, v159
	v_and_b32_e32 v3, 0xffff0000, v159
	v_mul_f32_e32 v0, v106, v0
	v_mul_f32_e32 v3, v107, v3
	v_cvt_pk_bf16_f32 v159, v0, v3
	global_store_dwordx4 v[154:155], v[156:159], off offset:256
	v_mad_i64_i32 v[154:155], s[2:3], v134, s91, v[150:151]
	v_lshl_add_u64 v[164:165], v[154:155], 0, s[76:77]
	v_lshl_add_u64 v[154:155], v[164:165], 0, v[148:149]
	s_waitcnt vmcnt(15)
; __device__ __forceinline__ float bflo(unsigned w) { return __uint_as_float(w << 16); }
; __device__ __forceinline__ float bfhi(unsigned w) { return __uint_as_float(w & 0xffff0000u); }
; __device__ __forceinline__ unsigned pk2(float lo, float hi) { unsigned r; asm("v_cvt_pk_bf16_f32 %0, %1, %2" : "=v"(r) : "v"(lo), "v"(hi)); return r; }
;     __device__ __forceinline__ void operator()(const f32x4 (&acc)[2][2][4][2], const Unit& u, int wr, int wc, int fr, int fq) const {
;     ...
; #pragma unroll
;                 for (int bj = 0; bj < 2; ++bj) { const int col = col0 + bj * HALF;
;                     const u32x4 gp = *(const u32x4*)(proj + (size_t)row * NPROJ + C_GP + col);
;                     const f32x4 v0 = acc[ai][bj][m][0], v1 = acc[ai][bj][m][1];
;                     u32x4 w; w.x = pk2(v0[0] * bflo(gp.x), v0[1] * bfhi(gp.x)); w.y = pk2(v0[2] * bflo(gp.y), v0[3] * bfhi(gp.y));
;                     w.z = pk2(v1[0] * bflo(gp.z), v1[1] * bfhi(gp.z)); w.w = pk2(v1[2] * bflo(gp.w), v1[3] * bfhi(gp.w));
;                     *(u32x4*)(merged + (size_t)row * DM + col) = w; } }
	v_mov_b32_e32 v154, v250
	v_mov_b32_e32 v155, v251
	v_mov_b32_e32 v156, v252
	v_mov_b32_e32 v157, v253
	v_lshlrev_b32_e32 v0, 16, v154
	v_and_b32_e32 v3, 0xffff0000, v154
	v_mul_f32_e32 v0, v76, v0
	v_mul_f32_e32 v3, v77, v3
	v_cvt_pk_bf16_f32 v158, v0, v3
	v_lshlrev_b32_e32 v0, 16, v155
	v_and_b32_e32 v3, 0xffff0000, v155
	v_mul_f32_e32 v0, v78, v0
	v_mul_f32_e32 v3, v79, v3
	v_cvt_pk_bf16_f32 v159, v0, v3
	v_lshlrev_b32_e32 v0, 16, v156
	v_and_b32_e32 v3, 0xffff0000, v156
	v_mul_f32_e32 v0, v80, v0
	v_mul_f32_e32 v3, v81, v3
	v_lshl_add_u64 v[154:155], s[8:9], 0, v[162:163]
	v_cvt_pk_bf16_f32 v160, v0, v3
	v_lshlrev_b32_e32 v0, 16, v157
	v_and_b32_e32 v3, 0xffff0000, v157
	v_lshl_add_u64 v[154:155], v[154:155], 0, v[148:149]
	v_lshl_add_u64 v[156:157], v[164:165], 0, v[152:153]
	v_mul_f32_e32 v0, v82, v0
	v_mul_f32_e32 v3, v83, v3
	v_cvt_pk_bf16_f32 v161, v0, v3
	global_store_dwordx4 v[154:155], v[158:161], off
	v_lshlrev_b64 v[162:163], 12, v[132:133]
	s_waitcnt vmcnt(15)
	v_mov_b32_e32 v156, v208
	v_mov_b32_e32 v157, v209
	v_mov_b32_e32 v158, v210
	v_mov_b32_e32 v159, v211
	v_lshlrev_b32_e32 v0, 16, v156
	v_and_b32_e32 v3, 0xffff0000, v156
	v_mul_f32_e32 v0, v108, v0
	v_mul_f32_e32 v3, v109, v3
	v_cvt_pk_bf16_f32 v156, v0, v3
	v_lshlrev_b32_e32 v0, 16, v157
	v_and_b32_e32 v3, 0xffff0000, v157
	v_mul_f32_e32 v0, v110, v0
	v_mul_f32_e32 v3, v111, v3
	v_cvt_pk_bf16_f32 v157, v0, v3
	v_lshlrev_b32_e32 v0, 16, v158
	v_and_b32_e32 v3, 0xffff0000, v158
	v_mul_f32_e32 v0, v112, v0
	v_mul_f32_e32 v3, v113, v3
	v_cvt_pk_bf16_f32 v158, v0, v3
	v_lshlrev_b32_e32 v0, 16, v159
	v_and_b32_e32 v3, 0xffff0000, v159
	v_mul_f32_e32 v0, v114, v0
	v_mul_f32_e32 v3, v115, v3
	v_cvt_pk_bf16_f32 v159, v0, v3
	global_store_dwordx4 v[154:155], v[156:159], off offset:256
	v_mad_i64_i32 v[154:155], s[2:3], v132, s91, v[150:151]
	v_lshl_add_u64 v[164:165], v[154:155], 0, s[76:77]
	v_lshl_add_u64 v[154:155], v[164:165], 0, v[148:149]
	v_mad_i64_i32 v[150:151], s[2:3], v2, s91, v[150:151]
	v_lshl_add_u64 v[150:151], v[150:151], 0, s[76:77]
	s_waitcnt vmcnt(14)
	v_mov_b32_e32 v154, v212
	v_mov_b32_e32 v155, v213
	v_mov_b32_e32 v156, v214
	v_mov_b32_e32 v157, v215
	v_lshlrev_b32_e32 v0, 16, v154
	v_and_b32_e32 v3, 0xffff0000, v154
	v_mul_f32_e32 v0, v84, v0
	v_mul_f32_e32 v3, v85, v3
	v_cvt_pk_bf16_f32 v158, v0, v3
	v_lshlrev_b32_e32 v0, 16, v155
	v_and_b32_e32 v3, 0xffff0000, v155
	v_mul_f32_e32 v0, v86, v0
	v_mul_f32_e32 v3, v87, v3
	v_cvt_pk_bf16_f32 v159, v0, v3
	v_lshlrev_b32_e32 v0, 16, v156
	v_and_b32_e32 v3, 0xffff0000, v156
	v_mul_f32_e32 v0, v88, v0
	v_mul_f32_e32 v3, v89, v3
	v_lshl_add_u64 v[154:155], s[8:9], 0, v[162:163]
	v_cvt_pk_bf16_f32 v160, v0, v3
	v_lshlrev_b32_e32 v0, 16, v157
	v_and_b32_e32 v3, 0xffff0000, v157
	v_lshl_add_u64 v[154:155], v[154:155], 0, v[148:149]
	v_lshl_add_u64 v[156:157], v[164:165], 0, v[152:153]
	v_mul_f32_e32 v0, v90, v0
	v_mul_f32_e32 v3, v91, v3
	v_cvt_pk_bf16_f32 v161, v0, v3
	global_store_dwordx4 v[154:155], v[158:161], off
	s_waitcnt vmcnt(13)
	v_mov_b32_e32 v156, v216
	v_mov_b32_e32 v157, v217
	v_mov_b32_e32 v158, v218
	v_mov_b32_e32 v159, v219
	v_lshlrev_b32_e32 v0, 16, v156
	v_and_b32_e32 v3, 0xffff0000, v156
	v_mul_f32_e32 v0, v116, v0
	v_mul_f32_e32 v3, v117, v3
	v_cvt_pk_bf16_f32 v156, v0, v3
	v_lshlrev_b32_e32 v0, 16, v157
	v_and_b32_e32 v3, 0xffff0000, v157
	v_mul_f32_e32 v0, v118, v0
	v_mul_f32_e32 v3, v119, v3
	v_cvt_pk_bf16_f32 v157, v0, v3
	v_lshlrev_b32_e32 v0, 16, v158
	v_and_b32_e32 v3, 0xffff0000, v158
	v_mul_f32_e32 v0, v120, v0
	v_mul_f32_e32 v3, v121, v3
	v_cvt_pk_bf16_f32 v158, v0, v3
	v_lshlrev_b32_e32 v0, 16, v159
	v_and_b32_e32 v3, 0xffff0000, v159
	v_mul_f32_e32 v0, v122, v0
	v_mul_f32_e32 v3, v123, v3
	v_cvt_pk_bf16_f32 v159, v0, v3
	global_store_dwordx4 v[154:155], v[156:159], off offset:256
	v_lshl_add_u64 v[154:155], v[150:151], 0, v[148:149]
	v_lshl_add_u64 v[150:151], v[150:151], 0, v[152:153]
	v_ashrrev_i32_e32 v3, 31, v2
	v_lshlrev_b64 v[158:159], 12, v[2:3]
	v_lshl_add_u64 v[158:159], s[8:9], 0, v[158:159]
	v_lshl_add_u64 v[148:149], v[158:159], 0, v[148:149]
	s_waitcnt vmcnt(10)
	v_mov_b32_e32 v154, v220
	v_mov_b32_e32 v155, v221
	v_mov_b32_e32 v156, v222
	v_mov_b32_e32 v157, v223
	v_mov_b32_e32 v150, v224
	v_mov_b32_e32 v151, v225
	v_mov_b32_e32 v152, v226
	v_mov_b32_e32 v153, v227
	v_lshlrev_b32_e32 v0, 16, v154
	v_and_b32_e32 v3, 0xffff0000, v154
	v_mul_f32_e32 v0, v92, v0
	v_mul_f32_e32 v3, v93, v3
	v_cvt_pk_bf16_f32 v154, v0, v3
	v_lshlrev_b32_e32 v0, 16, v155
	v_and_b32_e32 v3, 0xffff0000, v155
	v_mul_f32_e32 v0, v94, v0
	v_mul_f32_e32 v3, v95, v3
	v_cvt_pk_bf16_f32 v155, v0, v3
	v_lshlrev_b32_e32 v0, 16, v156
	v_and_b32_e32 v3, 0xffff0000, v156
	v_mul_f32_e32 v0, v96, v0
	v_mul_f32_e32 v3, v97, v3
	v_cvt_pk_bf16_f32 v156, v0, v3
	v_lshlrev_b32_e32 v0, 16, v157
	v_and_b32_e32 v3, 0xffff0000, v157
	v_mul_f32_e32 v0, v98, v0
	v_mul_f32_e32 v3, v99, v3
	v_cvt_pk_bf16_f32 v157, v0, v3
	v_lshlrev_b32_e32 v0, 16, v150
	v_and_b32_e32 v3, 0xffff0000, v150
	v_mul_f32_e32 v0, v124, v0
	v_mul_f32_e32 v3, v125, v3
	v_cvt_pk_bf16_f32 v150, v0, v3
	v_lshlrev_b32_e32 v0, 16, v151
	v_and_b32_e32 v3, 0xffff0000, v151
	v_mul_f32_e32 v0, v126, v0
	v_mul_f32_e32 v3, v127, v3
	v_cvt_pk_bf16_f32 v151, v0, v3
	v_lshlrev_b32_e32 v0, 16, v152
	v_and_b32_e32 v3, 0xffff0000, v152
	v_mul_f32_e32 v0, v128, v0
	v_mul_f32_e32 v3, v129, v3
	v_cvt_pk_bf16_f32 v152, v0, v3
	v_lshlrev_b32_e32 v0, 16, v153
	v_and_b32_e32 v3, 0xffff0000, v153
	global_store_dwordx4 v[148:149], v[154:157], off
	v_mul_f32_e32 v0, v130, v0
	v_mul_f32_e32 v3, v131, v3
	v_cvt_pk_bf16_f32 v153, v0, v3
	global_store_dwordx4 v[148:149], v[150:153], off offset:256
	s_cbranch_execnz .LBB0_907
